# baseline (speedup 1.0000x reference)
; template <int EPI, int NM, bool SWAP>
; DEVI void gemm_epilogue(const Params& p, f32x4 (&acc)[NM][4], const int R0, const int C0, const float* rsw, const EpiArgs& ea) {
;     ...
;   } else if constexpr (EPI == EPI_OUT) {
;     u16* abase = (u16*)(ws + OFF_ABF) + (size_t)(R0 + fr) * DM + C0 + fq * 4;
;     u32x2 rc[4];
; #pragma unroll
;     for (int n = 0; n < 4; ++n) rc[n] = *reinterpret_cast<const u32x2*>(abase + n * 16);
; #pragma unroll
;     for (int m = 0; m < NM; ++m) {
;       u32x2 rn[4];
;       if (m + 1 < NM) {
; #pragma unroll
;         for (int n = 0; n < 4; ++n) rn[n] = *reinterpret_cast<const u32x2*>(abase + (size_t)ROFF(m + 1) * DM + n * 16);
;       }
;       __builtin_amdgcn_sched_barrier(0);
;       float s = 0.f;
; #pragma unroll
;       for (int n = 0; n < 4; ++n) {
;         f32x4 h = acc[m][n];
;         h[0] += __uint_as_float(rc[n][0] << 16); h[1] += __uint_as_float(rc[n][0] & 0xffff0000u);
;         h[2] += __uint_as_float(rc[n][1] << 16); h[3] += __uint_as_float(rc[n][1] & 0xffff0000u);
;         *reinterpret_cast<u32x2*>(abase + (size_t)ROFF(m) * DM + n * 16) = u32x2{cvtpk(h[0], h[1]), cvtpk(h[2], h[3])};
;         s += h[0] * h[0] + h[1] * h[1] + h[2] * h[2] + h[3] * h[3];
;       }
;       s += __shfl_xor(s, 16); s += __shfl_xor(s, 32);
;       if (fq == 0) atomicAdd(ea.ss_next + R0 + ROFF(m) + fr, s);
;       __builtin_amdgcn_sched_barrier(0);
;       if (m + 1 < NM) {
; #pragma unroll
;         for (int n = 0; n < 4; ++n) rc[n] = rn[n];
;       }
;     }
.LBB0_379:
	s_or_b64 exec, exec, s[16:17]
	v_mov_b32_e32 v128, v222
	v_add_u32_e32 v140, s4, v144
	v_lshl_or_b32 v130, v143, 6, s92
	v_ashrrev_i32_e32 v131, 31, v130
	v_and_b32_e32 v143, 15, v128
	v_or_b32_e32 v132, v143, v140
	v_ashrrev_i32_e32 v133, 31, v132
	v_lshlrev_b64 v[132:133], 11, v[132:133]
	v_lshl_add_u64 v[132:133], s[38:39], 0, v[132:133]
	v_lshl_add_u64 v[130:131], v[130:131], 1, v[132:133]
	v_ashrrev_i32_e32 v132, 2, v128
	v_and_b32_e32 v132, -4, v132
	v_ashrrev_i32_e32 v133, 31, v132
	v_lshl_add_u64 v[130:131], v[132:133], 1, v[130:131]
	s_mov_b32 s4, 0x8000
	v_add_co_u32_e32 v132, vcc, s4, v130
	global_load_dwordx2 v[144:145], v[130:131], off
	global_load_dwordx2 v[146:147], v[130:131], off offset:32
	global_load_dwordx2 v[148:149], v[130:131], off offset:64
	global_load_dwordx2 v[150:151], v[130:131], off offset:96
	v_addc_co_u32_e32 v133, vcc, 0, v131, vcc
	global_load_dwordx2 v[138:139], v[132:133], off
	global_load_dwordx2 v[136:137], v[132:133], off offset:32
	global_load_dwordx2 v[134:135], v[132:133], off offset:64
	s_nop 0
	global_load_dwordx2 v[132:133], v[132:133], off offset:96
	s_mov_b64 s[100:101], 0x10000
	v_lshl_add_u64 v[170:171], v[130:131], 0, s[100:101]
	global_load_dwordx2 v[172:173], v[170:171], off
	global_load_dwordx2 v[174:175], v[170:171], off offset:32
	global_load_dwordx2 v[176:177], v[170:171], off offset:64
	global_load_dwordx2 v[178:179], v[170:171], off offset:96
	s_mov_b64 s[100:101], 0x18000
	v_lshl_add_u64 v[170:171], v[130:131], 0, s[100:101]
	global_load_dwordx2 v[180:181], v[170:171], off
	global_load_dwordx2 v[182:183], v[170:171], off offset:32
	global_load_dwordx2 v[184:185], v[170:171], off offset:64
	global_load_dwordx2 v[186:187], v[170:171], off offset:96
	s_mov_b64 s[100:101], 0x40000
	v_lshl_add_u64 v[170:171], v[130:131], 0, s[100:101]
	global_load_dwordx2 v[188:189], v[170:171], off
	global_load_dwordx2 v[190:191], v[170:171], off offset:32
	global_load_dwordx2 v[192:193], v[170:171], off offset:64
	global_load_dwordx2 v[194:195], v[170:171], off offset:96
	s_mov_b64 s[100:101], 0x48000
	v_lshl_add_u64 v[170:171], v[130:131], 0, s[100:101]
	global_load_dwordx2 v[196:197], v[170:171], off
	global_load_dwordx2 v[198:199], v[170:171], off offset:32
	global_load_dwordx2 v[200:201], v[170:171], off offset:64
	global_load_dwordx2 v[202:203], v[170:171], off offset:96
	s_mov_b64 s[100:101], 0x50000
	v_lshl_add_u64 v[170:171], v[130:131], 0, s[100:101]
	global_load_dwordx2 v[204:205], v[170:171], off
	global_load_dwordx2 v[206:207], v[170:171], off offset:32
	global_load_dwordx2 v[208:209], v[170:171], off offset:64
	global_load_dwordx2 v[210:211], v[170:171], off offset:96
	s_mov_b64 s[100:101], 0x58000
	v_lshl_add_u64 v[170:171], v[130:131], 0, s[100:101]
	global_load_dwordx2 v[212:213], v[170:171], off
	global_load_dwordx2 v[214:215], v[170:171], off offset:32
	global_load_dwordx2 v[216:217], v[170:171], off offset:64
	global_load_dwordx2 v[224:225], v[170:171], off offset:96
	v_cmp_gt_u32_e64 s[4:5], 16, v128
	v_ashrrev_i32_e32 v141, 31, v140
	s_waitcnt vmcnt(28)
	v_lshlrev_b32_e32 v128, 16, v144
	v_add_f32_e32 v128, v124, v128
	v_and_b32_e32 v124, 0xffff0000, v144
	v_add_f32_e32 v144, v125, v124
	v_lshlrev_b32_e32 v124, 16, v145
	v_add_f32_e32 v126, v126, v124
	v_and_b32_e32 v124, 0xffff0000, v145
	v_add_f32_e32 v127, v127, v124
	v_cvt_pk_bf16_f32 v124, v128, v144
	v_cvt_pk_bf16_f32 v125, v126, v127
	global_store_dwordx2 v[130:131], v[124:125], off
	v_mul_f32_e32 v124, v144, v144
	v_lshlrev_b32_e32 v125, 16, v146
	v_fmac_f32_e32 v124, v128, v128
	v_add_f32_e32 v125, v116, v125
	v_and_b32_e32 v116, 0xffff0000, v146
	v_fmac_f32_e32 v124, v126, v126
	v_add_f32_e32 v126, v117, v116
	v_lshlrev_b32_e32 v116, 16, v147
	v_add_f32_e32 v118, v118, v116
	v_and_b32_e32 v116, 0xffff0000, v147
	v_add_f32_e32 v119, v119, v116
	v_cvt_pk_bf16_f32 v116, v125, v126
	v_cvt_pk_bf16_f32 v117, v118, v119
	global_store_dwordx2 v[130:131], v[116:117], off offset:32
	v_mul_f32_e32 v116, v126, v126
	v_fmac_f32_e32 v116, v125, v125
	v_fmac_f32_e32 v116, v118, v118
	v_and_b32_e32 v118, 0xffff0000, v148
	v_lshlrev_b32_e32 v117, 16, v148
	v_add_f32_e32 v118, v121, v118
	v_fmac_f32_e32 v116, v119, v119
	v_add_f32_e32 v117, v120, v117
	v_lshlrev_b32_e32 v119, 16, v149
	v_mul_f32_e32 v121, v118, v118
	v_add_f32_e32 v119, v122, v119
	v_and_b32_e32 v120, 0xffff0000, v149
	v_fmac_f32_e32 v121, v117, v117
	v_fmac_f32_e32 v124, v127, v127
	v_add_f32_e32 v120, v123, v120
	v_fmac_f32_e32 v121, v119, v119
	v_add_f32_e32 v116, v124, v116
	v_fmac_f32_e32 v121, v120, v120
	v_add_f32_e32 v116, v116, v121
	v_lshlrev_b32_e32 v121, 16, v150
	v_add_f32_e32 v121, v112, v121
	v_and_b32_e32 v112, 0xffff0000, v150
	v_add_f32_e32 v123, v113, v112
	v_lshlrev_b32_e32 v112, 16, v151
	v_add_f32_e32 v124, v114, v112
	v_and_b32_e32 v112, 0xffff0000, v151
	v_add_f32_e32 v125, v115, v112
	v_mul_f32_e32 v112, v123, v123
	v_fmac_f32_e32 v112, v121, v121
	v_fmac_f32_e32 v112, v124, v124
	v_fmac_f32_e32 v112, v125, v125
	v_and_b32_e32 v113, 64, v142
	v_add_f32_e32 v114, v116, v112
	v_xor_b32_e32 v112, 16, v142
	v_add_u32_e32 v115, 64, v113
	v_cmp_lt_i32_e32 vcc, v112, v115
	v_lshlrev_b32_e32 v128, 2, v143
	s_nop 0
	v_cndmask_b32_e32 v112, v142, v112, vcc
	v_lshlrev_b32_e32 v122, 2, v112
	ds_bpermute_b32 v116, v122, v114
	v_cvt_pk_bf16_f32 v112, v117, v118
	v_cvt_pk_bf16_f32 v113, v119, v120
	global_store_dwordx2 v[130:131], v[112:113], off offset:64
	v_xor_b32_e32 v113, 32, v142
	v_cmp_lt_i32_e32 vcc, v113, v115
	v_cvt_pk_bf16_f32 v112, v121, v123
	s_waitcnt lgkmcnt(0)
	v_add_f32_e32 v114, v114, v116
	v_cndmask_b32_e32 v113, v142, v113, vcc
	v_lshlrev_b32_e32 v123, 2, v113
	ds_bpermute_b32 v115, v123, v114
	v_cvt_pk_bf16_f32 v113, v124, v125
	global_store_dwordx2 v[130:131], v[112:113], off offset:96
	v_lshl_add_u64 v[112:113], v[140:141], 2, s[10:11]
	s_and_saveexec_b64 s[92:93], s[4:5]
	s_cbranch_execz .LBB0_381
	s_waitcnt lgkmcnt(0)
	v_add_f32_e32 v116, v114, v115
	v_lshl_add_u64 v[114:115], v[112:113], 0, v[128:129]
	global_atomic_add_f32 v[114:115], v116, off
; template <int EPI, int NM, bool SWAP>
; DEVI void gemm_epilogue(const Params& p, f32x4 (&acc)[NM][4], const int R0, const int C0, const float* rsw, const EpiArgs& ea) {
;     ...
;   } else if constexpr (EPI == EPI_OUT) {
;     u16* abase = (u16*)(ws + OFF_ABF) + (size_t)(R0 + fr) * DM + C0 + fq * 4;
;     u32x2 rc[4];
; #pragma unroll
;     for (int n = 0; n < 4; ++n) rc[n] = *reinterpret_cast<const u32x2*>(abase + n * 16);
; #pragma unroll
;     for (int m = 0; m < NM; ++m) {
;       u32x2 rn[4];
;       if (m + 1 < NM) {
; #pragma unroll
;         for (int n = 0; n < 4; ++n) rn[n] = *reinterpret_cast<const u32x2*>(abase + (size_t)ROFF(m + 1) * DM + n * 16);
;       }
;       __builtin_amdgcn_sched_barrier(0);
;       float s = 0.f;
; #pragma unroll
;       for (int n = 0; n < 4; ++n) {
;         f32x4 h = acc[m][n];
;         h[0] += __uint_as_float(rc[n][0] << 16); h[1] += __uint_as_float(rc[n][0] & 0xffff0000u);
;         h[2] += __uint_as_float(rc[n][1] << 16); h[3] += __uint_as_float(rc[n][1] & 0xffff0000u);
;         *reinterpret_cast<u32x2*>(abase + (size_t)ROFF(m) * DM + n * 16) = u32x2{cvtpk(h[0], h[1]), cvtpk(h[2], h[3])};
;         s += h[0] * h[0] + h[1] * h[1] + h[2] * h[2] + h[3] * h[3];
;       }
;       s += __shfl_xor(s, 16); s += __shfl_xor(s, 32);
;       if (fq == 0) atomicAdd(ea.ss_next + R0 + ROFF(m) + fr, s);
;       __builtin_amdgcn_sched_barrier(0);
;       if (m + 1 < NM) {
; #pragma unroll
;         for (int n = 0; n < 4; ++n) rc[n] = rn[n];
;       }
;     }
.LBB0_381:
	s_or_b64 exec, exec, s[92:93]
	s_mov_b64 s[16:17], 0x8000
	v_lshl_add_u64 v[124:125], v[130:131], 0, s[16:17]
	s_mov_b64 s[16:17], 0x8020
	v_lshl_add_u64 v[126:127], v[130:131], 0, s[16:17]
	s_mov_b64 s[16:17], 0x8040
	v_lshl_add_u64 v[140:141], v[130:131], 0, s[16:17]
	s_mov_b64 s[16:17], 0x8060
	v_lshl_add_u64 v[144:145], v[130:131], 0, s[16:17]
	v_add_co_u32_e32 v114, vcc, 0x10000, v130
	s_waitcnt lgkmcnt(0)
	s_nop 0
	v_addc_co_u32_e32 v115, vcc, 0, v131, vcc
	s_nop 0
	s_waitcnt vmcnt(28)
	v_lshlrev_b32_e32 v143, 16, v138
	v_add_f32_e32 v143, v108, v143
	v_and_b32_e32 v108, 0xffff0000, v138
	v_add_f32_e32 v138, v109, v108
	v_lshlrev_b32_e32 v108, 16, v139
	v_add_f32_e32 v110, v110, v108
	v_and_b32_e32 v108, 0xffff0000, v139
	v_add_f32_e32 v111, v111, v108
	v_cvt_pk_bf16_f32 v108, v143, v138
	v_cvt_pk_bf16_f32 v109, v110, v111
	global_store_dwordx2 v[124:125], v[108:109], off
	v_lshlrev_b32_e32 v109, 16, v136
	v_add_f32_e32 v109, v100, v109
	v_and_b32_e32 v100, 0xffff0000, v136
	v_add_f32_e32 v101, v101, v100
	v_lshlrev_b32_e32 v100, 16, v137
	v_add_f32_e32 v102, v102, v100
	v_and_b32_e32 v100, 0xffff0000, v137
	v_mul_f32_e32 v108, v138, v138
	v_add_f32_e32 v103, v103, v100
	v_cvt_pk_bf16_f32 v100, v109, v101
	v_mul_f32_e32 v101, v101, v101
	v_fmac_f32_e32 v108, v143, v143
	v_fmac_f32_e32 v101, v109, v109
	v_fmac_f32_e32 v108, v110, v110
	v_fmac_f32_e32 v101, v102, v102
	v_fmac_f32_e32 v108, v111, v111
	v_fmac_f32_e32 v101, v103, v103
	v_add_f32_e32 v101, v108, v101
	v_lshlrev_b32_e32 v108, 16, v134
	v_add_f32_e32 v104, v104, v108
	v_and_b32_e32 v108, 0xffff0000, v134
	v_add_f32_e32 v105, v105, v108
	v_lshlrev_b32_e32 v108, 16, v135
	v_add_f32_e32 v106, v106, v108
	v_and_b32_e32 v108, 0xffff0000, v135
	v_add_f32_e32 v107, v107, v108
	v_mul_f32_e32 v108, v105, v105
	v_fmac_f32_e32 v108, v104, v104
	v_fmac_f32_e32 v108, v106, v106
	v_fmac_f32_e32 v108, v107, v107
	v_add_f32_e32 v101, v101, v108
	v_lshlrev_b32_e32 v108, 16, v132
	v_add_f32_e32 v108, v96, v108
	v_and_b32_e32 v96, 0xffff0000, v132
	v_add_f32_e32 v109, v97, v96
	v_lshlrev_b32_e32 v96, 16, v133
	v_add_f32_e32 v110, v98, v96
	v_and_b32_e32 v96, 0xffff0000, v133
	v_add_f32_e32 v111, v99, v96
	v_mul_f32_e32 v96, v109, v109
	v_fmac_f32_e32 v96, v108, v108
	v_fmac_f32_e32 v96, v110, v110
	v_fmac_f32_e32 v96, v111, v111
	v_add_f32_e32 v96, v101, v96
	ds_bpermute_b32 v97, v122, v96
	v_cvt_pk_bf16_f32 v101, v102, v103
	global_store_dwordx2 v[126:127], v[100:101], off
	v_cvt_pk_bf16_f32 v98, v104, v105
	v_cvt_pk_bf16_f32 v99, v106, v107
	s_waitcnt lgkmcnt(0)
	v_add_f32_e32 v96, v96, v97
	ds_bpermute_b32 v97, v123, v96
	global_store_dwordx2 v[140:141], v[98:99], off
	v_cvt_pk_bf16_f32 v98, v108, v109
	v_cvt_pk_bf16_f32 v99, v110, v111
	global_store_dwordx2 v[144:145], v[98:99], off
	s_and_saveexec_b64 s[92:93], s[4:5]
	s_cbranch_execz .LBB0_383
	s_waitcnt lgkmcnt(0)
	v_add_f32_e32 v98, v96, v97
	v_lshl_add_u64 v[96:97], v[112:113], 0, v[128:129]
	global_atomic_add_f32 v[96:97], v98, off offset:64
.LBB0_383:
	s_or_b64 exec, exec, s[92:93]
	s_mov_b64 s[16:17], 0x10000
	v_lshl_add_u64 v[104:105], v[130:131], 0, s[16:17]
	s_mov_b64 s[16:17], 0x10020
	v_lshl_add_u64 v[106:107], v[130:131], 0, s[16:17]
	s_mov_b64 s[16:17], 0x10040
	v_lshl_add_u64 v[108:109], v[130:131], 0, s[16:17]
	s_mov_b64 s[16:17], 0x10060
	v_lshl_add_u64 v[110:111], v[130:131], 0, s[16:17]
	v_add_co_u32_e32 v96, vcc, 0x18000, v130
	s_waitcnt lgkmcnt(0)
	s_nop 0
	v_addc_co_u32_e32 v97, vcc, 0, v131, vcc
	s_nop 0
	s_waitcnt vmcnt(28)
	v_lshlrev_b32_e32 v124, 16, v172
	v_add_f32_e32 v124, v92, v124
	v_and_b32_e32 v92, 0xffff0000, v172
	v_add_f32_e32 v120, v93, v92
	v_lshlrev_b32_e32 v92, 16, v173
	v_add_f32_e32 v94, v94, v92
	v_and_b32_e32 v92, 0xffff0000, v173
	v_add_f32_e32 v95, v95, v92
	v_cvt_pk_bf16_f32 v92, v124, v120
	v_cvt_pk_bf16_f32 v93, v94, v95
	global_store_dwordx2 v[104:105], v[92:93], off
	v_lshlrev_b32_e32 v93, 16, v174
	v_add_f32_e32 v93, v84, v93
	v_and_b32_e32 v84, 0xffff0000, v174
	v_add_f32_e32 v85, v85, v84
	v_lshlrev_b32_e32 v84, 16, v175
	v_add_f32_e32 v86, v86, v84
	v_and_b32_e32 v84, 0xffff0000, v175
	v_mul_f32_e32 v92, v120, v120
	v_add_f32_e32 v87, v87, v84
	v_cvt_pk_bf16_f32 v84, v93, v85
	v_mul_f32_e32 v85, v85, v85
	v_fmac_f32_e32 v92, v124, v124
	v_fmac_f32_e32 v85, v93, v93
	v_fmac_f32_e32 v92, v94, v94
	v_fmac_f32_e32 v85, v86, v86
	v_fmac_f32_e32 v92, v95, v95
	v_fmac_f32_e32 v85, v87, v87
	v_add_f32_e32 v85, v92, v85
	v_lshlrev_b32_e32 v92, 16, v176
	v_add_f32_e32 v88, v88, v92
	v_and_b32_e32 v92, 0xffff0000, v176
	v_add_f32_e32 v89, v89, v92
	v_lshlrev_b32_e32 v92, 16, v177
	v_add_f32_e32 v90, v90, v92
	v_and_b32_e32 v92, 0xffff0000, v177
	v_add_f32_e32 v91, v91, v92
	v_mul_f32_e32 v92, v89, v89
	v_fmac_f32_e32 v92, v88, v88
	v_fmac_f32_e32 v92, v90, v90
	v_fmac_f32_e32 v92, v91, v91
	v_add_f32_e32 v85, v85, v92
	v_lshlrev_b32_e32 v92, 16, v178
	v_add_f32_e32 v92, v80, v92
	v_and_b32_e32 v80, 0xffff0000, v178
	v_add_f32_e32 v93, v81, v80
	v_lshlrev_b32_e32 v80, 16, v179
	v_add_f32_e32 v94, v82, v80
	v_and_b32_e32 v80, 0xffff0000, v179
	v_add_f32_e32 v95, v83, v80
	v_mul_f32_e32 v80, v93, v93
	v_fmac_f32_e32 v80, v92, v92
	v_fmac_f32_e32 v80, v94, v94
	v_fmac_f32_e32 v80, v95, v95
	v_add_f32_e32 v80, v85, v80
	ds_bpermute_b32 v81, v122, v80
	v_cvt_pk_bf16_f32 v85, v86, v87
	global_store_dwordx2 v[106:107], v[84:85], off
	v_cvt_pk_bf16_f32 v82, v88, v89
	v_cvt_pk_bf16_f32 v83, v90, v91
	s_waitcnt lgkmcnt(0)
	v_add_f32_e32 v80, v80, v81
	ds_bpermute_b32 v81, v123, v80
	global_store_dwordx2 v[108:109], v[82:83], off
	v_cvt_pk_bf16_f32 v82, v92, v93
	v_cvt_pk_bf16_f32 v83, v94, v95
	global_store_dwordx2 v[110:111], v[82:83], off
	s_and_saveexec_b64 s[92:93], s[4:5]
	s_cbranch_execz .LBB0_385
	s_waitcnt lgkmcnt(0)
	v_add_f32_e32 v82, v80, v81
	v_lshl_add_u64 v[80:81], v[112:113], 0, v[128:129]
	global_atomic_add_f32 v[80:81], v82, off offset:128
; template <int EPI, int NM, bool SWAP>
; DEVI void gemm_epilogue(const Params& p, f32x4 (&acc)[NM][4], const int R0, const int C0, const float* rsw, const EpiArgs& ea) {
;     ...
;   } else if constexpr (EPI == EPI_OUT) {
;     u16* abase = (u16*)(ws + OFF_ABF) + (size_t)(R0 + fr) * DM + C0 + fq * 4;
;     u32x2 rc[4];
; #pragma unroll
;     for (int n = 0; n < 4; ++n) rc[n] = *reinterpret_cast<const u32x2*>(abase + n * 16);
; #pragma unroll
;     for (int m = 0; m < NM; ++m) {
;       u32x2 rn[4];
;       if (m + 1 < NM) {
; #pragma unroll
;         for (int n = 0; n < 4; ++n) rn[n] = *reinterpret_cast<const u32x2*>(abase + (size_t)ROFF(m + 1) * DM + n * 16);
;       }
;       __builtin_amdgcn_sched_barrier(0);
;       float s = 0.f;
; #pragma unroll
;       for (int n = 0; n < 4; ++n) {
;         f32x4 h = acc[m][n];
;         h[0] += __uint_as_float(rc[n][0] << 16); h[1] += __uint_as_float(rc[n][0] & 0xffff0000u);
;         h[2] += __uint_as_float(rc[n][1] << 16); h[3] += __uint_as_float(rc[n][1] & 0xffff0000u);
;         *reinterpret_cast<u32x2*>(abase + (size_t)ROFF(m) * DM + n * 16) = u32x2{cvtpk(h[0], h[1]), cvtpk(h[2], h[3])};
;         s += h[0] * h[0] + h[1] * h[1] + h[2] * h[2] + h[3] * h[3];
;       }
;       s += __shfl_xor(s, 16); s += __shfl_xor(s, 32);
;       if (fq == 0) atomicAdd(ea.ss_next + R0 + ROFF(m) + fr, s);
;       __builtin_amdgcn_sched_barrier(0);
;       if (m + 1 < NM) {
; #pragma unroll
;         for (int n = 0; n < 4; ++n) rc[n] = rn[n];
;       }
;     }
.LBB0_385:
	s_or_b64 exec, exec, s[92:93]
	s_mov_b64 s[16:17], 0x18000
	v_lshl_add_u64 v[88:89], v[130:131], 0, s[16:17]
	s_mov_b64 s[16:17], 0x18020
	v_lshl_add_u64 v[90:91], v[130:131], 0, s[16:17]
	s_mov_b64 s[16:17], 0x18040
	v_lshl_add_u64 v[92:93], v[130:131], 0, s[16:17]
	s_mov_b64 s[16:17], 0x18060
	v_lshl_add_u64 v[94:95], v[130:131], 0, s[16:17]
	v_add_co_u32_e32 v80, vcc, 0x40000, v130
	s_waitcnt lgkmcnt(0)
	s_nop 0
	v_addc_co_u32_e32 v81, vcc, 0, v131, vcc
	s_nop 0
	s_waitcnt vmcnt(28)
	v_lshlrev_b32_e32 v104, 16, v180
	v_add_f32_e32 v104, v76, v104
	v_and_b32_e32 v76, 0xffff0000, v180
	v_add_f32_e32 v102, v77, v76
	v_lshlrev_b32_e32 v76, 16, v181
	v_add_f32_e32 v78, v78, v76
	v_and_b32_e32 v76, 0xffff0000, v181
	v_add_f32_e32 v79, v79, v76
	v_cvt_pk_bf16_f32 v76, v104, v102
	v_cvt_pk_bf16_f32 v77, v78, v79
	global_store_dwordx2 v[88:89], v[76:77], off
	v_lshlrev_b32_e32 v77, 16, v182
	v_add_f32_e32 v77, v68, v77
	v_and_b32_e32 v68, 0xffff0000, v182
	v_add_f32_e32 v69, v69, v68
	v_lshlrev_b32_e32 v68, 16, v183
	v_add_f32_e32 v70, v70, v68
	v_and_b32_e32 v68, 0xffff0000, v183
	v_mul_f32_e32 v76, v102, v102
	v_add_f32_e32 v71, v71, v68
	v_cvt_pk_bf16_f32 v68, v77, v69
	v_mul_f32_e32 v69, v69, v69
	v_fmac_f32_e32 v76, v104, v104
	v_fmac_f32_e32 v69, v77, v77
	v_fmac_f32_e32 v76, v78, v78
	v_fmac_f32_e32 v69, v70, v70
	v_fmac_f32_e32 v76, v79, v79
	v_fmac_f32_e32 v69, v71, v71
	v_add_f32_e32 v69, v76, v69
	v_lshlrev_b32_e32 v76, 16, v184
	v_add_f32_e32 v72, v72, v76
	v_and_b32_e32 v76, 0xffff0000, v184
	v_add_f32_e32 v73, v73, v76
	v_lshlrev_b32_e32 v76, 16, v185
	v_add_f32_e32 v74, v74, v76
	v_and_b32_e32 v76, 0xffff0000, v185
	v_add_f32_e32 v75, v75, v76
	v_mul_f32_e32 v76, v73, v73
	v_fmac_f32_e32 v76, v72, v72
	v_fmac_f32_e32 v76, v74, v74
	v_fmac_f32_e32 v76, v75, v75
	v_add_f32_e32 v69, v69, v76
	v_lshlrev_b32_e32 v76, 16, v186
	v_add_f32_e32 v76, v64, v76
	v_and_b32_e32 v64, 0xffff0000, v186
	v_add_f32_e32 v77, v65, v64
	v_lshlrev_b32_e32 v64, 16, v187
	v_add_f32_e32 v78, v66, v64
	v_and_b32_e32 v64, 0xffff0000, v187
	v_add_f32_e32 v79, v67, v64
	v_mul_f32_e32 v64, v77, v77
	v_fmac_f32_e32 v64, v76, v76
	v_fmac_f32_e32 v64, v78, v78
	v_fmac_f32_e32 v64, v79, v79
	v_add_f32_e32 v64, v69, v64
	ds_bpermute_b32 v65, v122, v64
	v_cvt_pk_bf16_f32 v69, v70, v71
	global_store_dwordx2 v[90:91], v[68:69], off
	v_cvt_pk_bf16_f32 v66, v72, v73
	v_cvt_pk_bf16_f32 v67, v74, v75
	s_waitcnt lgkmcnt(0)
	v_add_f32_e32 v64, v64, v65
	ds_bpermute_b32 v65, v123, v64
	global_store_dwordx2 v[92:93], v[66:67], off
	v_cvt_pk_bf16_f32 v66, v76, v77
	v_cvt_pk_bf16_f32 v67, v78, v79
	global_store_dwordx2 v[94:95], v[66:67], off
	s_and_saveexec_b64 s[92:93], s[4:5]
	s_cbranch_execz .LBB0_387
	s_waitcnt lgkmcnt(0)
	v_add_f32_e32 v66, v64, v65
	v_lshl_add_u64 v[64:65], v[112:113], 0, v[128:129]
	global_atomic_add_f32 v[64:65], v66, off offset:192
.LBB0_387:
	s_or_b64 exec, exec, s[92:93]
	s_mov_b64 s[16:17], 0x40000
	v_lshl_add_u64 v[72:73], v[130:131], 0, s[16:17]
	s_mov_b64 s[16:17], 0x40020
	v_lshl_add_u64 v[74:75], v[130:131], 0, s[16:17]
	s_mov_b64 s[16:17], 0x40040
	v_lshl_add_u64 v[76:77], v[130:131], 0, s[16:17]
	v_lshl_add_u64 v[78:79], v[130:131], 0, s[50:51]
	v_add_co_u32_e32 v64, vcc, 0x48000, v130
	s_waitcnt lgkmcnt(0)
	s_nop 0
	v_addc_co_u32_e32 v65, vcc, 0, v131, vcc
	s_nop 0
	s_waitcnt vmcnt(28)
	v_lshlrev_b32_e32 v88, 16, v188
	v_add_f32_e32 v88, v60, v88
	v_and_b32_e32 v60, 0xffff0000, v188
	v_add_f32_e32 v86, v61, v60
	v_lshlrev_b32_e32 v60, 16, v189
	v_add_f32_e32 v62, v62, v60
	v_and_b32_e32 v60, 0xffff0000, v189
	v_add_f32_e32 v63, v63, v60
	v_cvt_pk_bf16_f32 v60, v88, v86
	v_cvt_pk_bf16_f32 v61, v62, v63
	global_store_dwordx2 v[72:73], v[60:61], off
	v_lshlrev_b32_e32 v61, 16, v190
	v_add_f32_e32 v61, v56, v61
	v_and_b32_e32 v56, 0xffff0000, v190
	v_add_f32_e32 v57, v57, v56
	v_lshlrev_b32_e32 v56, 16, v191
	v_add_f32_e32 v58, v58, v56
	v_and_b32_e32 v56, 0xffff0000, v191
	v_mul_f32_e32 v60, v86, v86
	v_add_f32_e32 v59, v59, v56
	v_cvt_pk_bf16_f32 v56, v61, v57
	v_mul_f32_e32 v57, v57, v57
	v_fmac_f32_e32 v60, v88, v88
	v_fmac_f32_e32 v57, v61, v61
	v_fmac_f32_e32 v60, v62, v62
	v_fmac_f32_e32 v57, v58, v58
	v_fmac_f32_e32 v60, v63, v63
	v_fmac_f32_e32 v57, v59, v59
	v_add_f32_e32 v57, v60, v57
	v_lshlrev_b32_e32 v60, 16, v192
	v_add_f32_e32 v52, v52, v60
	v_and_b32_e32 v60, 0xffff0000, v192
	v_add_f32_e32 v53, v53, v60
	v_lshlrev_b32_e32 v60, 16, v193
	v_add_f32_e32 v54, v54, v60
	v_and_b32_e32 v60, 0xffff0000, v193
	v_add_f32_e32 v55, v55, v60
	v_mul_f32_e32 v60, v53, v53
	v_fmac_f32_e32 v60, v52, v52
	v_fmac_f32_e32 v60, v54, v54
	v_fmac_f32_e32 v60, v55, v55
	v_add_f32_e32 v57, v57, v60
	v_lshlrev_b32_e32 v60, 16, v194
	v_add_f32_e32 v60, v48, v60
	v_and_b32_e32 v48, 0xffff0000, v194
	v_add_f32_e32 v61, v49, v48
	v_lshlrev_b32_e32 v48, 16, v195
	v_add_f32_e32 v62, v50, v48
	v_and_b32_e32 v48, 0xffff0000, v195
	v_add_f32_e32 v63, v51, v48
	v_mul_f32_e32 v48, v61, v61
	v_fmac_f32_e32 v48, v60, v60
	v_fmac_f32_e32 v48, v62, v62
	v_fmac_f32_e32 v48, v63, v63
	v_add_f32_e32 v48, v57, v48
	ds_bpermute_b32 v49, v122, v48
	v_cvt_pk_bf16_f32 v57, v58, v59
	global_store_dwordx2 v[74:75], v[56:57], off
	v_cvt_pk_bf16_f32 v50, v52, v53
	v_cvt_pk_bf16_f32 v51, v54, v55
	s_waitcnt lgkmcnt(0)
	v_add_f32_e32 v48, v48, v49
	ds_bpermute_b32 v49, v123, v48
	global_store_dwordx2 v[76:77], v[50:51], off
	v_cvt_pk_bf16_f32 v50, v60, v61
	v_cvt_pk_bf16_f32 v51, v62, v63
	global_store_dwordx2 v[78:79], v[50:51], off
	s_and_saveexec_b64 s[92:93], s[4:5]
	s_cbranch_execz .LBB0_389
	s_waitcnt lgkmcnt(0)
	v_add_f32_e32 v50, v48, v49
	v_lshl_add_u64 v[48:49], v[112:113], 0, v[128:129]
	global_atomic_add_f32 v[48:49], v50, off offset:512
; template <int EPI, int NM, bool SWAP>
; DEVI void gemm_epilogue(const Params& p, f32x4 (&acc)[NM][4], const int R0, const int C0, const float* rsw, const EpiArgs& ea) {
;     ...
;   } else if constexpr (EPI == EPI_OUT) {
;     u16* abase = (u16*)(ws + OFF_ABF) + (size_t)(R0 + fr) * DM + C0 + fq * 4;
;     u32x2 rc[4];
; #pragma unroll
;     for (int n = 0; n < 4; ++n) rc[n] = *reinterpret_cast<const u32x2*>(abase + n * 16);
; #pragma unroll
;     for (int m = 0; m < NM; ++m) {
;       u32x2 rn[4];
;       if (m + 1 < NM) {
; #pragma unroll
;         for (int n = 0; n < 4; ++n) rn[n] = *reinterpret_cast<const u32x2*>(abase + (size_t)ROFF(m + 1) * DM + n * 16);
;       }
;       __builtin_amdgcn_sched_barrier(0);
;       float s = 0.f;
; #pragma unroll
;       for (int n = 0; n < 4; ++n) {
;         f32x4 h = acc[m][n];
;         h[0] += __uint_as_float(rc[n][0] << 16); h[1] += __uint_as_float(rc[n][0] & 0xffff0000u);
;         h[2] += __uint_as_float(rc[n][1] << 16); h[3] += __uint_as_float(rc[n][1] & 0xffff0000u);
;         *reinterpret_cast<u32x2*>(abase + (size_t)ROFF(m) * DM + n * 16) = u32x2{cvtpk(h[0], h[1]), cvtpk(h[2], h[3])};
;         s += h[0] * h[0] + h[1] * h[1] + h[2] * h[2] + h[3] * h[3];
;       }
;       s += __shfl_xor(s, 16); s += __shfl_xor(s, 32);
;       if (fq == 0) atomicAdd(ea.ss_next + R0 + ROFF(m) + fr, s);
;       __builtin_amdgcn_sched_barrier(0);
;       if (m + 1 < NM) {
; #pragma unroll
;         for (int n = 0; n < 4; ++n) rc[n] = rn[n];
;       }
;     }
.LBB0_389:
	s_or_b64 exec, exec, s[92:93]
	v_lshl_add_u64 v[56:57], v[130:131], 0, s[52:53]
	v_lshl_add_u64 v[58:59], v[130:131], 0, s[54:55]
	v_lshl_add_u64 v[60:61], v[130:131], 0, s[56:57]
	v_lshl_add_u64 v[62:63], v[130:131], 0, s[68:69]
	v_add_co_u32_e32 v48, vcc, 0x50000, v130
	s_waitcnt lgkmcnt(0)
	s_nop 0
	v_addc_co_u32_e32 v49, vcc, 0, v131, vcc
	s_nop 0
	s_waitcnt vmcnt(28)
	v_lshlrev_b32_e32 v72, 16, v196
	v_add_f32_e32 v72, v44, v72
	v_and_b32_e32 v44, 0xffff0000, v196
	v_add_f32_e32 v70, v45, v44
	v_lshlrev_b32_e32 v44, 16, v197
	v_add_f32_e32 v46, v46, v44
	v_and_b32_e32 v44, 0xffff0000, v197
	v_add_f32_e32 v47, v47, v44
	v_cvt_pk_bf16_f32 v44, v72, v70
	v_cvt_pk_bf16_f32 v45, v46, v47
	global_store_dwordx2 v[56:57], v[44:45], off
	v_lshlrev_b32_e32 v45, 16, v198
	v_add_f32_e32 v45, v40, v45
	v_and_b32_e32 v40, 0xffff0000, v198
	v_add_f32_e32 v41, v41, v40
	v_lshlrev_b32_e32 v40, 16, v199
	v_add_f32_e32 v42, v42, v40
	v_and_b32_e32 v40, 0xffff0000, v199
	v_mul_f32_e32 v44, v70, v70
	v_add_f32_e32 v43, v43, v40
	v_cvt_pk_bf16_f32 v40, v45, v41
	v_mul_f32_e32 v41, v41, v41
	v_fmac_f32_e32 v44, v72, v72
	v_fmac_f32_e32 v41, v45, v45
	v_fmac_f32_e32 v44, v46, v46
	v_fmac_f32_e32 v41, v42, v42
	v_fmac_f32_e32 v44, v47, v47
	v_fmac_f32_e32 v41, v43, v43
	v_add_f32_e32 v41, v44, v41
	v_lshlrev_b32_e32 v44, 16, v200
	v_add_f32_e32 v36, v36, v44
	v_and_b32_e32 v44, 0xffff0000, v200
	v_add_f32_e32 v37, v37, v44
	v_lshlrev_b32_e32 v44, 16, v201
	v_add_f32_e32 v38, v38, v44
	v_and_b32_e32 v44, 0xffff0000, v201
	v_add_f32_e32 v39, v39, v44
	v_mul_f32_e32 v44, v37, v37
	v_fmac_f32_e32 v44, v36, v36
	v_fmac_f32_e32 v44, v38, v38
	v_fmac_f32_e32 v44, v39, v39
	v_add_f32_e32 v41, v41, v44
	v_lshlrev_b32_e32 v44, 16, v202
	v_add_f32_e32 v44, v32, v44
	v_and_b32_e32 v32, 0xffff0000, v202
	v_add_f32_e32 v45, v33, v32
	v_lshlrev_b32_e32 v32, 16, v203
	v_add_f32_e32 v46, v34, v32
	v_and_b32_e32 v32, 0xffff0000, v203
	v_add_f32_e32 v47, v35, v32
	v_mul_f32_e32 v32, v45, v45
	v_fmac_f32_e32 v32, v44, v44
	v_fmac_f32_e32 v32, v46, v46
	v_fmac_f32_e32 v32, v47, v47
	v_add_f32_e32 v32, v41, v32
	ds_bpermute_b32 v33, v122, v32
	v_cvt_pk_bf16_f32 v41, v42, v43
	global_store_dwordx2 v[58:59], v[40:41], off
	v_cvt_pk_bf16_f32 v34, v36, v37
	v_cvt_pk_bf16_f32 v35, v38, v39
	s_waitcnt lgkmcnt(0)
	v_add_f32_e32 v32, v32, v33
	ds_bpermute_b32 v33, v123, v32
	global_store_dwordx2 v[60:61], v[34:35], off
	v_cvt_pk_bf16_f32 v34, v44, v45
	v_cvt_pk_bf16_f32 v35, v46, v47
	global_store_dwordx2 v[62:63], v[34:35], off
	s_and_saveexec_b64 s[92:93], s[4:5]
	s_cbranch_execz .LBB0_391
	s_waitcnt lgkmcnt(0)
	v_add_f32_e32 v34, v32, v33
	v_lshl_add_u64 v[32:33], v[112:113], 0, v[128:129]
	global_atomic_add_f32 v[32:33], v34, off offset:576
; template <int EPI, int NM, bool SWAP>
; DEVI void gemm_epilogue(const Params& p, f32x4 (&acc)[NM][4], const int R0, const int C0, const float* rsw, const EpiArgs& ea) {
;     ...
;     for (int m = 0; m < NM; ++m) {
;       u32x2 rn[4];
;       if (m + 1 < NM) {
; #pragma unroll
;         for (int n = 0; n < 4; ++n) rn[n] = *reinterpret_cast<const u32x2*>(abase + (size_t)ROFF(m + 1) * DM + n * 16);
;       }
;       __builtin_amdgcn_sched_barrier(0);
;       float s = 0.f;
; #pragma unroll
;       for (int n = 0; n < 4; ++n) {
;         f32x4 h = acc[m][n];
;         h[0] += __uint_as_float(rc[n][0] << 16); h[1] += __uint_as_float(rc[n][0] & 0xffff0000u);
;         h[2] += __uint_as_float(rc[n][1] << 16); h[3] += __uint_as_float(rc[n][1] & 0xffff0000u);
;         *reinterpret_cast<u32x2*>(abase + (size_t)ROFF(m) * DM + n * 16) = u32x2{cvtpk(h[0], h[1]), cvtpk(h[2], h[3])};
;         s += h[0] * h[0] + h[1] * h[1] + h[2] * h[2] + h[3] * h[3];
;       }
;       s += __shfl_xor(s, 16); s += __shfl_xor(s, 32);
;       if (fq == 0) atomicAdd(ea.ss_next + R0 + ROFF(m) + fr, s);
;       __builtin_amdgcn_sched_barrier(0);
;       if (m + 1 < NM) {
; #pragma unroll
;         for (int n = 0; n < 4; ++n) rc[n] = rn[n];
;       }
;     }
.LBB0_391:
	s_or_b64 exec, exec, s[92:93]
	v_lshl_add_u64 v[40:41], v[130:131], 0, s[70:71]
	v_lshl_add_u64 v[42:43], v[130:131], 0, s[78:79]
	v_lshl_add_u64 v[44:45], v[130:131], 0, s[80:81]
	v_lshl_add_u64 v[46:47], v[130:131], 0, s[82:83]
	v_add_co_u32_e32 v32, vcc, 0x58000, v130
	s_waitcnt lgkmcnt(0)
	s_nop 0
	v_addc_co_u32_e32 v33, vcc, 0, v131, vcc
	s_nop 0
	s_waitcnt vmcnt(28)
	v_lshlrev_b32_e32 v56, 16, v204
	v_add_f32_e32 v56, v28, v56
	v_and_b32_e32 v28, 0xffff0000, v204
	v_add_f32_e32 v54, v29, v28
	v_lshlrev_b32_e32 v28, 16, v205
	v_add_f32_e32 v30, v30, v28
	v_and_b32_e32 v28, 0xffff0000, v205
	v_add_f32_e32 v31, v31, v28
	v_cvt_pk_bf16_f32 v28, v56, v54
	v_cvt_pk_bf16_f32 v29, v30, v31
	global_store_dwordx2 v[40:41], v[28:29], off
	v_lshlrev_b32_e32 v29, 16, v206
	v_add_f32_e32 v29, v24, v29
	v_and_b32_e32 v24, 0xffff0000, v206
	v_add_f32_e32 v25, v25, v24
	v_lshlrev_b32_e32 v24, 16, v207
	v_add_f32_e32 v26, v26, v24
	v_and_b32_e32 v24, 0xffff0000, v207
	v_mul_f32_e32 v28, v54, v54
	v_add_f32_e32 v27, v27, v24
	v_cvt_pk_bf16_f32 v24, v29, v25
	v_mul_f32_e32 v25, v25, v25
	v_fmac_f32_e32 v28, v56, v56
	v_fmac_f32_e32 v25, v29, v29
	v_fmac_f32_e32 v28, v30, v30
	v_fmac_f32_e32 v25, v26, v26
	v_fmac_f32_e32 v28, v31, v31
	v_fmac_f32_e32 v25, v27, v27
	v_add_f32_e32 v25, v28, v25
	v_lshlrev_b32_e32 v28, 16, v208
	v_add_f32_e32 v20, v20, v28
	v_and_b32_e32 v28, 0xffff0000, v208
	v_add_f32_e32 v21, v21, v28
	v_lshlrev_b32_e32 v28, 16, v209
	v_add_f32_e32 v22, v22, v28
	v_and_b32_e32 v28, 0xffff0000, v209
	v_add_f32_e32 v23, v23, v28
	v_mul_f32_e32 v28, v21, v21
	v_fmac_f32_e32 v28, v20, v20
	v_fmac_f32_e32 v28, v22, v22
	v_fmac_f32_e32 v28, v23, v23
	v_add_f32_e32 v25, v25, v28
	v_lshlrev_b32_e32 v28, 16, v210
	v_add_f32_e32 v28, v16, v28
	v_and_b32_e32 v16, 0xffff0000, v210
	v_add_f32_e32 v29, v17, v16
	v_lshlrev_b32_e32 v16, 16, v211
	v_add_f32_e32 v30, v18, v16
	v_and_b32_e32 v16, 0xffff0000, v211
	v_add_f32_e32 v31, v19, v16
	v_mul_f32_e32 v16, v29, v29
	v_fmac_f32_e32 v16, v28, v28
	v_fmac_f32_e32 v16, v30, v30
	v_fmac_f32_e32 v16, v31, v31
	v_add_f32_e32 v16, v25, v16
	ds_bpermute_b32 v17, v122, v16
	v_cvt_pk_bf16_f32 v25, v26, v27
	global_store_dwordx2 v[42:43], v[24:25], off
	v_cvt_pk_bf16_f32 v18, v20, v21
	v_cvt_pk_bf16_f32 v19, v22, v23
	s_waitcnt lgkmcnt(0)
	v_add_f32_e32 v16, v16, v17
	ds_bpermute_b32 v17, v123, v16
	global_store_dwordx2 v[44:45], v[18:19], off
	v_cvt_pk_bf16_f32 v18, v28, v29
	v_cvt_pk_bf16_f32 v19, v30, v31
	global_store_dwordx2 v[46:47], v[18:19], off
	s_and_saveexec_b64 s[92:93], s[4:5]
	s_cbranch_execz .LBB0_393
	s_waitcnt lgkmcnt(0)
	v_add_f32_e32 v18, v16, v17
	v_lshl_add_u64 v[16:17], v[112:113], 0, v[128:129]
	global_atomic_add_f32 v[16:17], v18, off offset:640
.LBB0_393:
	s_or_b64 exec, exec, s[92:93]
	s_waitcnt lgkmcnt(0)
	v_lshl_add_u64 v[16:17], v[130:131], 0, s[84:85]
	v_lshl_add_u64 v[18:19], v[130:131], 0, s[86:87]
	v_lshl_add_u64 v[20:21], v[130:131], 0, s[88:89]
	v_lshl_add_u64 v[22:23], v[130:131], 0, s[90:91]
	s_waitcnt vmcnt(28)
	v_lshlrev_b32_e32 v24, 16, v212
	v_add_f32_e32 v24, v12, v24
	v_and_b32_e32 v12, 0xffff0000, v212
	v_add_f32_e32 v25, v13, v12
	v_lshlrev_b32_e32 v12, 16, v213
	v_add_f32_e32 v14, v14, v12
	v_and_b32_e32 v12, 0xffff0000, v213
	v_add_f32_e32 v15, v15, v12
	v_cvt_pk_bf16_f32 v12, v24, v25
	v_cvt_pk_bf16_f32 v13, v14, v15
	global_store_dwordx2 v[16:17], v[12:13], off
	v_lshlrev_b32_e32 v13, 16, v214
	v_add_f32_e32 v13, v8, v13
	v_and_b32_e32 v8, 0xffff0000, v214
	v_add_f32_e32 v9, v9, v8
	v_lshlrev_b32_e32 v8, 16, v215
	v_add_f32_e32 v10, v10, v8
	v_and_b32_e32 v8, 0xffff0000, v215
	v_mul_f32_e32 v12, v25, v25
	v_add_f32_e32 v11, v11, v8
	v_cvt_pk_bf16_f32 v8, v13, v9
	v_mul_f32_e32 v9, v9, v9
	v_fmac_f32_e32 v12, v24, v24
	v_fmac_f32_e32 v9, v13, v13
	v_fmac_f32_e32 v12, v14, v14
	v_fmac_f32_e32 v9, v10, v10
	v_fmac_f32_e32 v12, v15, v15
	v_fmac_f32_e32 v9, v11, v11
	v_add_f32_e32 v9, v12, v9
	v_lshlrev_b32_e32 v12, 16, v216
	v_add_f32_e32 v4, v4, v12
	v_and_b32_e32 v12, 0xffff0000, v216
	v_add_f32_e32 v5, v5, v12
	v_lshlrev_b32_e32 v12, 16, v217
	v_add_f32_e32 v6, v6, v12
	v_and_b32_e32 v12, 0xffff0000, v217
	v_add_f32_e32 v7, v7, v12
	v_mul_f32_e32 v12, v5, v5
	v_fmac_f32_e32 v12, v4, v4
	v_fmac_f32_e32 v12, v6, v6
	v_fmac_f32_e32 v12, v7, v7
	v_add_f32_e32 v9, v9, v12
	v_lshlrev_b32_e32 v12, 16, v224
	v_add_f32_e32 v12, v0, v12
	v_and_b32_e32 v0, 0xffff0000, v224
	v_add_f32_e32 v13, v1, v0
	v_lshlrev_b32_e32 v0, 16, v225
	v_add_f32_e32 v14, v2, v0
	v_and_b32_e32 v0, 0xffff0000, v225
	v_add_f32_e32 v15, v3, v0
	v_mul_f32_e32 v0, v13, v13
	v_fmac_f32_e32 v0, v12, v12
	v_fmac_f32_e32 v0, v14, v14
	v_fmac_f32_e32 v0, v15, v15
	v_add_f32_e32 v0, v9, v0
	ds_bpermute_b32 v1, v122, v0
	v_cvt_pk_bf16_f32 v9, v10, v11
	global_store_dwordx2 v[18:19], v[8:9], off
	v_cvt_pk_bf16_f32 v2, v4, v5
	v_cvt_pk_bf16_f32 v3, v6, v7
	s_waitcnt lgkmcnt(0)
	v_add_f32_e32 v0, v0, v1
	ds_bpermute_b32 v1, v123, v0
	global_store_dwordx2 v[20:21], v[2:3], off
	v_cvt_pk_bf16_f32 v2, v12, v13
	v_cvt_pk_bf16_f32 v3, v14, v15
	global_store_dwordx2 v[22:23], v[2:3], off
	s_and_saveexec_b64 s[92:93], s[4:5]
	s_cbranch_execz .LBB0_368
	s_waitcnt lgkmcnt(0)
	v_add_f32_e32 v2, v0, v1
	v_lshl_add_u64 v[0:1], v[112:113], 0, v[128:129]
	global_atomic_add_f32 v[0:1], v2, off offset:704
	s_branch .LBB0_368

; template <int EPI, int NM, bool SWAP>
; DEVI void gemm_epilogue(const Params& p, f32x4 (&acc)[NM][4], const int R0, const int C0, const float* rsw, const EpiArgs& ea) {
;     ...
;   } else if constexpr (EPI == EPI_OUT) {
;     u16* abase = (u16*)(ws + OFF_ABF) + (size_t)(R0 + fr) * DM + C0 + fq * 4;
;     u32x2 rc[4];
; #pragma unroll
;     for (int n = 0; n < 4; ++n) rc[n] = *reinterpret_cast<const u32x2*>(abase + n * 16);
; #pragma unroll
;     for (int m = 0; m < NM; ++m) {
;       u32x2 rn[4];
;       if (m + 1 < NM) {
; #pragma unroll
;         for (int n = 0; n < 4; ++n) rn[n] = *reinterpret_cast<const u32x2*>(abase + (size_t)ROFF(m + 1) * DM + n * 16);
;       }
;       __builtin_amdgcn_sched_barrier(0);
;       float s = 0.f;
; #pragma unroll
;       for (int n = 0; n < 4; ++n) {
;         f32x4 h = acc[m][n];
;         h[0] += __uint_as_float(rc[n][0] << 16); h[1] += __uint_as_float(rc[n][0] & 0xffff0000u);
;         h[2] += __uint_as_float(rc[n][1] << 16); h[3] += __uint_as_float(rc[n][1] & 0xffff0000u);
;         *reinterpret_cast<u32x2*>(abase + (size_t)ROFF(m) * DM + n * 16) = u32x2{cvtpk(h[0], h[1]), cvtpk(h[2], h[3])};
;         s += h[0] * h[0] + h[1] * h[1] + h[2] * h[2] + h[3] * h[3];
;       }
;       s += __shfl_xor(s, 16); s += __shfl_xor(s, 32);
;       if (fq == 0) atomicAdd(ea.ss_next + R0 + ROFF(m) + fr, s);
.LBB0_451:
	s_or_b64 exec, exec, s[6:7]
	v_lshlrev_b32_e32 v128, 6, v147
	v_lshl_or_b32 v130, s92, 8, v128
	v_mov_b32_e32 v128, v222
	v_add_u32_e32 v140, s93, v148
	v_ashrrev_i32_e32 v131, 31, v130
	v_and_b32_e32 v147, 15, v128
	v_or_b32_e32 v132, v147, v140
	v_ashrrev_i32_e32 v133, 31, v132
	v_lshlrev_b64 v[132:133], 11, v[132:133]
	v_lshl_add_u64 v[132:133], s[38:39], 0, v[132:133]
	v_lshl_add_u64 v[130:131], v[130:131], 1, v[132:133]
	v_ashrrev_i32_e32 v132, 2, v128
	v_and_b32_e32 v132, -4, v132
	v_ashrrev_i32_e32 v133, 31, v132
	v_lshl_add_u64 v[130:131], v[132:133], 1, v[130:131]
	s_mov_b32 s6, 0x8000
	v_add_co_u32_e32 v132, vcc, s6, v130
	global_load_dwordx2 v[142:143], v[130:131], off
	global_load_dwordx2 v[144:145], v[130:131], off offset:32
	global_load_dwordx2 v[148:149], v[130:131], off offset:64
	global_load_dwordx2 v[150:151], v[130:131], off offset:96
	v_addc_co_u32_e32 v133, vcc, 0, v131, vcc
	global_load_dwordx2 v[138:139], v[132:133], off
	global_load_dwordx2 v[136:137], v[132:133], off offset:32
	global_load_dwordx2 v[134:135], v[132:133], off offset:64
	s_nop 0
	global_load_dwordx2 v[132:133], v[132:133], off offset:96
	s_mov_b64 s[100:101], 0x10000
	v_lshl_add_u64 v[174:175], v[130:131], 0, s[100:101]
	global_load_dwordx2 v[176:177], v[174:175], off
	global_load_dwordx2 v[178:179], v[174:175], off offset:32
	global_load_dwordx2 v[180:181], v[174:175], off offset:64
	global_load_dwordx2 v[182:183], v[174:175], off offset:96
	s_mov_b64 s[100:101], 0x18000
	v_lshl_add_u64 v[174:175], v[130:131], 0, s[100:101]
	global_load_dwordx2 v[184:185], v[174:175], off
	global_load_dwordx2 v[186:187], v[174:175], off offset:32
	global_load_dwordx2 v[188:189], v[174:175], off offset:64
	global_load_dwordx2 v[190:191], v[174:175], off offset:96
	s_mov_b64 s[100:101], 0x40000
	v_lshl_add_u64 v[174:175], v[130:131], 0, s[100:101]
	global_load_dwordx2 v[192:193], v[174:175], off
	global_load_dwordx2 v[194:195], v[174:175], off offset:32
	global_load_dwordx2 v[196:197], v[174:175], off offset:64
	global_load_dwordx2 v[198:199], v[174:175], off offset:96
	s_mov_b64 s[100:101], 0x48000
	v_lshl_add_u64 v[174:175], v[130:131], 0, s[100:101]
	global_load_dwordx2 v[200:201], v[174:175], off
	global_load_dwordx2 v[202:203], v[174:175], off offset:32
	global_load_dwordx2 v[204:205], v[174:175], off offset:64
	global_load_dwordx2 v[206:207], v[174:175], off offset:96
	s_mov_b64 s[100:101], 0x50000
	v_lshl_add_u64 v[174:175], v[130:131], 0, s[100:101]
	global_load_dwordx2 v[208:209], v[174:175], off
	global_load_dwordx2 v[210:211], v[174:175], off offset:32
	global_load_dwordx2 v[212:213], v[174:175], off offset:64
	global_load_dwordx2 v[214:215], v[174:175], off offset:96
	s_mov_b64 s[100:101], 0x58000
	v_lshl_add_u64 v[174:175], v[130:131], 0, s[100:101]
	global_load_dwordx2 v[216:217], v[174:175], off
	global_load_dwordx2 v[224:225], v[174:175], off offset:32
	global_load_dwordx2 v[226:227], v[174:175], off offset:64
	global_load_dwordx2 v[228:229], v[174:175], off offset:96
	v_cmp_gt_u32_e64 s[6:7], 16, v128
	v_ashrrev_i32_e32 v141, 31, v140
	s_waitcnt vmcnt(28)
	v_lshlrev_b32_e32 v128, 16, v142
	v_add_f32_e32 v128, v124, v128
	v_and_b32_e32 v124, 0xffff0000, v142
	v_add_f32_e32 v142, v125, v124
	v_lshlrev_b32_e32 v124, 16, v143
	v_add_f32_e32 v126, v126, v124
	v_and_b32_e32 v124, 0xffff0000, v143
	v_add_f32_e32 v127, v127, v124
	v_cvt_pk_bf16_f32 v124, v128, v142
	v_cvt_pk_bf16_f32 v125, v126, v127
	global_store_dwordx2 v[130:131], v[124:125], off
	v_mul_f32_e32 v124, v142, v142
	v_lshlrev_b32_e32 v125, 16, v144
	v_fmac_f32_e32 v124, v128, v128
	v_add_f32_e32 v125, v116, v125
	v_and_b32_e32 v116, 0xffff0000, v144
	v_fmac_f32_e32 v124, v126, v126
	v_add_f32_e32 v126, v117, v116
	v_lshlrev_b32_e32 v116, 16, v145
	v_add_f32_e32 v118, v118, v116
	v_and_b32_e32 v116, 0xffff0000, v145
	v_add_f32_e32 v119, v119, v116
	v_cvt_pk_bf16_f32 v116, v125, v126
	v_cvt_pk_bf16_f32 v117, v118, v119
	global_store_dwordx2 v[130:131], v[116:117], off offset:32
	v_mul_f32_e32 v116, v126, v126
	v_fmac_f32_e32 v116, v125, v125
	v_fmac_f32_e32 v116, v118, v118
	v_and_b32_e32 v118, 0xffff0000, v148
	v_lshlrev_b32_e32 v117, 16, v148
	v_add_f32_e32 v118, v121, v118
	v_fmac_f32_e32 v116, v119, v119
	v_add_f32_e32 v117, v120, v117
	v_lshlrev_b32_e32 v119, 16, v149
	v_mul_f32_e32 v121, v118, v118
	v_add_f32_e32 v119, v122, v119
	v_and_b32_e32 v120, 0xffff0000, v149
	v_fmac_f32_e32 v121, v117, v117
	v_fmac_f32_e32 v124, v127, v127
	v_add_f32_e32 v120, v123, v120
	v_fmac_f32_e32 v121, v119, v119
	v_add_f32_e32 v116, v124, v116
	v_fmac_f32_e32 v121, v120, v120
	v_add_f32_e32 v116, v116, v121
	v_lshlrev_b32_e32 v121, 16, v150
	v_add_f32_e32 v121, v112, v121
	v_and_b32_e32 v112, 0xffff0000, v150
	v_add_f32_e32 v123, v113, v112
	v_lshlrev_b32_e32 v112, 16, v151
	v_add_f32_e32 v124, v114, v112
	v_and_b32_e32 v112, 0xffff0000, v151
	v_add_f32_e32 v125, v115, v112
	v_mul_f32_e32 v112, v123, v123
	v_fmac_f32_e32 v112, v121, v121
	v_fmac_f32_e32 v112, v124, v124
	v_fmac_f32_e32 v112, v125, v125
	v_and_b32_e32 v113, 64, v146
	v_add_f32_e32 v114, v116, v112
	v_xor_b32_e32 v112, 16, v146
	v_add_u32_e32 v115, 64, v113
	v_cmp_lt_i32_e32 vcc, v112, v115
	v_lshlrev_b32_e32 v128, 2, v147
	s_nop 0
	v_cndmask_b32_e32 v112, v146, v112, vcc
	v_lshlrev_b32_e32 v122, 2, v112
	ds_bpermute_b32 v116, v122, v114
	v_cvt_pk_bf16_f32 v112, v117, v118
	v_cvt_pk_bf16_f32 v113, v119, v120
	global_store_dwordx2 v[130:131], v[112:113], off offset:64
	v_xor_b32_e32 v113, 32, v146
	v_cmp_lt_i32_e32 vcc, v113, v115
	v_cvt_pk_bf16_f32 v112, v121, v123
	s_waitcnt lgkmcnt(0)
	v_add_f32_e32 v114, v114, v116
	v_cndmask_b32_e32 v113, v146, v113, vcc
	v_lshlrev_b32_e32 v123, 2, v113
	ds_bpermute_b32 v115, v123, v114
	v_cvt_pk_bf16_f32 v113, v124, v125
	global_store_dwordx2 v[130:131], v[112:113], off offset:96
	v_lshl_add_u64 v[112:113], v[140:141], 2, s[22:23]
	s_and_saveexec_b64 s[86:87], s[6:7]
	s_cbranch_execz .LBB0_453
	s_waitcnt lgkmcnt(0)
	v_add_f32_e32 v116, v114, v115
	v_lshl_add_u64 v[114:115], v[112:113], 0, v[128:129]
	global_atomic_add_f32 v[114:115], v116, off
; template <int EPI, int NM, bool SWAP>
; DEVI void gemm_epilogue(const Params& p, f32x4 (&acc)[NM][4], const int R0, const int C0, const float* rsw, const EpiArgs& ea) {
;     ...
;     for (int m = 0; m < NM; ++m) {
;       u32x2 rn[4];
;       if (m + 1 < NM) {
; #pragma unroll
;         for (int n = 0; n < 4; ++n) rn[n] = *reinterpret_cast<const u32x2*>(abase + (size_t)ROFF(m + 1) * DM + n * 16);
;       }
;       __builtin_amdgcn_sched_barrier(0);
;       float s = 0.f;
; #pragma unroll
;       for (int n = 0; n < 4; ++n) {
;         f32x4 h = acc[m][n];
;         h[0] += __uint_as_float(rc[n][0] << 16); h[1] += __uint_as_float(rc[n][0] & 0xffff0000u);
;         h[2] += __uint_as_float(rc[n][1] << 16); h[3] += __uint_as_float(rc[n][1] & 0xffff0000u);
;         *reinterpret_cast<u32x2*>(abase + (size_t)ROFF(m) * DM + n * 16) = u32x2{cvtpk(h[0], h[1]), cvtpk(h[2], h[3])};
;         s += h[0] * h[0] + h[1] * h[1] + h[2] * h[2] + h[3] * h[3];
;       }
;       s += __shfl_xor(s, 16); s += __shfl_xor(s, 32);
;       if (fq == 0) atomicAdd(ea.ss_next + R0 + ROFF(m) + fr, s);
;       __builtin_amdgcn_sched_barrier(0);
;       if (m + 1 < NM) {
; #pragma unroll
;         for (int n = 0; n < 4; ++n) rc[n] = rn[n];
;       }
;     }
.LBB0_453:
	s_or_b64 exec, exec, s[86:87]
	s_mov_b64 s[16:17], 0x8000
	v_lshl_add_u64 v[124:125], v[130:131], 0, s[16:17]
	s_mov_b64 s[16:17], 0x8020
	v_lshl_add_u64 v[126:127], v[130:131], 0, s[16:17]
	s_mov_b64 s[16:17], 0x8040
	v_lshl_add_u64 v[140:141], v[130:131], 0, s[16:17]
	s_mov_b64 s[16:17], 0x8060
	v_lshl_add_u64 v[142:143], v[130:131], 0, s[16:17]
	v_add_co_u32_e32 v114, vcc, 0x10000, v130
	s_waitcnt lgkmcnt(0)
	s_nop 0
	v_addc_co_u32_e32 v115, vcc, 0, v131, vcc
	s_nop 0
	s_waitcnt vmcnt(28)
	v_lshlrev_b32_e32 v144, 16, v138
	v_add_f32_e32 v144, v108, v144
	v_and_b32_e32 v108, 0xffff0000, v138
	v_add_f32_e32 v138, v109, v108
	v_lshlrev_b32_e32 v108, 16, v139
	v_add_f32_e32 v110, v110, v108
	v_and_b32_e32 v108, 0xffff0000, v139
	v_add_f32_e32 v111, v111, v108
	v_cvt_pk_bf16_f32 v108, v144, v138
	v_cvt_pk_bf16_f32 v109, v110, v111
	global_store_dwordx2 v[124:125], v[108:109], off
	v_lshlrev_b32_e32 v109, 16, v136
	v_add_f32_e32 v109, v100, v109
	v_and_b32_e32 v100, 0xffff0000, v136
	v_add_f32_e32 v101, v101, v100
	v_lshlrev_b32_e32 v100, 16, v137
	v_add_f32_e32 v102, v102, v100
	v_and_b32_e32 v100, 0xffff0000, v137
	v_mul_f32_e32 v108, v138, v138
	v_add_f32_e32 v103, v103, v100
	v_cvt_pk_bf16_f32 v100, v109, v101
	v_mul_f32_e32 v101, v101, v101
	v_fmac_f32_e32 v108, v144, v144
	v_fmac_f32_e32 v101, v109, v109
	v_fmac_f32_e32 v108, v110, v110
	v_fmac_f32_e32 v101, v102, v102
	v_fmac_f32_e32 v108, v111, v111
	v_fmac_f32_e32 v101, v103, v103
	v_add_f32_e32 v101, v108, v101
	v_lshlrev_b32_e32 v108, 16, v134
	v_add_f32_e32 v104, v104, v108
	v_and_b32_e32 v108, 0xffff0000, v134
	v_add_f32_e32 v105, v105, v108
	v_lshlrev_b32_e32 v108, 16, v135
	v_add_f32_e32 v106, v106, v108
	v_and_b32_e32 v108, 0xffff0000, v135
	v_add_f32_e32 v107, v107, v108
	v_mul_f32_e32 v108, v105, v105
	v_fmac_f32_e32 v108, v104, v104
	v_fmac_f32_e32 v108, v106, v106
	v_fmac_f32_e32 v108, v107, v107
	v_add_f32_e32 v101, v101, v108
	v_lshlrev_b32_e32 v108, 16, v132
	v_add_f32_e32 v108, v96, v108
	v_and_b32_e32 v96, 0xffff0000, v132
	v_add_f32_e32 v109, v97, v96
	v_lshlrev_b32_e32 v96, 16, v133
	v_add_f32_e32 v110, v98, v96
	v_and_b32_e32 v96, 0xffff0000, v133
	v_add_f32_e32 v111, v99, v96
	v_mul_f32_e32 v96, v109, v109
	v_fmac_f32_e32 v96, v108, v108
	v_fmac_f32_e32 v96, v110, v110
	v_fmac_f32_e32 v96, v111, v111
	v_add_f32_e32 v96, v101, v96
	ds_bpermute_b32 v97, v122, v96
	v_cvt_pk_bf16_f32 v101, v102, v103
	global_store_dwordx2 v[126:127], v[100:101], off
	v_cvt_pk_bf16_f32 v98, v104, v105
	v_cvt_pk_bf16_f32 v99, v106, v107
	s_waitcnt lgkmcnt(0)
	v_add_f32_e32 v96, v96, v97
	ds_bpermute_b32 v97, v123, v96
	global_store_dwordx2 v[140:141], v[98:99], off
	v_cvt_pk_bf16_f32 v98, v108, v109
	v_cvt_pk_bf16_f32 v99, v110, v111
	global_store_dwordx2 v[142:143], v[98:99], off
	s_and_saveexec_b64 s[86:87], s[6:7]
	s_cbranch_execz .LBB0_455
	s_waitcnt lgkmcnt(0)
	v_add_f32_e32 v98, v96, v97
	v_lshl_add_u64 v[96:97], v[112:113], 0, v[128:129]
	global_atomic_add_f32 v[96:97], v98, off offset:64
.LBB0_455:
	s_or_b64 exec, exec, s[86:87]
	s_mov_b64 s[16:17], 0x10000
	v_lshl_add_u64 v[104:105], v[130:131], 0, s[16:17]
	s_mov_b64 s[16:17], 0x10020
	v_lshl_add_u64 v[106:107], v[130:131], 0, s[16:17]
	s_mov_b64 s[16:17], 0x10040
	v_lshl_add_u64 v[108:109], v[130:131], 0, s[16:17]
	s_mov_b64 s[16:17], 0x10060
	v_lshl_add_u64 v[110:111], v[130:131], 0, s[16:17]
	v_add_co_u32_e32 v96, vcc, 0x18000, v130
	s_waitcnt lgkmcnt(0)
	s_nop 0
	v_addc_co_u32_e32 v97, vcc, 0, v131, vcc
	s_nop 0
	s_waitcnt vmcnt(28)
	v_lshlrev_b32_e32 v124, 16, v176
	v_add_f32_e32 v124, v92, v124
	v_and_b32_e32 v92, 0xffff0000, v176
	v_add_f32_e32 v120, v93, v92
	v_lshlrev_b32_e32 v92, 16, v177
	v_add_f32_e32 v94, v94, v92
	v_and_b32_e32 v92, 0xffff0000, v177
	v_add_f32_e32 v95, v95, v92
	v_cvt_pk_bf16_f32 v92, v124, v120
	v_cvt_pk_bf16_f32 v93, v94, v95
	global_store_dwordx2 v[104:105], v[92:93], off
	v_lshlrev_b32_e32 v93, 16, v178
	v_add_f32_e32 v93, v84, v93
	v_and_b32_e32 v84, 0xffff0000, v178
	v_add_f32_e32 v85, v85, v84
	v_lshlrev_b32_e32 v84, 16, v179
	v_add_f32_e32 v86, v86, v84
	v_and_b32_e32 v84, 0xffff0000, v179
	v_mul_f32_e32 v92, v120, v120
	v_add_f32_e32 v87, v87, v84
	v_cvt_pk_bf16_f32 v84, v93, v85
	v_mul_f32_e32 v85, v85, v85
	v_fmac_f32_e32 v92, v124, v124
	v_fmac_f32_e32 v85, v93, v93
	v_fmac_f32_e32 v92, v94, v94
	v_fmac_f32_e32 v85, v86, v86
	v_fmac_f32_e32 v92, v95, v95
	v_fmac_f32_e32 v85, v87, v87
	v_add_f32_e32 v85, v92, v85
	v_lshlrev_b32_e32 v92, 16, v180
	v_add_f32_e32 v88, v88, v92
	v_and_b32_e32 v92, 0xffff0000, v180
	v_add_f32_e32 v89, v89, v92
	v_lshlrev_b32_e32 v92, 16, v181
	v_add_f32_e32 v90, v90, v92
	v_and_b32_e32 v92, 0xffff0000, v181
	v_add_f32_e32 v91, v91, v92
	v_mul_f32_e32 v92, v89, v89
	v_fmac_f32_e32 v92, v88, v88
	v_fmac_f32_e32 v92, v90, v90
	v_fmac_f32_e32 v92, v91, v91
	v_add_f32_e32 v85, v85, v92
	v_lshlrev_b32_e32 v92, 16, v182
	v_add_f32_e32 v92, v80, v92
	v_and_b32_e32 v80, 0xffff0000, v182
	v_add_f32_e32 v93, v81, v80
	v_lshlrev_b32_e32 v80, 16, v183
	v_add_f32_e32 v94, v82, v80
	v_and_b32_e32 v80, 0xffff0000, v183
	v_add_f32_e32 v95, v83, v80
	v_mul_f32_e32 v80, v93, v93
	v_fmac_f32_e32 v80, v92, v92
	v_fmac_f32_e32 v80, v94, v94
	v_fmac_f32_e32 v80, v95, v95
	v_add_f32_e32 v80, v85, v80
	ds_bpermute_b32 v81, v122, v80
	v_cvt_pk_bf16_f32 v85, v86, v87
	global_store_dwordx2 v[106:107], v[84:85], off
	v_cvt_pk_bf16_f32 v82, v88, v89
	v_cvt_pk_bf16_f32 v83, v90, v91
	s_waitcnt lgkmcnt(0)
	v_add_f32_e32 v80, v80, v81
	ds_bpermute_b32 v81, v123, v80
	global_store_dwordx2 v[108:109], v[82:83], off
	v_cvt_pk_bf16_f32 v82, v92, v93
	v_cvt_pk_bf16_f32 v83, v94, v95
	global_store_dwordx2 v[110:111], v[82:83], off
	s_and_saveexec_b64 s[86:87], s[6:7]
	s_cbranch_execz .LBB0_457
	s_waitcnt lgkmcnt(0)
	v_add_f32_e32 v82, v80, v81
	v_lshl_add_u64 v[80:81], v[112:113], 0, v[128:129]
	global_atomic_add_f32 v[80:81], v82, off offset:128
; template <int EPI, int NM, bool SWAP>
; DEVI void gemm_epilogue(const Params& p, f32x4 (&acc)[NM][4], const int R0, const int C0, const float* rsw, const EpiArgs& ea) {
;     ...
;     for (int m = 0; m < NM; ++m) {
;       u32x2 rn[4];
;       if (m + 1 < NM) {
; #pragma unroll
;         for (int n = 0; n < 4; ++n) rn[n] = *reinterpret_cast<const u32x2*>(abase + (size_t)ROFF(m + 1) * DM + n * 16);
;       }
;       __builtin_amdgcn_sched_barrier(0);
;       float s = 0.f;
; #pragma unroll
;       for (int n = 0; n < 4; ++n) {
;         f32x4 h = acc[m][n];
;         h[0] += __uint_as_float(rc[n][0] << 16); h[1] += __uint_as_float(rc[n][0] & 0xffff0000u);
;         h[2] += __uint_as_float(rc[n][1] << 16); h[3] += __uint_as_float(rc[n][1] & 0xffff0000u);
;         *reinterpret_cast<u32x2*>(abase + (size_t)ROFF(m) * DM + n * 16) = u32x2{cvtpk(h[0], h[1]), cvtpk(h[2], h[3])};
;         s += h[0] * h[0] + h[1] * h[1] + h[2] * h[2] + h[3] * h[3];
;       }
;       s += __shfl_xor(s, 16); s += __shfl_xor(s, 32);
;       if (fq == 0) atomicAdd(ea.ss_next + R0 + ROFF(m) + fr, s);
;       __builtin_amdgcn_sched_barrier(0);
;       if (m + 1 < NM) {
; #pragma unroll
;         for (int n = 0; n < 4; ++n) rc[n] = rn[n];
;       }
;     }
.LBB0_457:
	s_or_b64 exec, exec, s[86:87]
	s_mov_b64 s[16:17], 0x18000
	v_lshl_add_u64 v[88:89], v[130:131], 0, s[16:17]
	s_mov_b64 s[16:17], 0x18020
	v_lshl_add_u64 v[90:91], v[130:131], 0, s[16:17]
	s_mov_b64 s[16:17], 0x18040
	v_lshl_add_u64 v[92:93], v[130:131], 0, s[16:17]
	s_mov_b64 s[16:17], 0x18060
	v_lshl_add_u64 v[94:95], v[130:131], 0, s[16:17]
	v_add_co_u32_e32 v80, vcc, 0x40000, v130
	s_waitcnt lgkmcnt(0)
	s_nop 0
	v_addc_co_u32_e32 v81, vcc, 0, v131, vcc
	s_nop 0
	s_waitcnt vmcnt(28)
	v_lshlrev_b32_e32 v104, 16, v184
	v_add_f32_e32 v104, v76, v104
	v_and_b32_e32 v76, 0xffff0000, v184
	v_add_f32_e32 v102, v77, v76
	v_lshlrev_b32_e32 v76, 16, v185
	v_add_f32_e32 v78, v78, v76
	v_and_b32_e32 v76, 0xffff0000, v185
	v_add_f32_e32 v79, v79, v76
	v_cvt_pk_bf16_f32 v76, v104, v102
	v_cvt_pk_bf16_f32 v77, v78, v79
	global_store_dwordx2 v[88:89], v[76:77], off
	v_lshlrev_b32_e32 v77, 16, v186
	v_add_f32_e32 v77, v68, v77
	v_and_b32_e32 v68, 0xffff0000, v186
	v_add_f32_e32 v69, v69, v68
	v_lshlrev_b32_e32 v68, 16, v187
	v_add_f32_e32 v70, v70, v68
	v_and_b32_e32 v68, 0xffff0000, v187
	v_mul_f32_e32 v76, v102, v102
	v_add_f32_e32 v71, v71, v68
	v_cvt_pk_bf16_f32 v68, v77, v69
	v_mul_f32_e32 v69, v69, v69
	v_fmac_f32_e32 v76, v104, v104
	v_fmac_f32_e32 v69, v77, v77
	v_fmac_f32_e32 v76, v78, v78
	v_fmac_f32_e32 v69, v70, v70
	v_fmac_f32_e32 v76, v79, v79
	v_fmac_f32_e32 v69, v71, v71
	v_add_f32_e32 v69, v76, v69
	v_lshlrev_b32_e32 v76, 16, v188
	v_add_f32_e32 v72, v72, v76
	v_and_b32_e32 v76, 0xffff0000, v188
	v_add_f32_e32 v73, v73, v76
	v_lshlrev_b32_e32 v76, 16, v189
	v_add_f32_e32 v74, v74, v76
	v_and_b32_e32 v76, 0xffff0000, v189
	v_add_f32_e32 v75, v75, v76
	v_mul_f32_e32 v76, v73, v73
	v_fmac_f32_e32 v76, v72, v72
	v_fmac_f32_e32 v76, v74, v74
	v_fmac_f32_e32 v76, v75, v75
	v_add_f32_e32 v69, v69, v76
	v_lshlrev_b32_e32 v76, 16, v190
	v_add_f32_e32 v76, v64, v76
	v_and_b32_e32 v64, 0xffff0000, v190
	v_add_f32_e32 v77, v65, v64
	v_lshlrev_b32_e32 v64, 16, v191
	v_add_f32_e32 v78, v66, v64
	v_and_b32_e32 v64, 0xffff0000, v191
	v_add_f32_e32 v79, v67, v64
	v_mul_f32_e32 v64, v77, v77
	v_fmac_f32_e32 v64, v76, v76
	v_fmac_f32_e32 v64, v78, v78
	v_fmac_f32_e32 v64, v79, v79
	v_add_f32_e32 v64, v69, v64
	ds_bpermute_b32 v65, v122, v64
	v_cvt_pk_bf16_f32 v69, v70, v71
	global_store_dwordx2 v[90:91], v[68:69], off
	v_cvt_pk_bf16_f32 v66, v72, v73
	v_cvt_pk_bf16_f32 v67, v74, v75
	s_waitcnt lgkmcnt(0)
	v_add_f32_e32 v64, v64, v65
	ds_bpermute_b32 v65, v123, v64
	global_store_dwordx2 v[92:93], v[66:67], off
	v_cvt_pk_bf16_f32 v66, v76, v77
	v_cvt_pk_bf16_f32 v67, v78, v79
	global_store_dwordx2 v[94:95], v[66:67], off
	s_and_saveexec_b64 s[86:87], s[6:7]
	s_cbranch_execz .LBB0_459
	s_waitcnt lgkmcnt(0)
	v_add_f32_e32 v66, v64, v65
	v_lshl_add_u64 v[64:65], v[112:113], 0, v[128:129]
	global_atomic_add_f32 v[64:65], v66, off offset:192
.LBB0_459:
	s_or_b64 exec, exec, s[86:87]
	s_mov_b64 s[16:17], 0x40000
	v_lshl_add_u64 v[72:73], v[130:131], 0, s[16:17]
	s_mov_b64 s[16:17], 0x40020
	v_lshl_add_u64 v[74:75], v[130:131], 0, s[16:17]
	s_mov_b64 s[16:17], 0x40040
	v_lshl_add_u64 v[76:77], v[130:131], 0, s[16:17]
	s_mov_b64 s[16:17], 0x40060
	v_lshl_add_u64 v[78:79], v[130:131], 0, s[16:17]
	v_add_co_u32_e32 v64, vcc, 0x48000, v130
	s_waitcnt lgkmcnt(0)
	s_nop 0
	v_addc_co_u32_e32 v65, vcc, 0, v131, vcc
	s_nop 0
	s_waitcnt vmcnt(28)
	v_lshlrev_b32_e32 v88, 16, v192
	v_add_f32_e32 v88, v60, v88
	v_and_b32_e32 v60, 0xffff0000, v192
	v_add_f32_e32 v86, v61, v60
	v_lshlrev_b32_e32 v60, 16, v193
	v_add_f32_e32 v62, v62, v60
	v_and_b32_e32 v60, 0xffff0000, v193
	v_add_f32_e32 v63, v63, v60
	v_cvt_pk_bf16_f32 v60, v88, v86
	v_cvt_pk_bf16_f32 v61, v62, v63
	global_store_dwordx2 v[72:73], v[60:61], off
	v_lshlrev_b32_e32 v61, 16, v194
	v_add_f32_e32 v61, v56, v61
	v_and_b32_e32 v56, 0xffff0000, v194
	v_add_f32_e32 v57, v57, v56
	v_lshlrev_b32_e32 v56, 16, v195
	v_add_f32_e32 v58, v58, v56
	v_and_b32_e32 v56, 0xffff0000, v195
	v_mul_f32_e32 v60, v86, v86
	v_add_f32_e32 v59, v59, v56
	v_cvt_pk_bf16_f32 v56, v61, v57
	v_mul_f32_e32 v57, v57, v57
	v_fmac_f32_e32 v60, v88, v88
	v_fmac_f32_e32 v57, v61, v61
	v_fmac_f32_e32 v60, v62, v62
	v_fmac_f32_e32 v57, v58, v58
	v_fmac_f32_e32 v60, v63, v63
	v_fmac_f32_e32 v57, v59, v59
	v_add_f32_e32 v57, v60, v57
	v_lshlrev_b32_e32 v60, 16, v196
	v_add_f32_e32 v52, v52, v60
	v_and_b32_e32 v60, 0xffff0000, v196
	v_add_f32_e32 v53, v53, v60
	v_lshlrev_b32_e32 v60, 16, v197
	v_add_f32_e32 v54, v54, v60
	v_and_b32_e32 v60, 0xffff0000, v197
	v_add_f32_e32 v55, v55, v60
	v_mul_f32_e32 v60, v53, v53
	v_fmac_f32_e32 v60, v52, v52
	v_fmac_f32_e32 v60, v54, v54
	v_fmac_f32_e32 v60, v55, v55
	v_add_f32_e32 v57, v57, v60
	v_lshlrev_b32_e32 v60, 16, v198
	v_add_f32_e32 v60, v48, v60
	v_and_b32_e32 v48, 0xffff0000, v198
	v_add_f32_e32 v61, v49, v48
	v_lshlrev_b32_e32 v48, 16, v199
	v_add_f32_e32 v62, v50, v48
	v_and_b32_e32 v48, 0xffff0000, v199
	v_add_f32_e32 v63, v51, v48
	v_mul_f32_e32 v48, v61, v61
	v_fmac_f32_e32 v48, v60, v60
	v_fmac_f32_e32 v48, v62, v62
	v_fmac_f32_e32 v48, v63, v63
	v_add_f32_e32 v48, v57, v48
	ds_bpermute_b32 v49, v122, v48
	v_cvt_pk_bf16_f32 v57, v58, v59
	global_store_dwordx2 v[74:75], v[56:57], off
	v_cvt_pk_bf16_f32 v50, v52, v53
	v_cvt_pk_bf16_f32 v51, v54, v55
	s_waitcnt lgkmcnt(0)
	v_add_f32_e32 v48, v48, v49
	ds_bpermute_b32 v49, v123, v48
	global_store_dwordx2 v[76:77], v[50:51], off
	v_cvt_pk_bf16_f32 v50, v60, v61
	v_cvt_pk_bf16_f32 v51, v62, v63
	global_store_dwordx2 v[78:79], v[50:51], off
	s_and_saveexec_b64 s[86:87], s[6:7]
	s_cbranch_execz .LBB0_461
	s_waitcnt lgkmcnt(0)
	v_add_f32_e32 v50, v48, v49
	v_lshl_add_u64 v[48:49], v[112:113], 0, v[128:129]
	global_atomic_add_f32 v[48:49], v50, off offset:512
; template <int EPI, int NM, bool SWAP>
; DEVI void gemm_epilogue(const Params& p, f32x4 (&acc)[NM][4], const int R0, const int C0, const float* rsw, const EpiArgs& ea) {
;     ...
;     for (int m = 0; m < NM; ++m) {
;       u32x2 rn[4];
;       if (m + 1 < NM) {
; #pragma unroll
;         for (int n = 0; n < 4; ++n) rn[n] = *reinterpret_cast<const u32x2*>(abase + (size_t)ROFF(m + 1) * DM + n * 16);
;       }
;       __builtin_amdgcn_sched_barrier(0);
;       float s = 0.f;
; #pragma unroll
;       for (int n = 0; n < 4; ++n) {
;         f32x4 h = acc[m][n];
;         h[0] += __uint_as_float(rc[n][0] << 16); h[1] += __uint_as_float(rc[n][0] & 0xffff0000u);
;         h[2] += __uint_as_float(rc[n][1] << 16); h[3] += __uint_as_float(rc[n][1] & 0xffff0000u);
;         *reinterpret_cast<u32x2*>(abase + (size_t)ROFF(m) * DM + n * 16) = u32x2{cvtpk(h[0], h[1]), cvtpk(h[2], h[3])};
;         s += h[0] * h[0] + h[1] * h[1] + h[2] * h[2] + h[3] * h[3];
;       }
;       s += __shfl_xor(s, 16); s += __shfl_xor(s, 32);
;       if (fq == 0) atomicAdd(ea.ss_next + R0 + ROFF(m) + fr, s);
;       __builtin_amdgcn_sched_barrier(0);
;       if (m + 1 < NM) {
; #pragma unroll
;         for (int n = 0; n < 4; ++n) rc[n] = rn[n];
;       }
;     }
.LBB0_461:
	s_or_b64 exec, exec, s[86:87]
	s_mov_b64 s[16:17], 0x48000
	v_lshl_add_u64 v[56:57], v[130:131], 0, s[16:17]
	s_mov_b64 s[16:17], 0x48020
	v_lshl_add_u64 v[58:59], v[130:131], 0, s[16:17]
	s_mov_b64 s[16:17], 0x48040
	v_lshl_add_u64 v[60:61], v[130:131], 0, s[16:17]
	s_mov_b64 s[16:17], 0x48060
	v_lshl_add_u64 v[62:63], v[130:131], 0, s[16:17]
	v_add_co_u32_e32 v48, vcc, 0x50000, v130
	s_waitcnt lgkmcnt(0)
	s_nop 0
	v_addc_co_u32_e32 v49, vcc, 0, v131, vcc
	s_nop 0
	s_waitcnt vmcnt(28)
	v_lshlrev_b32_e32 v72, 16, v200
	v_add_f32_e32 v72, v44, v72
	v_and_b32_e32 v44, 0xffff0000, v200
	v_add_f32_e32 v70, v45, v44
	v_lshlrev_b32_e32 v44, 16, v201
	v_add_f32_e32 v46, v46, v44
	v_and_b32_e32 v44, 0xffff0000, v201
	v_add_f32_e32 v47, v47, v44
	v_cvt_pk_bf16_f32 v44, v72, v70
	v_cvt_pk_bf16_f32 v45, v46, v47
	global_store_dwordx2 v[56:57], v[44:45], off
	v_lshlrev_b32_e32 v45, 16, v202
	v_add_f32_e32 v45, v40, v45
	v_and_b32_e32 v40, 0xffff0000, v202
	v_add_f32_e32 v41, v41, v40
	v_lshlrev_b32_e32 v40, 16, v203
	v_add_f32_e32 v42, v42, v40
	v_and_b32_e32 v40, 0xffff0000, v203
	v_mul_f32_e32 v44, v70, v70
	v_add_f32_e32 v43, v43, v40
	v_cvt_pk_bf16_f32 v40, v45, v41
	v_mul_f32_e32 v41, v41, v41
	v_fmac_f32_e32 v44, v72, v72
	v_fmac_f32_e32 v41, v45, v45
	v_fmac_f32_e32 v44, v46, v46
	v_fmac_f32_e32 v41, v42, v42
	v_fmac_f32_e32 v44, v47, v47
	v_fmac_f32_e32 v41, v43, v43
	v_add_f32_e32 v41, v44, v41
	v_lshlrev_b32_e32 v44, 16, v204
	v_add_f32_e32 v36, v36, v44
	v_and_b32_e32 v44, 0xffff0000, v204
	v_add_f32_e32 v37, v37, v44
	v_lshlrev_b32_e32 v44, 16, v205
	v_add_f32_e32 v38, v38, v44
	v_and_b32_e32 v44, 0xffff0000, v205
	v_add_f32_e32 v39, v39, v44
	v_mul_f32_e32 v44, v37, v37
	v_fmac_f32_e32 v44, v36, v36
	v_fmac_f32_e32 v44, v38, v38
	v_fmac_f32_e32 v44, v39, v39
	v_add_f32_e32 v41, v41, v44
	v_lshlrev_b32_e32 v44, 16, v206
	v_add_f32_e32 v44, v32, v44
	v_and_b32_e32 v32, 0xffff0000, v206
	v_add_f32_e32 v45, v33, v32
	v_lshlrev_b32_e32 v32, 16, v207
	v_add_f32_e32 v46, v34, v32
	v_and_b32_e32 v32, 0xffff0000, v207
	v_add_f32_e32 v47, v35, v32
	v_mul_f32_e32 v32, v45, v45
	v_fmac_f32_e32 v32, v44, v44
	v_fmac_f32_e32 v32, v46, v46
	v_fmac_f32_e32 v32, v47, v47
	v_add_f32_e32 v32, v41, v32
	ds_bpermute_b32 v33, v122, v32
	v_cvt_pk_bf16_f32 v41, v42, v43
	global_store_dwordx2 v[58:59], v[40:41], off
	v_cvt_pk_bf16_f32 v34, v36, v37
	v_cvt_pk_bf16_f32 v35, v38, v39
	s_waitcnt lgkmcnt(0)
	v_add_f32_e32 v32, v32, v33
	ds_bpermute_b32 v33, v123, v32
	global_store_dwordx2 v[60:61], v[34:35], off
	v_cvt_pk_bf16_f32 v34, v44, v45
	v_cvt_pk_bf16_f32 v35, v46, v47
	global_store_dwordx2 v[62:63], v[34:35], off
	s_and_saveexec_b64 s[86:87], s[6:7]
	s_cbranch_execz .LBB0_463
	s_waitcnt lgkmcnt(0)
	v_add_f32_e32 v34, v32, v33
	v_lshl_add_u64 v[32:33], v[112:113], 0, v[128:129]
	global_atomic_add_f32 v[32:33], v34, off offset:576
; template <int EPI, int NM, bool SWAP>
; DEVI void gemm_epilogue(const Params& p, f32x4 (&acc)[NM][4], const int R0, const int C0, const float* rsw, const EpiArgs& ea) {
;     ...
;     for (int m = 0; m < NM; ++m) {
;       u32x2 rn[4];
;       if (m + 1 < NM) {
; #pragma unroll
;         for (int n = 0; n < 4; ++n) rn[n] = *reinterpret_cast<const u32x2*>(abase + (size_t)ROFF(m + 1) * DM + n * 16);
;       }
;       __builtin_amdgcn_sched_barrier(0);
;       float s = 0.f;
; #pragma unroll
;       for (int n = 0; n < 4; ++n) {
;         f32x4 h = acc[m][n];
;         h[0] += __uint_as_float(rc[n][0] << 16); h[1] += __uint_as_float(rc[n][0] & 0xffff0000u);
;         h[2] += __uint_as_float(rc[n][1] << 16); h[3] += __uint_as_float(rc[n][1] & 0xffff0000u);
;         *reinterpret_cast<u32x2*>(abase + (size_t)ROFF(m) * DM + n * 16) = u32x2{cvtpk(h[0], h[1]), cvtpk(h[2], h[3])};
;         s += h[0] * h[0] + h[1] * h[1] + h[2] * h[2] + h[3] * h[3];
;       }
;       s += __shfl_xor(s, 16); s += __shfl_xor(s, 32);
;       if (fq == 0) atomicAdd(ea.ss_next + R0 + ROFF(m) + fr, s);
;       __builtin_amdgcn_sched_barrier(0);
;       if (m + 1 < NM) {
; #pragma unroll
;         for (int n = 0; n < 4; ++n) rc[n] = rn[n];
;       }
;     }
.LBB0_463:
	s_or_b64 exec, exec, s[86:87]
	v_lshl_add_u64 v[40:41], v[130:131], 0, s[54:55]
	v_lshl_add_u64 v[42:43], v[130:131], 0, s[56:57]
	v_lshl_add_u64 v[44:45], v[130:131], 0, s[68:69]
	v_lshl_add_u64 v[46:47], v[130:131], 0, s[70:71]
	v_add_co_u32_e32 v32, vcc, 0x58000, v130
	s_waitcnt lgkmcnt(0)
	s_nop 0
	v_addc_co_u32_e32 v33, vcc, 0, v131, vcc
	s_nop 0
	s_waitcnt vmcnt(28)
	v_lshlrev_b32_e32 v56, 16, v208
	v_add_f32_e32 v56, v28, v56
	v_and_b32_e32 v28, 0xffff0000, v208
	v_add_f32_e32 v54, v29, v28
	v_lshlrev_b32_e32 v28, 16, v209
	v_add_f32_e32 v30, v30, v28
	v_and_b32_e32 v28, 0xffff0000, v209
	v_add_f32_e32 v31, v31, v28
	v_cvt_pk_bf16_f32 v28, v56, v54
	v_cvt_pk_bf16_f32 v29, v30, v31
	global_store_dwordx2 v[40:41], v[28:29], off
	v_lshlrev_b32_e32 v29, 16, v210
	v_add_f32_e32 v29, v24, v29
	v_and_b32_e32 v24, 0xffff0000, v210
	v_add_f32_e32 v25, v25, v24
	v_lshlrev_b32_e32 v24, 16, v211
	v_add_f32_e32 v26, v26, v24
	v_and_b32_e32 v24, 0xffff0000, v211
	v_mul_f32_e32 v28, v54, v54
	v_add_f32_e32 v27, v27, v24
	v_cvt_pk_bf16_f32 v24, v29, v25
	v_mul_f32_e32 v25, v25, v25
	v_fmac_f32_e32 v28, v56, v56
	v_fmac_f32_e32 v25, v29, v29
	v_fmac_f32_e32 v28, v30, v30
	v_fmac_f32_e32 v25, v26, v26
	v_fmac_f32_e32 v28, v31, v31
	v_fmac_f32_e32 v25, v27, v27
	v_add_f32_e32 v25, v28, v25
	v_lshlrev_b32_e32 v28, 16, v212
	v_add_f32_e32 v20, v20, v28
	v_and_b32_e32 v28, 0xffff0000, v212
	v_add_f32_e32 v21, v21, v28
	v_lshlrev_b32_e32 v28, 16, v213
	v_add_f32_e32 v22, v22, v28
	v_and_b32_e32 v28, 0xffff0000, v213
	v_add_f32_e32 v23, v23, v28
	v_mul_f32_e32 v28, v21, v21
	v_fmac_f32_e32 v28, v20, v20
	v_fmac_f32_e32 v28, v22, v22
	v_fmac_f32_e32 v28, v23, v23
	v_add_f32_e32 v25, v25, v28
	v_lshlrev_b32_e32 v28, 16, v214
	v_add_f32_e32 v28, v16, v28
	v_and_b32_e32 v16, 0xffff0000, v214
	v_add_f32_e32 v29, v17, v16
	v_lshlrev_b32_e32 v16, 16, v215
	v_add_f32_e32 v30, v18, v16
	v_and_b32_e32 v16, 0xffff0000, v215
	v_add_f32_e32 v31, v19, v16
	v_mul_f32_e32 v16, v29, v29
	v_fmac_f32_e32 v16, v28, v28
	v_fmac_f32_e32 v16, v30, v30
	v_fmac_f32_e32 v16, v31, v31
	v_add_f32_e32 v16, v25, v16
	ds_bpermute_b32 v17, v122, v16
	v_cvt_pk_bf16_f32 v25, v26, v27
	global_store_dwordx2 v[42:43], v[24:25], off
	v_cvt_pk_bf16_f32 v18, v20, v21
	v_cvt_pk_bf16_f32 v19, v22, v23
	s_waitcnt lgkmcnt(0)
	v_add_f32_e32 v16, v16, v17
	ds_bpermute_b32 v17, v123, v16
	global_store_dwordx2 v[44:45], v[18:19], off
	v_cvt_pk_bf16_f32 v18, v28, v29
	v_cvt_pk_bf16_f32 v19, v30, v31
	global_store_dwordx2 v[46:47], v[18:19], off
	s_and_saveexec_b64 s[86:87], s[6:7]
	s_cbranch_execz .LBB0_465
	s_waitcnt lgkmcnt(0)
	v_add_f32_e32 v18, v16, v17
	v_lshl_add_u64 v[16:17], v[112:113], 0, v[128:129]
	global_atomic_add_f32 v[16:17], v18, off offset:640
.LBB0_465:
	s_or_b64 exec, exec, s[86:87]
	s_waitcnt lgkmcnt(0)
	v_lshl_add_u64 v[16:17], v[130:131], 0, s[78:79]
	v_lshl_add_u64 v[18:19], v[130:131], 0, s[80:81]
	v_lshl_add_u64 v[20:21], v[130:131], 0, s[82:83]
	v_lshl_add_u64 v[22:23], v[130:131], 0, s[84:85]
	s_waitcnt vmcnt(28)
	v_lshlrev_b32_e32 v24, 16, v216
	v_add_f32_e32 v24, v12, v24
	v_and_b32_e32 v12, 0xffff0000, v216
	v_add_f32_e32 v25, v13, v12
	v_lshlrev_b32_e32 v12, 16, v217
	v_add_f32_e32 v14, v14, v12
	v_and_b32_e32 v12, 0xffff0000, v217
	v_add_f32_e32 v15, v15, v12
	v_cvt_pk_bf16_f32 v12, v24, v25
	v_cvt_pk_bf16_f32 v13, v14, v15
	global_store_dwordx2 v[16:17], v[12:13], off
	v_lshlrev_b32_e32 v13, 16, v224
	v_add_f32_e32 v13, v8, v13
	v_and_b32_e32 v8, 0xffff0000, v224
	v_add_f32_e32 v9, v9, v8
	v_lshlrev_b32_e32 v8, 16, v225
	v_add_f32_e32 v10, v10, v8
	v_and_b32_e32 v8, 0xffff0000, v225
	v_mul_f32_e32 v12, v25, v25
	v_add_f32_e32 v11, v11, v8
	v_cvt_pk_bf16_f32 v8, v13, v9
	v_mul_f32_e32 v9, v9, v9
	v_fmac_f32_e32 v12, v24, v24
	v_fmac_f32_e32 v9, v13, v13
	v_fmac_f32_e32 v12, v14, v14
	v_fmac_f32_e32 v9, v10, v10
	v_fmac_f32_e32 v12, v15, v15
	v_fmac_f32_e32 v9, v11, v11
	v_add_f32_e32 v9, v12, v9
	v_lshlrev_b32_e32 v12, 16, v226
	v_add_f32_e32 v4, v4, v12
	v_and_b32_e32 v12, 0xffff0000, v226
	v_add_f32_e32 v5, v5, v12
	v_lshlrev_b32_e32 v12, 16, v227
	v_add_f32_e32 v6, v6, v12
	v_and_b32_e32 v12, 0xffff0000, v227
	v_add_f32_e32 v7, v7, v12
	v_mul_f32_e32 v12, v5, v5
	v_fmac_f32_e32 v12, v4, v4
	v_fmac_f32_e32 v12, v6, v6
	v_fmac_f32_e32 v12, v7, v7
	v_add_f32_e32 v9, v9, v12
	v_lshlrev_b32_e32 v12, 16, v228
	v_add_f32_e32 v12, v0, v12
	v_and_b32_e32 v0, 0xffff0000, v228
	v_add_f32_e32 v13, v1, v0
	v_lshlrev_b32_e32 v0, 16, v229
	v_add_f32_e32 v14, v2, v0
	v_and_b32_e32 v0, 0xffff0000, v229
	v_add_f32_e32 v15, v3, v0
	v_mul_f32_e32 v0, v13, v13
	v_fmac_f32_e32 v0, v12, v12
	v_fmac_f32_e32 v0, v14, v14
	v_fmac_f32_e32 v0, v15, v15
	v_add_f32_e32 v0, v9, v0
	ds_bpermute_b32 v1, v122, v0
	v_cvt_pk_bf16_f32 v9, v10, v11
	global_store_dwordx2 v[18:19], v[8:9], off
	v_cvt_pk_bf16_f32 v2, v4, v5
	v_cvt_pk_bf16_f32 v3, v6, v7
	s_waitcnt lgkmcnt(0)
	v_add_f32_e32 v0, v0, v1
	ds_bpermute_b32 v1, v123, v0
	global_store_dwordx2 v[20:21], v[2:3], off
	v_cvt_pk_bf16_f32 v2, v12, v13
	v_cvt_pk_bf16_f32 v3, v14, v15
	global_store_dwordx2 v[22:23], v[2:3], off
	s_and_saveexec_b64 s[86:87], s[6:7]
	s_cbranch_execz .LBB0_440
	s_waitcnt lgkmcnt(0)
	v_add_f32_e32 v2, v0, v1
	v_lshl_add_u64 v[0:1], v[112:113], 0, v[128:129]
	global_atomic_add_f32 v[0:1], v2, off offset:704
	s_branch .LBB0_440

; template <int EPI, int NM, bool SWAP>
; DEVI void gemm_epilogue(const Params& p, f32x4 (&acc)[NM][4], const int R0, const int C0, const float* rsw, const EpiArgs& ea) {
;     ...
;   } else if constexpr (EPI == EPI_OUT) {
;     u16* abase = (u16*)(ws + OFF_ABF) + (size_t)(R0 + fr) * DM + C0 + fq * 4;
;     u32x2 rc[4];
; #pragma unroll
;     for (int n = 0; n < 4; ++n) rc[n] = *reinterpret_cast<const u32x2*>(abase + n * 16);
; #pragma unroll
;     for (int m = 0; m < NM; ++m) {
;       u32x2 rn[4];
;       if (m + 1 < NM) {
; #pragma unroll
;         for (int n = 0; n < 4; ++n) rn[n] = *reinterpret_cast<const u32x2*>(abase + (size_t)ROFF(m + 1) * DM + n * 16);
;       }
;       __builtin_amdgcn_sched_barrier(0);
;       float s = 0.f;
; #pragma unroll
;       for (int n = 0; n < 4; ++n) {
;         f32x4 h = acc[m][n];
;         h[0] += __uint_as_float(rc[n][0] << 16); h[1] += __uint_as_float(rc[n][0] & 0xffff0000u);
;         h[2] += __uint_as_float(rc[n][1] << 16); h[3] += __uint_as_float(rc[n][1] & 0xffff0000u);
;         *reinterpret_cast<u32x2*>(abase + (size_t)ROFF(m) * DM + n * 16) = u32x2{cvtpk(h[0], h[1]), cvtpk(h[2], h[3])};
;         s += h[0] * h[0] + h[1] * h[1] + h[2] * h[2] + h[3] * h[3];
;       }
;       s += __shfl_xor(s, 16); s += __shfl_xor(s, 32);
;       if (fq == 0) atomicAdd(ea.ss_next + R0 + ROFF(m) + fr, s);
.LBB0_583:
	s_or_b64 exec, exec, s[40:41]
	v_mov_b32_e32 v128, v222
	v_add_u32_e32 v140, s8, v144
	v_lshl_or_b32 v130, v143, 6, s92
	v_ashrrev_i32_e32 v131, 31, v130
	v_and_b32_e32 v143, 15, v128
	v_or_b32_e32 v132, v143, v140
	v_ashrrev_i32_e32 v133, 31, v132
	v_lshlrev_b64 v[132:133], 11, v[132:133]
	v_lshl_add_u64 v[132:133], s[38:39], 0, v[132:133]
	v_lshl_add_u64 v[130:131], v[130:131], 1, v[132:133]
	v_ashrrev_i32_e32 v132, 2, v128
	v_and_b32_e32 v132, -4, v132
	v_ashrrev_i32_e32 v133, 31, v132
	v_lshl_add_u64 v[130:131], v[132:133], 1, v[130:131]
	s_mov_b32 s8, 0x8000
	v_add_co_u32_e32 v132, vcc, s8, v130
	global_load_dwordx2 v[144:145], v[130:131], off
	global_load_dwordx2 v[146:147], v[130:131], off offset:32
	global_load_dwordx2 v[148:149], v[130:131], off offset:64
	global_load_dwordx2 v[150:151], v[130:131], off offset:96
	v_addc_co_u32_e32 v133, vcc, 0, v131, vcc
	global_load_dwordx2 v[138:139], v[132:133], off
	global_load_dwordx2 v[136:137], v[132:133], off offset:32
	global_load_dwordx2 v[134:135], v[132:133], off offset:64
	s_nop 0
	global_load_dwordx2 v[132:133], v[132:133], off offset:96
	s_mov_b64 s[100:101], 0x10000
	v_lshl_add_u64 v[170:171], v[130:131], 0, s[100:101]
	global_load_dwordx2 v[172:173], v[170:171], off
	global_load_dwordx2 v[174:175], v[170:171], off offset:32
	global_load_dwordx2 v[176:177], v[170:171], off offset:64
	global_load_dwordx2 v[178:179], v[170:171], off offset:96
	s_mov_b64 s[100:101], 0x18000
	v_lshl_add_u64 v[170:171], v[130:131], 0, s[100:101]
	global_load_dwordx2 v[180:181], v[170:171], off
	global_load_dwordx2 v[182:183], v[170:171], off offset:32
	global_load_dwordx2 v[184:185], v[170:171], off offset:64
	global_load_dwordx2 v[186:187], v[170:171], off offset:96
	s_mov_b64 s[100:101], 0x40000
	v_lshl_add_u64 v[170:171], v[130:131], 0, s[100:101]
	global_load_dwordx2 v[188:189], v[170:171], off
	global_load_dwordx2 v[190:191], v[170:171], off offset:32
	global_load_dwordx2 v[192:193], v[170:171], off offset:64
	global_load_dwordx2 v[194:195], v[170:171], off offset:96
	s_mov_b64 s[100:101], 0x48000
	v_lshl_add_u64 v[170:171], v[130:131], 0, s[100:101]
	global_load_dwordx2 v[196:197], v[170:171], off
	global_load_dwordx2 v[198:199], v[170:171], off offset:32
	global_load_dwordx2 v[200:201], v[170:171], off offset:64
	global_load_dwordx2 v[202:203], v[170:171], off offset:96
	s_mov_b64 s[100:101], 0x50000
	v_lshl_add_u64 v[170:171], v[130:131], 0, s[100:101]
	global_load_dwordx2 v[204:205], v[170:171], off
	global_load_dwordx2 v[206:207], v[170:171], off offset:32
	global_load_dwordx2 v[208:209], v[170:171], off offset:64
	global_load_dwordx2 v[210:211], v[170:171], off offset:96
	s_mov_b64 s[100:101], 0x58000
	v_lshl_add_u64 v[170:171], v[130:131], 0, s[100:101]
	global_load_dwordx2 v[212:213], v[170:171], off
	global_load_dwordx2 v[214:215], v[170:171], off offset:32
	global_load_dwordx2 v[216:217], v[170:171], off offset:64
	global_load_dwordx2 v[224:225], v[170:171], off offset:96
	v_cmp_gt_u32_e64 s[8:9], 16, v128
	v_ashrrev_i32_e32 v141, 31, v140
	s_waitcnt vmcnt(28)
	v_lshlrev_b32_e32 v128, 16, v144
	v_add_f32_e32 v128, v124, v128
	v_and_b32_e32 v124, 0xffff0000, v144
	v_add_f32_e32 v144, v125, v124
	v_lshlrev_b32_e32 v124, 16, v145
	v_add_f32_e32 v126, v126, v124
	v_and_b32_e32 v124, 0xffff0000, v145
	v_add_f32_e32 v127, v127, v124
	v_cvt_pk_bf16_f32 v124, v128, v144
	v_cvt_pk_bf16_f32 v125, v126, v127
	global_store_dwordx2 v[130:131], v[124:125], off
	v_mul_f32_e32 v124, v144, v144
	v_lshlrev_b32_e32 v125, 16, v146
	v_fmac_f32_e32 v124, v128, v128
	v_add_f32_e32 v125, v116, v125
	v_and_b32_e32 v116, 0xffff0000, v146
	v_fmac_f32_e32 v124, v126, v126
	v_add_f32_e32 v126, v117, v116
	v_lshlrev_b32_e32 v116, 16, v147
	v_add_f32_e32 v118, v118, v116
	v_and_b32_e32 v116, 0xffff0000, v147
	v_add_f32_e32 v119, v119, v116
	v_cvt_pk_bf16_f32 v116, v125, v126
	v_cvt_pk_bf16_f32 v117, v118, v119
	global_store_dwordx2 v[130:131], v[116:117], off offset:32
	v_mul_f32_e32 v116, v126, v126
	v_fmac_f32_e32 v116, v125, v125
	v_fmac_f32_e32 v116, v118, v118
	v_and_b32_e32 v118, 0xffff0000, v148
	v_lshlrev_b32_e32 v117, 16, v148
	v_add_f32_e32 v118, v121, v118
	v_fmac_f32_e32 v116, v119, v119
	v_add_f32_e32 v117, v120, v117
	v_lshlrev_b32_e32 v119, 16, v149
	v_mul_f32_e32 v121, v118, v118
	v_add_f32_e32 v119, v122, v119
	v_and_b32_e32 v120, 0xffff0000, v149
	v_fmac_f32_e32 v121, v117, v117
	v_fmac_f32_e32 v124, v127, v127
	v_add_f32_e32 v120, v123, v120
	v_fmac_f32_e32 v121, v119, v119
	v_add_f32_e32 v116, v124, v116
	v_fmac_f32_e32 v121, v120, v120
	v_add_f32_e32 v116, v116, v121
	v_lshlrev_b32_e32 v121, 16, v150
	v_add_f32_e32 v121, v112, v121
	v_and_b32_e32 v112, 0xffff0000, v150
	v_add_f32_e32 v123, v113, v112
	v_lshlrev_b32_e32 v112, 16, v151
	v_add_f32_e32 v124, v114, v112
	v_and_b32_e32 v112, 0xffff0000, v151
	v_add_f32_e32 v125, v115, v112
	v_mul_f32_e32 v112, v123, v123
	v_fmac_f32_e32 v112, v121, v121
	v_fmac_f32_e32 v112, v124, v124
	v_fmac_f32_e32 v112, v125, v125
	v_and_b32_e32 v113, 64, v142
	v_add_f32_e32 v114, v116, v112
	v_xor_b32_e32 v112, 16, v142
	v_add_u32_e32 v115, 64, v113
	v_cmp_lt_i32_e32 vcc, v112, v115
	v_lshlrev_b32_e32 v128, 2, v143
	s_nop 0
	v_cndmask_b32_e32 v112, v142, v112, vcc
	v_lshlrev_b32_e32 v122, 2, v112
	ds_bpermute_b32 v116, v122, v114
	v_cvt_pk_bf16_f32 v112, v117, v118
	v_cvt_pk_bf16_f32 v113, v119, v120
	global_store_dwordx2 v[130:131], v[112:113], off offset:64
	v_xor_b32_e32 v113, 32, v142
	v_cmp_lt_i32_e32 vcc, v113, v115
	v_cvt_pk_bf16_f32 v112, v121, v123
	s_waitcnt lgkmcnt(0)
	v_add_f32_e32 v114, v114, v116
	v_cndmask_b32_e32 v113, v142, v113, vcc
	v_lshlrev_b32_e32 v123, 2, v113
	ds_bpermute_b32 v115, v123, v114
	v_cvt_pk_bf16_f32 v113, v124, v125
	global_store_dwordx2 v[130:131], v[112:113], off offset:96
	v_lshl_add_u64 v[112:113], v[140:141], 2, s[10:11]
	s_and_saveexec_b64 s[92:93], s[8:9]
	s_cbranch_execz .LBB0_585
	s_waitcnt lgkmcnt(0)
	v_add_f32_e32 v116, v114, v115
	v_lshl_add_u64 v[114:115], v[112:113], 0, v[128:129]
	global_atomic_add_f32 v[114:115], v116, off
; template <int EPI, int NM, bool SWAP>
; DEVI void gemm_epilogue(const Params& p, f32x4 (&acc)[NM][4], const int R0, const int C0, const float* rsw, const EpiArgs& ea) {
;     ...
;     for (int m = 0; m < NM; ++m) {
;       u32x2 rn[4];
;       if (m + 1 < NM) {
; #pragma unroll
;         for (int n = 0; n < 4; ++n) rn[n] = *reinterpret_cast<const u32x2*>(abase + (size_t)ROFF(m + 1) * DM + n * 16);
;       }
;       __builtin_amdgcn_sched_barrier(0);
;       float s = 0.f;
; #pragma unroll
;       for (int n = 0; n < 4; ++n) {
;         f32x4 h = acc[m][n];
;         h[0] += __uint_as_float(rc[n][0] << 16); h[1] += __uint_as_float(rc[n][0] & 0xffff0000u);
;         h[2] += __uint_as_float(rc[n][1] << 16); h[3] += __uint_as_float(rc[n][1] & 0xffff0000u);
;         *reinterpret_cast<u32x2*>(abase + (size_t)ROFF(m) * DM + n * 16) = u32x2{cvtpk(h[0], h[1]), cvtpk(h[2], h[3])};
;         s += h[0] * h[0] + h[1] * h[1] + h[2] * h[2] + h[3] * h[3];
;       }
;       s += __shfl_xor(s, 16); s += __shfl_xor(s, 32);
;       if (fq == 0) atomicAdd(ea.ss_next + R0 + ROFF(m) + fr, s);
;       __builtin_amdgcn_sched_barrier(0);
;       if (m + 1 < NM) {
; #pragma unroll
;         for (int n = 0; n < 4; ++n) rc[n] = rn[n];
;       }
;     }
.LBB0_585:
	s_or_b64 exec, exec, s[92:93]
	s_mov_b64 s[40:41], 0x8000
	v_lshl_add_u64 v[124:125], v[130:131], 0, s[40:41]
	s_mov_b64 s[40:41], 0x8020
	v_lshl_add_u64 v[126:127], v[130:131], 0, s[40:41]
	s_mov_b64 s[40:41], 0x8040
	v_lshl_add_u64 v[140:141], v[130:131], 0, s[40:41]
	s_mov_b64 s[40:41], 0x8060
	v_lshl_add_u64 v[144:145], v[130:131], 0, s[40:41]
	v_add_co_u32_e32 v114, vcc, 0x10000, v130
	s_waitcnt lgkmcnt(0)
	s_nop 0
	v_addc_co_u32_e32 v115, vcc, 0, v131, vcc
	s_nop 0
	s_waitcnt vmcnt(28)
	v_lshlrev_b32_e32 v143, 16, v138
	v_add_f32_e32 v143, v108, v143
	v_and_b32_e32 v108, 0xffff0000, v138
	v_add_f32_e32 v138, v109, v108
	v_lshlrev_b32_e32 v108, 16, v139
	v_add_f32_e32 v110, v110, v108
	v_and_b32_e32 v108, 0xffff0000, v139
	v_add_f32_e32 v111, v111, v108
	v_cvt_pk_bf16_f32 v108, v143, v138
	v_cvt_pk_bf16_f32 v109, v110, v111
	global_store_dwordx2 v[124:125], v[108:109], off
	v_lshlrev_b32_e32 v109, 16, v136
	v_add_f32_e32 v109, v100, v109
	v_and_b32_e32 v100, 0xffff0000, v136
	v_add_f32_e32 v101, v101, v100
	v_lshlrev_b32_e32 v100, 16, v137
	v_add_f32_e32 v102, v102, v100
	v_and_b32_e32 v100, 0xffff0000, v137
	v_mul_f32_e32 v108, v138, v138
	v_add_f32_e32 v103, v103, v100
	v_cvt_pk_bf16_f32 v100, v109, v101
	v_mul_f32_e32 v101, v101, v101
	v_fmac_f32_e32 v108, v143, v143
	v_fmac_f32_e32 v101, v109, v109
	v_fmac_f32_e32 v108, v110, v110
	v_fmac_f32_e32 v101, v102, v102
	v_fmac_f32_e32 v108, v111, v111
	v_fmac_f32_e32 v101, v103, v103
	v_add_f32_e32 v101, v108, v101
	v_lshlrev_b32_e32 v108, 16, v134
	v_add_f32_e32 v104, v104, v108
	v_and_b32_e32 v108, 0xffff0000, v134
	v_add_f32_e32 v105, v105, v108
	v_lshlrev_b32_e32 v108, 16, v135
	v_add_f32_e32 v106, v106, v108
	v_and_b32_e32 v108, 0xffff0000, v135
	v_add_f32_e32 v107, v107, v108
	v_mul_f32_e32 v108, v105, v105
	v_fmac_f32_e32 v108, v104, v104
	v_fmac_f32_e32 v108, v106, v106
	v_fmac_f32_e32 v108, v107, v107
	v_add_f32_e32 v101, v101, v108
	v_lshlrev_b32_e32 v108, 16, v132
	v_add_f32_e32 v108, v96, v108
	v_and_b32_e32 v96, 0xffff0000, v132
	v_add_f32_e32 v109, v97, v96
	v_lshlrev_b32_e32 v96, 16, v133
	v_add_f32_e32 v110, v98, v96
	v_and_b32_e32 v96, 0xffff0000, v133
	v_add_f32_e32 v111, v99, v96
	v_mul_f32_e32 v96, v109, v109
	v_fmac_f32_e32 v96, v108, v108
	v_fmac_f32_e32 v96, v110, v110
	v_fmac_f32_e32 v96, v111, v111
	v_add_f32_e32 v96, v101, v96
	ds_bpermute_b32 v97, v122, v96
	v_cvt_pk_bf16_f32 v101, v102, v103
	global_store_dwordx2 v[126:127], v[100:101], off
	v_cvt_pk_bf16_f32 v98, v104, v105
	v_cvt_pk_bf16_f32 v99, v106, v107
	s_waitcnt lgkmcnt(0)
	v_add_f32_e32 v96, v96, v97
	ds_bpermute_b32 v97, v123, v96
	global_store_dwordx2 v[140:141], v[98:99], off
	v_cvt_pk_bf16_f32 v98, v108, v109
	v_cvt_pk_bf16_f32 v99, v110, v111
	global_store_dwordx2 v[144:145], v[98:99], off
	s_and_saveexec_b64 s[92:93], s[8:9]
	s_cbranch_execz .LBB0_587
	s_waitcnt lgkmcnt(0)
	v_add_f32_e32 v98, v96, v97
	v_lshl_add_u64 v[96:97], v[112:113], 0, v[128:129]
	global_atomic_add_f32 v[96:97], v98, off offset:64
.LBB0_587:
	s_or_b64 exec, exec, s[92:93]
	s_mov_b64 s[40:41], 0x10000
	v_lshl_add_u64 v[104:105], v[130:131], 0, s[40:41]
	s_mov_b64 s[40:41], 0x10020
	v_lshl_add_u64 v[106:107], v[130:131], 0, s[40:41]
	s_mov_b64 s[40:41], 0x10040
	v_lshl_add_u64 v[108:109], v[130:131], 0, s[40:41]
	s_mov_b64 s[40:41], 0x10060
	v_lshl_add_u64 v[110:111], v[130:131], 0, s[40:41]
	v_add_co_u32_e32 v96, vcc, 0x18000, v130
	s_waitcnt lgkmcnt(0)
	s_nop 0
	v_addc_co_u32_e32 v97, vcc, 0, v131, vcc
	s_nop 0
	s_waitcnt vmcnt(28)
	v_lshlrev_b32_e32 v124, 16, v172
	v_add_f32_e32 v124, v92, v124
	v_and_b32_e32 v92, 0xffff0000, v172
	v_add_f32_e32 v120, v93, v92
	v_lshlrev_b32_e32 v92, 16, v173
	v_add_f32_e32 v94, v94, v92
	v_and_b32_e32 v92, 0xffff0000, v173
	v_add_f32_e32 v95, v95, v92
	v_cvt_pk_bf16_f32 v92, v124, v120
	v_cvt_pk_bf16_f32 v93, v94, v95
	global_store_dwordx2 v[104:105], v[92:93], off
	v_lshlrev_b32_e32 v93, 16, v174
	v_add_f32_e32 v93, v84, v93
	v_and_b32_e32 v84, 0xffff0000, v174
	v_add_f32_e32 v85, v85, v84
	v_lshlrev_b32_e32 v84, 16, v175
	v_add_f32_e32 v86, v86, v84
	v_and_b32_e32 v84, 0xffff0000, v175
	v_mul_f32_e32 v92, v120, v120
	v_add_f32_e32 v87, v87, v84
	v_cvt_pk_bf16_f32 v84, v93, v85
	v_mul_f32_e32 v85, v85, v85
	v_fmac_f32_e32 v92, v124, v124
	v_fmac_f32_e32 v85, v93, v93
	v_fmac_f32_e32 v92, v94, v94
	v_fmac_f32_e32 v85, v86, v86
	v_fmac_f32_e32 v92, v95, v95
	v_fmac_f32_e32 v85, v87, v87
	v_add_f32_e32 v85, v92, v85
	v_lshlrev_b32_e32 v92, 16, v176
	v_add_f32_e32 v88, v88, v92
	v_and_b32_e32 v92, 0xffff0000, v176
	v_add_f32_e32 v89, v89, v92
	v_lshlrev_b32_e32 v92, 16, v177
	v_add_f32_e32 v90, v90, v92
	v_and_b32_e32 v92, 0xffff0000, v177
	v_add_f32_e32 v91, v91, v92
	v_mul_f32_e32 v92, v89, v89
	v_fmac_f32_e32 v92, v88, v88
	v_fmac_f32_e32 v92, v90, v90
	v_fmac_f32_e32 v92, v91, v91
	v_add_f32_e32 v85, v85, v92
	v_lshlrev_b32_e32 v92, 16, v178
	v_add_f32_e32 v92, v80, v92
	v_and_b32_e32 v80, 0xffff0000, v178
	v_add_f32_e32 v93, v81, v80
	v_lshlrev_b32_e32 v80, 16, v179
	v_add_f32_e32 v94, v82, v80
	v_and_b32_e32 v80, 0xffff0000, v179
	v_add_f32_e32 v95, v83, v80
	v_mul_f32_e32 v80, v93, v93
	v_fmac_f32_e32 v80, v92, v92
	v_fmac_f32_e32 v80, v94, v94
	v_fmac_f32_e32 v80, v95, v95
	v_add_f32_e32 v80, v85, v80
	ds_bpermute_b32 v81, v122, v80
	v_cvt_pk_bf16_f32 v85, v86, v87
	global_store_dwordx2 v[106:107], v[84:85], off
	v_cvt_pk_bf16_f32 v82, v88, v89
	v_cvt_pk_bf16_f32 v83, v90, v91
	s_waitcnt lgkmcnt(0)
	v_add_f32_e32 v80, v80, v81
	ds_bpermute_b32 v81, v123, v80
	global_store_dwordx2 v[108:109], v[82:83], off
	v_cvt_pk_bf16_f32 v82, v92, v93
	v_cvt_pk_bf16_f32 v83, v94, v95
	global_store_dwordx2 v[110:111], v[82:83], off
	s_and_saveexec_b64 s[92:93], s[8:9]
	s_cbranch_execz .LBB0_589
	s_waitcnt lgkmcnt(0)
	v_add_f32_e32 v82, v80, v81
	v_lshl_add_u64 v[80:81], v[112:113], 0, v[128:129]
	global_atomic_add_f32 v[80:81], v82, off offset:128
; template <int EPI, int NM, bool SWAP>
; DEVI void gemm_epilogue(const Params& p, f32x4 (&acc)[NM][4], const int R0, const int C0, const float* rsw, const EpiArgs& ea) {
;     ...
;     for (int m = 0; m < NM; ++m) {
;       u32x2 rn[4];
;       if (m + 1 < NM) {
; #pragma unroll
;         for (int n = 0; n < 4; ++n) rn[n] = *reinterpret_cast<const u32x2*>(abase + (size_t)ROFF(m + 1) * DM + n * 16);
;       }
;       __builtin_amdgcn_sched_barrier(0);
;       float s = 0.f;
; #pragma unroll
;       for (int n = 0; n < 4; ++n) {
;         f32x4 h = acc[m][n];
;         h[0] += __uint_as_float(rc[n][0] << 16); h[1] += __uint_as_float(rc[n][0] & 0xffff0000u);
;         h[2] += __uint_as_float(rc[n][1] << 16); h[3] += __uint_as_float(rc[n][1] & 0xffff0000u);
;         *reinterpret_cast<u32x2*>(abase + (size_t)ROFF(m) * DM + n * 16) = u32x2{cvtpk(h[0], h[1]), cvtpk(h[2], h[3])};
;         s += h[0] * h[0] + h[1] * h[1] + h[2] * h[2] + h[3] * h[3];
;       }
;       s += __shfl_xor(s, 16); s += __shfl_xor(s, 32);
;       if (fq == 0) atomicAdd(ea.ss_next + R0 + ROFF(m) + fr, s);
;       __builtin_amdgcn_sched_barrier(0);
;       if (m + 1 < NM) {
; #pragma unroll
;         for (int n = 0; n < 4; ++n) rc[n] = rn[n];
;       }
;     }
.LBB0_589:
	s_or_b64 exec, exec, s[92:93]
	s_mov_b64 s[40:41], 0x18000
	v_lshl_add_u64 v[88:89], v[130:131], 0, s[40:41]
	s_mov_b64 s[40:41], 0x18020
	v_lshl_add_u64 v[90:91], v[130:131], 0, s[40:41]
	v_lshl_add_u64 v[92:93], v[130:131], 0, s[50:51]
	v_lshl_add_u64 v[94:95], v[130:131], 0, s[52:53]
	v_add_co_u32_e32 v80, vcc, 0x40000, v130
	s_waitcnt lgkmcnt(0)
	s_nop 0
	v_addc_co_u32_e32 v81, vcc, 0, v131, vcc
	s_nop 0
	s_waitcnt vmcnt(28)
	v_lshlrev_b32_e32 v104, 16, v180
	v_add_f32_e32 v104, v76, v104
	v_and_b32_e32 v76, 0xffff0000, v180
	v_add_f32_e32 v102, v77, v76
	v_lshlrev_b32_e32 v76, 16, v181
	v_add_f32_e32 v78, v78, v76
	v_and_b32_e32 v76, 0xffff0000, v181
	v_add_f32_e32 v79, v79, v76
	v_cvt_pk_bf16_f32 v76, v104, v102
	v_cvt_pk_bf16_f32 v77, v78, v79
	global_store_dwordx2 v[88:89], v[76:77], off
	v_lshlrev_b32_e32 v77, 16, v182
	v_add_f32_e32 v77, v68, v77
	v_and_b32_e32 v68, 0xffff0000, v182
	v_add_f32_e32 v69, v69, v68
	v_lshlrev_b32_e32 v68, 16, v183
	v_add_f32_e32 v70, v70, v68
	v_and_b32_e32 v68, 0xffff0000, v183
	v_mul_f32_e32 v76, v102, v102
	v_add_f32_e32 v71, v71, v68
	v_cvt_pk_bf16_f32 v68, v77, v69
	v_mul_f32_e32 v69, v69, v69
	v_fmac_f32_e32 v76, v104, v104
	v_fmac_f32_e32 v69, v77, v77
	v_fmac_f32_e32 v76, v78, v78
	v_fmac_f32_e32 v69, v70, v70
	v_fmac_f32_e32 v76, v79, v79
	v_fmac_f32_e32 v69, v71, v71
	v_add_f32_e32 v69, v76, v69
	v_lshlrev_b32_e32 v76, 16, v184
	v_add_f32_e32 v72, v72, v76
	v_and_b32_e32 v76, 0xffff0000, v184
	v_add_f32_e32 v73, v73, v76
	v_lshlrev_b32_e32 v76, 16, v185
	v_add_f32_e32 v74, v74, v76
	v_and_b32_e32 v76, 0xffff0000, v185
	v_add_f32_e32 v75, v75, v76
	v_mul_f32_e32 v76, v73, v73
	v_fmac_f32_e32 v76, v72, v72
	v_fmac_f32_e32 v76, v74, v74
	v_fmac_f32_e32 v76, v75, v75
	v_add_f32_e32 v69, v69, v76
	v_lshlrev_b32_e32 v76, 16, v186
	v_add_f32_e32 v76, v64, v76
	v_and_b32_e32 v64, 0xffff0000, v186
	v_add_f32_e32 v77, v65, v64
	v_lshlrev_b32_e32 v64, 16, v187
	v_add_f32_e32 v78, v66, v64
	v_and_b32_e32 v64, 0xffff0000, v187
	v_add_f32_e32 v79, v67, v64
	v_mul_f32_e32 v64, v77, v77
	v_fmac_f32_e32 v64, v76, v76
	v_fmac_f32_e32 v64, v78, v78
	v_fmac_f32_e32 v64, v79, v79
	v_add_f32_e32 v64, v69, v64
	ds_bpermute_b32 v65, v122, v64
	v_cvt_pk_bf16_f32 v69, v70, v71
	global_store_dwordx2 v[90:91], v[68:69], off
	v_cvt_pk_bf16_f32 v66, v72, v73
	v_cvt_pk_bf16_f32 v67, v74, v75
	s_waitcnt lgkmcnt(0)
	v_add_f32_e32 v64, v64, v65
	ds_bpermute_b32 v65, v123, v64
	global_store_dwordx2 v[92:93], v[66:67], off
	v_cvt_pk_bf16_f32 v66, v76, v77
	v_cvt_pk_bf16_f32 v67, v78, v79
	global_store_dwordx2 v[94:95], v[66:67], off
	s_and_saveexec_b64 s[92:93], s[8:9]
	s_cbranch_execz .LBB0_591
	s_waitcnt lgkmcnt(0)
	v_add_f32_e32 v66, v64, v65
	v_lshl_add_u64 v[64:65], v[112:113], 0, v[128:129]
	global_atomic_add_f32 v[64:65], v66, off offset:192
.LBB0_591:
	s_or_b64 exec, exec, s[92:93]
	v_lshl_add_u64 v[72:73], v[130:131], 0, s[54:55]
	v_lshl_add_u64 v[74:75], v[130:131], 0, s[56:57]
	v_lshl_add_u64 v[76:77], v[130:131], 0, s[58:59]
	v_lshl_add_u64 v[78:79], v[130:131], 0, s[60:61]
	v_add_co_u32_e32 v64, vcc, 0x48000, v130
	s_waitcnt lgkmcnt(0)
	s_nop 0
	v_addc_co_u32_e32 v65, vcc, 0, v131, vcc
	s_nop 0
	s_waitcnt vmcnt(28)
	v_lshlrev_b32_e32 v88, 16, v188
	v_add_f32_e32 v88, v60, v88
	v_and_b32_e32 v60, 0xffff0000, v188
	v_add_f32_e32 v86, v61, v60
	v_lshlrev_b32_e32 v60, 16, v189
	v_add_f32_e32 v62, v62, v60
	v_and_b32_e32 v60, 0xffff0000, v189
	v_add_f32_e32 v63, v63, v60
	v_cvt_pk_bf16_f32 v60, v88, v86
	v_cvt_pk_bf16_f32 v61, v62, v63
	global_store_dwordx2 v[72:73], v[60:61], off
	v_lshlrev_b32_e32 v61, 16, v190
	v_add_f32_e32 v61, v56, v61
	v_and_b32_e32 v56, 0xffff0000, v190
	v_add_f32_e32 v57, v57, v56
	v_lshlrev_b32_e32 v56, 16, v191
	v_add_f32_e32 v58, v58, v56
	v_and_b32_e32 v56, 0xffff0000, v191
	v_mul_f32_e32 v60, v86, v86
	v_add_f32_e32 v59, v59, v56
	v_cvt_pk_bf16_f32 v56, v61, v57
	v_mul_f32_e32 v57, v57, v57
	v_fmac_f32_e32 v60, v88, v88
	v_fmac_f32_e32 v57, v61, v61
	v_fmac_f32_e32 v60, v62, v62
	v_fmac_f32_e32 v57, v58, v58
	v_fmac_f32_e32 v60, v63, v63
	v_fmac_f32_e32 v57, v59, v59
	v_add_f32_e32 v57, v60, v57
	v_lshlrev_b32_e32 v60, 16, v192
	v_add_f32_e32 v52, v52, v60
	v_and_b32_e32 v60, 0xffff0000, v192
	v_add_f32_e32 v53, v53, v60
	v_lshlrev_b32_e32 v60, 16, v193
	v_add_f32_e32 v54, v54, v60
	v_and_b32_e32 v60, 0xffff0000, v193
	v_add_f32_e32 v55, v55, v60
	v_mul_f32_e32 v60, v53, v53
	v_fmac_f32_e32 v60, v52, v52
	v_fmac_f32_e32 v60, v54, v54
	v_fmac_f32_e32 v60, v55, v55
	v_add_f32_e32 v57, v57, v60
	v_lshlrev_b32_e32 v60, 16, v194
	v_add_f32_e32 v60, v48, v60
	v_and_b32_e32 v48, 0xffff0000, v194
	v_add_f32_e32 v61, v49, v48
	v_lshlrev_b32_e32 v48, 16, v195
	v_add_f32_e32 v62, v50, v48
	v_and_b32_e32 v48, 0xffff0000, v195
	v_add_f32_e32 v63, v51, v48
	v_mul_f32_e32 v48, v61, v61
	v_fmac_f32_e32 v48, v60, v60
	v_fmac_f32_e32 v48, v62, v62
	v_fmac_f32_e32 v48, v63, v63
	v_add_f32_e32 v48, v57, v48
	ds_bpermute_b32 v49, v122, v48
	v_cvt_pk_bf16_f32 v57, v58, v59
	global_store_dwordx2 v[74:75], v[56:57], off
	v_cvt_pk_bf16_f32 v50, v52, v53
	v_cvt_pk_bf16_f32 v51, v54, v55
	s_waitcnt lgkmcnt(0)
	v_add_f32_e32 v48, v48, v49
	ds_bpermute_b32 v49, v123, v48
	global_store_dwordx2 v[76:77], v[50:51], off
	v_cvt_pk_bf16_f32 v50, v60, v61
	v_cvt_pk_bf16_f32 v51, v62, v63
	global_store_dwordx2 v[78:79], v[50:51], off
	s_and_saveexec_b64 s[92:93], s[8:9]
	s_cbranch_execz .LBB0_593
	s_waitcnt lgkmcnt(0)
	v_add_f32_e32 v50, v48, v49
	v_lshl_add_u64 v[48:49], v[112:113], 0, v[128:129]
	global_atomic_add_f32 v[48:49], v50, off offset:512
; template <int EPI, int NM, bool SWAP>
; DEVI void gemm_epilogue(const Params& p, f32x4 (&acc)[NM][4], const int R0, const int C0, const float* rsw, const EpiArgs& ea) {
;     ...
;     for (int m = 0; m < NM; ++m) {
;       u32x2 rn[4];
;       if (m + 1 < NM) {
; #pragma unroll
;         for (int n = 0; n < 4; ++n) rn[n] = *reinterpret_cast<const u32x2*>(abase + (size_t)ROFF(m + 1) * DM + n * 16);
;       }
;       __builtin_amdgcn_sched_barrier(0);
;       float s = 0.f;
; #pragma unroll
;       for (int n = 0; n < 4; ++n) {
;         f32x4 h = acc[m][n];
;         h[0] += __uint_as_float(rc[n][0] << 16); h[1] += __uint_as_float(rc[n][0] & 0xffff0000u);
;         h[2] += __uint_as_float(rc[n][1] << 16); h[3] += __uint_as_float(rc[n][1] & 0xffff0000u);
;         *reinterpret_cast<u32x2*>(abase + (size_t)ROFF(m) * DM + n * 16) = u32x2{cvtpk(h[0], h[1]), cvtpk(h[2], h[3])};
;         s += h[0] * h[0] + h[1] * h[1] + h[2] * h[2] + h[3] * h[3];
;       }
;       s += __shfl_xor(s, 16); s += __shfl_xor(s, 32);
;       if (fq == 0) atomicAdd(ea.ss_next + R0 + ROFF(m) + fr, s);
;       __builtin_amdgcn_sched_barrier(0);
;       if (m + 1 < NM) {
; #pragma unroll
;         for (int n = 0; n < 4; ++n) rc[n] = rn[n];
;       }
;     }
.LBB0_593:
	s_or_b64 exec, exec, s[92:93]
	v_lshl_add_u64 v[56:57], v[130:131], 0, s[62:63]
	v_lshl_add_u64 v[58:59], v[130:131], 0, s[64:65]
	v_lshl_add_u64 v[60:61], v[130:131], 0, s[66:67]
	v_lshl_add_u64 v[62:63], v[130:131], 0, s[68:69]
	v_add_co_u32_e32 v48, vcc, 0x50000, v130
	s_waitcnt lgkmcnt(0)
	s_nop 0
	v_addc_co_u32_e32 v49, vcc, 0, v131, vcc
	s_nop 0
	s_waitcnt vmcnt(28)
	v_lshlrev_b32_e32 v72, 16, v196
	v_add_f32_e32 v72, v44, v72
	v_and_b32_e32 v44, 0xffff0000, v196
	v_add_f32_e32 v70, v45, v44
	v_lshlrev_b32_e32 v44, 16, v197
	v_add_f32_e32 v46, v46, v44
	v_and_b32_e32 v44, 0xffff0000, v197
	v_add_f32_e32 v47, v47, v44
	v_cvt_pk_bf16_f32 v44, v72, v70
	v_cvt_pk_bf16_f32 v45, v46, v47
	global_store_dwordx2 v[56:57], v[44:45], off
	v_lshlrev_b32_e32 v45, 16, v198
	v_add_f32_e32 v45, v40, v45
	v_and_b32_e32 v40, 0xffff0000, v198
	v_add_f32_e32 v41, v41, v40
	v_lshlrev_b32_e32 v40, 16, v199
	v_add_f32_e32 v42, v42, v40
	v_and_b32_e32 v40, 0xffff0000, v199
	v_mul_f32_e32 v44, v70, v70
	v_add_f32_e32 v43, v43, v40
	v_cvt_pk_bf16_f32 v40, v45, v41
	v_mul_f32_e32 v41, v41, v41
	v_fmac_f32_e32 v44, v72, v72
	v_fmac_f32_e32 v41, v45, v45
	v_fmac_f32_e32 v44, v46, v46
	v_fmac_f32_e32 v41, v42, v42
	v_fmac_f32_e32 v44, v47, v47
	v_fmac_f32_e32 v41, v43, v43
	v_add_f32_e32 v41, v44, v41
	v_lshlrev_b32_e32 v44, 16, v200
	v_add_f32_e32 v36, v36, v44
	v_and_b32_e32 v44, 0xffff0000, v200
	v_add_f32_e32 v37, v37, v44
	v_lshlrev_b32_e32 v44, 16, v201
	v_add_f32_e32 v38, v38, v44
	v_and_b32_e32 v44, 0xffff0000, v201
	v_add_f32_e32 v39, v39, v44
	v_mul_f32_e32 v44, v37, v37
	v_fmac_f32_e32 v44, v36, v36
	v_fmac_f32_e32 v44, v38, v38
	v_fmac_f32_e32 v44, v39, v39
	v_add_f32_e32 v41, v41, v44
	v_lshlrev_b32_e32 v44, 16, v202
	v_add_f32_e32 v44, v32, v44
	v_and_b32_e32 v32, 0xffff0000, v202
	v_add_f32_e32 v45, v33, v32
	v_lshlrev_b32_e32 v32, 16, v203
	v_add_f32_e32 v46, v34, v32
	v_and_b32_e32 v32, 0xffff0000, v203
	v_add_f32_e32 v47, v35, v32
	v_mul_f32_e32 v32, v45, v45
	v_fmac_f32_e32 v32, v44, v44
	v_fmac_f32_e32 v32, v46, v46
	v_fmac_f32_e32 v32, v47, v47
	v_add_f32_e32 v32, v41, v32
	ds_bpermute_b32 v33, v122, v32
	v_cvt_pk_bf16_f32 v41, v42, v43
	global_store_dwordx2 v[58:59], v[40:41], off
	v_cvt_pk_bf16_f32 v34, v36, v37
	v_cvt_pk_bf16_f32 v35, v38, v39
	s_waitcnt lgkmcnt(0)
	v_add_f32_e32 v32, v32, v33
	ds_bpermute_b32 v33, v123, v32
	global_store_dwordx2 v[60:61], v[34:35], off
	v_cvt_pk_bf16_f32 v34, v44, v45
	v_cvt_pk_bf16_f32 v35, v46, v47
	global_store_dwordx2 v[62:63], v[34:35], off
	s_and_saveexec_b64 s[92:93], s[8:9]
	s_cbranch_execz .LBB0_595
	s_waitcnt lgkmcnt(0)
	v_add_f32_e32 v34, v32, v33
	v_lshl_add_u64 v[32:33], v[112:113], 0, v[128:129]
	global_atomic_add_f32 v[32:33], v34, off offset:576
; template <int EPI, int NM, bool SWAP>
; DEVI void gemm_epilogue(const Params& p, f32x4 (&acc)[NM][4], const int R0, const int C0, const float* rsw, const EpiArgs& ea) {
;     ...
;     for (int m = 0; m < NM; ++m) {
;       u32x2 rn[4];
;       if (m + 1 < NM) {
; #pragma unroll
;         for (int n = 0; n < 4; ++n) rn[n] = *reinterpret_cast<const u32x2*>(abase + (size_t)ROFF(m + 1) * DM + n * 16);
;       }
;       __builtin_amdgcn_sched_barrier(0);
;       float s = 0.f;
; #pragma unroll
;       for (int n = 0; n < 4; ++n) {
;         f32x4 h = acc[m][n];
;         h[0] += __uint_as_float(rc[n][0] << 16); h[1] += __uint_as_float(rc[n][0] & 0xffff0000u);
;         h[2] += __uint_as_float(rc[n][1] << 16); h[3] += __uint_as_float(rc[n][1] & 0xffff0000u);
;         *reinterpret_cast<u32x2*>(abase + (size_t)ROFF(m) * DM + n * 16) = u32x2{cvtpk(h[0], h[1]), cvtpk(h[2], h[3])};
;         s += h[0] * h[0] + h[1] * h[1] + h[2] * h[2] + h[3] * h[3];
;       }
;       s += __shfl_xor(s, 16); s += __shfl_xor(s, 32);
;       if (fq == 0) atomicAdd(ea.ss_next + R0 + ROFF(m) + fr, s);
;       __builtin_amdgcn_sched_barrier(0);
;       if (m + 1 < NM) {
; #pragma unroll
;         for (int n = 0; n < 4; ++n) rc[n] = rn[n];
;       }
;     }
.LBB0_595:
	s_or_b64 exec, exec, s[92:93]
	v_lshl_add_u64 v[40:41], v[130:131], 0, s[70:71]
	v_lshl_add_u64 v[42:43], v[130:131], 0, s[78:79]
	v_lshl_add_u64 v[44:45], v[130:131], 0, s[80:81]
	v_lshl_add_u64 v[46:47], v[130:131], 0, s[82:83]
	v_add_co_u32_e32 v32, vcc, 0x58000, v130
	s_waitcnt lgkmcnt(0)
	s_nop 0
	v_addc_co_u32_e32 v33, vcc, 0, v131, vcc
	s_nop 0
	s_waitcnt vmcnt(28)
	v_lshlrev_b32_e32 v56, 16, v204
	v_add_f32_e32 v56, v28, v56
	v_and_b32_e32 v28, 0xffff0000, v204
	v_add_f32_e32 v54, v29, v28
	v_lshlrev_b32_e32 v28, 16, v205
	v_add_f32_e32 v30, v30, v28
	v_and_b32_e32 v28, 0xffff0000, v205
	v_add_f32_e32 v31, v31, v28
	v_cvt_pk_bf16_f32 v28, v56, v54
	v_cvt_pk_bf16_f32 v29, v30, v31
	global_store_dwordx2 v[40:41], v[28:29], off
	v_lshlrev_b32_e32 v29, 16, v206
	v_add_f32_e32 v29, v24, v29
	v_and_b32_e32 v24, 0xffff0000, v206
	v_add_f32_e32 v25, v25, v24
	v_lshlrev_b32_e32 v24, 16, v207
	v_add_f32_e32 v26, v26, v24
	v_and_b32_e32 v24, 0xffff0000, v207
	v_mul_f32_e32 v28, v54, v54
	v_add_f32_e32 v27, v27, v24
	v_cvt_pk_bf16_f32 v24, v29, v25
	v_mul_f32_e32 v25, v25, v25
	v_fmac_f32_e32 v28, v56, v56
	v_fmac_f32_e32 v25, v29, v29
	v_fmac_f32_e32 v28, v30, v30
	v_fmac_f32_e32 v25, v26, v26
	v_fmac_f32_e32 v28, v31, v31
	v_fmac_f32_e32 v25, v27, v27
	v_add_f32_e32 v25, v28, v25
	v_lshlrev_b32_e32 v28, 16, v208
	v_add_f32_e32 v20, v20, v28
	v_and_b32_e32 v28, 0xffff0000, v208
	v_add_f32_e32 v21, v21, v28
	v_lshlrev_b32_e32 v28, 16, v209
	v_add_f32_e32 v22, v22, v28
	v_and_b32_e32 v28, 0xffff0000, v209
	v_add_f32_e32 v23, v23, v28
	v_mul_f32_e32 v28, v21, v21
	v_fmac_f32_e32 v28, v20, v20
	v_fmac_f32_e32 v28, v22, v22
	v_fmac_f32_e32 v28, v23, v23
	v_add_f32_e32 v25, v25, v28
	v_lshlrev_b32_e32 v28, 16, v210
	v_add_f32_e32 v28, v16, v28
	v_and_b32_e32 v16, 0xffff0000, v210
	v_add_f32_e32 v29, v17, v16
	v_lshlrev_b32_e32 v16, 16, v211
	v_add_f32_e32 v30, v18, v16
	v_and_b32_e32 v16, 0xffff0000, v211
	v_add_f32_e32 v31, v19, v16
	v_mul_f32_e32 v16, v29, v29
	v_fmac_f32_e32 v16, v28, v28
	v_fmac_f32_e32 v16, v30, v30
	v_fmac_f32_e32 v16, v31, v31
	v_add_f32_e32 v16, v25, v16
	ds_bpermute_b32 v17, v122, v16
	v_cvt_pk_bf16_f32 v25, v26, v27
	global_store_dwordx2 v[42:43], v[24:25], off
	v_cvt_pk_bf16_f32 v18, v20, v21
	v_cvt_pk_bf16_f32 v19, v22, v23
	s_waitcnt lgkmcnt(0)
	v_add_f32_e32 v16, v16, v17
	ds_bpermute_b32 v17, v123, v16
	global_store_dwordx2 v[44:45], v[18:19], off
	v_cvt_pk_bf16_f32 v18, v28, v29
	v_cvt_pk_bf16_f32 v19, v30, v31
	global_store_dwordx2 v[46:47], v[18:19], off
	s_and_saveexec_b64 s[92:93], s[8:9]
	s_cbranch_execz .LBB0_597
	s_waitcnt lgkmcnt(0)
	v_add_f32_e32 v18, v16, v17
	v_lshl_add_u64 v[16:17], v[112:113], 0, v[128:129]
	global_atomic_add_f32 v[16:17], v18, off offset:640
.LBB0_597:
	s_or_b64 exec, exec, s[92:93]
	s_waitcnt lgkmcnt(0)
	v_lshl_add_u64 v[16:17], v[130:131], 0, s[84:85]
	v_lshl_add_u64 v[18:19], v[130:131], 0, s[86:87]
	v_lshl_add_u64 v[20:21], v[130:131], 0, s[88:89]
	v_lshl_add_u64 v[22:23], v[130:131], 0, s[90:91]
	s_waitcnt vmcnt(28)
	v_lshlrev_b32_e32 v24, 16, v212
	v_add_f32_e32 v24, v12, v24
	v_and_b32_e32 v12, 0xffff0000, v212
	v_add_f32_e32 v25, v13, v12
	v_lshlrev_b32_e32 v12, 16, v213
	v_add_f32_e32 v14, v14, v12
	v_and_b32_e32 v12, 0xffff0000, v213
	v_add_f32_e32 v15, v15, v12
	v_cvt_pk_bf16_f32 v12, v24, v25
	v_cvt_pk_bf16_f32 v13, v14, v15
	global_store_dwordx2 v[16:17], v[12:13], off
	v_lshlrev_b32_e32 v13, 16, v214
	v_add_f32_e32 v13, v8, v13
	v_and_b32_e32 v8, 0xffff0000, v214
	v_add_f32_e32 v9, v9, v8
	v_lshlrev_b32_e32 v8, 16, v215
	v_add_f32_e32 v10, v10, v8
	v_and_b32_e32 v8, 0xffff0000, v215
	v_mul_f32_e32 v12, v25, v25
	v_add_f32_e32 v11, v11, v8
	v_cvt_pk_bf16_f32 v8, v13, v9
	v_mul_f32_e32 v9, v9, v9
	v_fmac_f32_e32 v12, v24, v24
	v_fmac_f32_e32 v9, v13, v13
	v_fmac_f32_e32 v12, v14, v14
	v_fmac_f32_e32 v9, v10, v10
	v_fmac_f32_e32 v12, v15, v15
	v_fmac_f32_e32 v9, v11, v11
	v_add_f32_e32 v9, v12, v9
	v_lshlrev_b32_e32 v12, 16, v216
	v_add_f32_e32 v4, v4, v12
	v_and_b32_e32 v12, 0xffff0000, v216
	v_add_f32_e32 v5, v5, v12
	v_lshlrev_b32_e32 v12, 16, v217
	v_add_f32_e32 v6, v6, v12
	v_and_b32_e32 v12, 0xffff0000, v217
	v_add_f32_e32 v7, v7, v12
	v_mul_f32_e32 v12, v5, v5
	v_fmac_f32_e32 v12, v4, v4
	v_fmac_f32_e32 v12, v6, v6
	v_fmac_f32_e32 v12, v7, v7
	v_add_f32_e32 v9, v9, v12
	v_lshlrev_b32_e32 v12, 16, v224
	v_add_f32_e32 v12, v0, v12
	v_and_b32_e32 v0, 0xffff0000, v224
	v_add_f32_e32 v13, v1, v0
	v_lshlrev_b32_e32 v0, 16, v225
	v_add_f32_e32 v14, v2, v0
	v_and_b32_e32 v0, 0xffff0000, v225
	v_add_f32_e32 v15, v3, v0
	v_mul_f32_e32 v0, v13, v13
	v_fmac_f32_e32 v0, v12, v12
	v_fmac_f32_e32 v0, v14, v14
	v_fmac_f32_e32 v0, v15, v15
	v_add_f32_e32 v0, v9, v0
	ds_bpermute_b32 v1, v122, v0
	v_cvt_pk_bf16_f32 v9, v10, v11
	global_store_dwordx2 v[18:19], v[8:9], off
	v_cvt_pk_bf16_f32 v2, v4, v5
	v_cvt_pk_bf16_f32 v3, v6, v7
	s_waitcnt lgkmcnt(0)
	v_add_f32_e32 v0, v0, v1
	ds_bpermute_b32 v1, v123, v0
	global_store_dwordx2 v[20:21], v[2:3], off
	v_cvt_pk_bf16_f32 v2, v12, v13
	v_cvt_pk_bf16_f32 v3, v14, v15
	global_store_dwordx2 v[22:23], v[2:3], off
	s_and_saveexec_b64 s[92:93], s[8:9]
	s_cbranch_execz .LBB0_572
	s_waitcnt lgkmcnt(0)
	v_add_f32_e32 v2, v0, v1
	v_lshl_add_u64 v[0:1], v[112:113], 0, v[128:129]
	global_atomic_add_f32 v[0:1], v2, off offset:704
	s_branch .LBB0_572

; template <int EPI, int NM, bool SWAP>
; DEVI void gemm_epilogue(const Params& p, f32x4 (&acc)[NM][4], const int R0, const int C0, const float* rsw, const EpiArgs& ea) {
;     ...
;   } else if constexpr (EPI == EPI_OUT) {
;     u16* abase = (u16*)(ws + OFF_ABF) + (size_t)(R0 + fr) * DM + C0 + fq * 4;
;     u32x2 rc[4];
; #pragma unroll
;     for (int n = 0; n < 4; ++n) rc[n] = *reinterpret_cast<const u32x2*>(abase + n * 16);
; #pragma unroll
;     for (int m = 0; m < NM; ++m) {
;       u32x2 rn[4];
;       if (m + 1 < NM) {
; #pragma unroll
;         for (int n = 0; n < 4; ++n) rn[n] = *reinterpret_cast<const u32x2*>(abase + (size_t)ROFF(m + 1) * DM + n * 16);
;       }
;       __builtin_amdgcn_sched_barrier(0);
;       float s = 0.f;
; #pragma unroll
;       for (int n = 0; n < 4; ++n) {
;         f32x4 h = acc[m][n];
;         h[0] += __uint_as_float(rc[n][0] << 16); h[1] += __uint_as_float(rc[n][0] & 0xffff0000u);
;         h[2] += __uint_as_float(rc[n][1] << 16); h[3] += __uint_as_float(rc[n][1] & 0xffff0000u);
;         *reinterpret_cast<u32x2*>(abase + (size_t)ROFF(m) * DM + n * 16) = u32x2{cvtpk(h[0], h[1]), cvtpk(h[2], h[3])};
;         s += h[0] * h[0] + h[1] * h[1] + h[2] * h[2] + h[3] * h[3];
;       }
;       s += __shfl_xor(s, 16); s += __shfl_xor(s, 32);
;       if (fq == 0) atomicAdd(ea.ss_next + R0 + ROFF(m) + fr, s);
.LBB0_655:
	s_or_b64 exec, exec, s[4:5]
	v_lshlrev_b32_e32 v128, 6, v147
	v_lshl_or_b32 v130, s96, 8, v128
	v_mov_b32_e32 v128, v222
	v_add_u32_e32 v140, s97, v148
	v_ashrrev_i32_e32 v131, 31, v130
	v_and_b32_e32 v147, 15, v128
	v_or_b32_e32 v132, v147, v140
	v_ashrrev_i32_e32 v133, 31, v132
	v_lshlrev_b64 v[132:133], 11, v[132:133]
	v_lshl_add_u64 v[132:133], s[38:39], 0, v[132:133]
	v_lshl_add_u64 v[130:131], v[130:131], 1, v[132:133]
	v_ashrrev_i32_e32 v132, 2, v128
	v_and_b32_e32 v132, -4, v132
	v_ashrrev_i32_e32 v133, 31, v132
	v_lshl_add_u64 v[130:131], v[132:133], 1, v[130:131]
	s_mov_b32 s4, 0x8000
	v_add_co_u32_e32 v132, vcc, s4, v130
	global_load_dwordx2 v[142:143], v[130:131], off
	global_load_dwordx2 v[144:145], v[130:131], off offset:32
	global_load_dwordx2 v[148:149], v[130:131], off offset:64
	global_load_dwordx2 v[150:151], v[130:131], off offset:96
	v_addc_co_u32_e32 v133, vcc, 0, v131, vcc
	global_load_dwordx2 v[138:139], v[132:133], off
	global_load_dwordx2 v[136:137], v[132:133], off offset:32
	global_load_dwordx2 v[134:135], v[132:133], off offset:64
	s_nop 0
	global_load_dwordx2 v[132:133], v[132:133], off offset:96
	s_mov_b64 s[100:101], 0x10000
	v_lshl_add_u64 v[174:175], v[130:131], 0, s[100:101]
	global_load_dwordx2 v[176:177], v[174:175], off
	global_load_dwordx2 v[178:179], v[174:175], off offset:32
	global_load_dwordx2 v[180:181], v[174:175], off offset:64
	global_load_dwordx2 v[182:183], v[174:175], off offset:96
	s_mov_b64 s[100:101], 0x18000
	v_lshl_add_u64 v[174:175], v[130:131], 0, s[100:101]
	global_load_dwordx2 v[184:185], v[174:175], off
	global_load_dwordx2 v[186:187], v[174:175], off offset:32
	global_load_dwordx2 v[188:189], v[174:175], off offset:64
	global_load_dwordx2 v[190:191], v[174:175], off offset:96
	s_mov_b64 s[100:101], 0x40000
	v_lshl_add_u64 v[174:175], v[130:131], 0, s[100:101]
	global_load_dwordx2 v[192:193], v[174:175], off
	global_load_dwordx2 v[194:195], v[174:175], off offset:32
	global_load_dwordx2 v[196:197], v[174:175], off offset:64
	global_load_dwordx2 v[198:199], v[174:175], off offset:96
	s_mov_b64 s[100:101], 0x48000
	v_lshl_add_u64 v[174:175], v[130:131], 0, s[100:101]
	global_load_dwordx2 v[200:201], v[174:175], off
	global_load_dwordx2 v[202:203], v[174:175], off offset:32
	global_load_dwordx2 v[204:205], v[174:175], off offset:64
	global_load_dwordx2 v[206:207], v[174:175], off offset:96
	s_mov_b64 s[100:101], 0x50000
	v_lshl_add_u64 v[174:175], v[130:131], 0, s[100:101]
	global_load_dwordx2 v[208:209], v[174:175], off
	global_load_dwordx2 v[210:211], v[174:175], off offset:32
	global_load_dwordx2 v[212:213], v[174:175], off offset:64
	global_load_dwordx2 v[214:215], v[174:175], off offset:96
	s_mov_b64 s[100:101], 0x58000
	v_lshl_add_u64 v[174:175], v[130:131], 0, s[100:101]
	global_load_dwordx2 v[216:217], v[174:175], off
	global_load_dwordx2 v[224:225], v[174:175], off offset:32
	global_load_dwordx2 v[226:227], v[174:175], off offset:64
	global_load_dwordx2 v[228:229], v[174:175], off offset:96
	v_cmp_gt_u32_e64 s[4:5], 16, v128
	v_ashrrev_i32_e32 v141, 31, v140
	s_waitcnt vmcnt(28)
	v_lshlrev_b32_e32 v128, 16, v142
	v_add_f32_e32 v128, v124, v128
	v_and_b32_e32 v124, 0xffff0000, v142
	v_add_f32_e32 v142, v125, v124
	v_lshlrev_b32_e32 v124, 16, v143
	v_add_f32_e32 v126, v126, v124
	v_and_b32_e32 v124, 0xffff0000, v143
	v_add_f32_e32 v127, v127, v124
	v_cvt_pk_bf16_f32 v124, v128, v142
	v_cvt_pk_bf16_f32 v125, v126, v127
	global_store_dwordx2 v[130:131], v[124:125], off
	v_mul_f32_e32 v124, v142, v142
	v_lshlrev_b32_e32 v125, 16, v144
	v_fmac_f32_e32 v124, v128, v128
	v_add_f32_e32 v125, v116, v125
	v_and_b32_e32 v116, 0xffff0000, v144
	v_fmac_f32_e32 v124, v126, v126
	v_add_f32_e32 v126, v117, v116
	v_lshlrev_b32_e32 v116, 16, v145
	v_add_f32_e32 v118, v118, v116
	v_and_b32_e32 v116, 0xffff0000, v145
	v_add_f32_e32 v119, v119, v116
	v_cvt_pk_bf16_f32 v116, v125, v126
	v_cvt_pk_bf16_f32 v117, v118, v119
	global_store_dwordx2 v[130:131], v[116:117], off offset:32
	v_mul_f32_e32 v116, v126, v126
	v_fmac_f32_e32 v116, v125, v125
	v_fmac_f32_e32 v116, v118, v118
	v_and_b32_e32 v118, 0xffff0000, v148
	v_lshlrev_b32_e32 v117, 16, v148
	v_add_f32_e32 v118, v121, v118
	v_fmac_f32_e32 v116, v119, v119
	v_add_f32_e32 v117, v120, v117
	v_lshlrev_b32_e32 v119, 16, v149
	v_mul_f32_e32 v121, v118, v118
	v_add_f32_e32 v119, v122, v119
	v_and_b32_e32 v120, 0xffff0000, v149
	v_fmac_f32_e32 v121, v117, v117
	v_fmac_f32_e32 v124, v127, v127
	v_add_f32_e32 v120, v123, v120
	v_fmac_f32_e32 v121, v119, v119
	v_add_f32_e32 v116, v124, v116
	v_fmac_f32_e32 v121, v120, v120
	v_add_f32_e32 v116, v116, v121
	v_lshlrev_b32_e32 v121, 16, v150
	v_add_f32_e32 v121, v112, v121
	v_and_b32_e32 v112, 0xffff0000, v150
	v_add_f32_e32 v123, v113, v112
	v_lshlrev_b32_e32 v112, 16, v151
	v_add_f32_e32 v124, v114, v112
	v_and_b32_e32 v112, 0xffff0000, v151
	v_add_f32_e32 v125, v115, v112
	v_mul_f32_e32 v112, v123, v123
	v_fmac_f32_e32 v112, v121, v121
	v_fmac_f32_e32 v112, v124, v124
	v_fmac_f32_e32 v112, v125, v125
	v_and_b32_e32 v113, 64, v146
	v_add_f32_e32 v114, v116, v112
	v_xor_b32_e32 v112, 16, v146
	v_add_u32_e32 v115, 64, v113
	v_cmp_lt_i32_e32 vcc, v112, v115
	v_lshlrev_b32_e32 v128, 2, v147
	s_nop 0
	v_cndmask_b32_e32 v112, v146, v112, vcc
	v_lshlrev_b32_e32 v122, 2, v112
	ds_bpermute_b32 v116, v122, v114
	v_cvt_pk_bf16_f32 v112, v117, v118
	v_cvt_pk_bf16_f32 v113, v119, v120
	global_store_dwordx2 v[130:131], v[112:113], off offset:64
	v_xor_b32_e32 v113, 32, v146
	v_cmp_lt_i32_e32 vcc, v113, v115
	v_cvt_pk_bf16_f32 v112, v121, v123
	s_waitcnt lgkmcnt(0)
	v_add_f32_e32 v114, v114, v116
	v_cndmask_b32_e32 v113, v146, v113, vcc
	v_lshlrev_b32_e32 v123, 2, v113
	ds_bpermute_b32 v115, v123, v114
	v_cvt_pk_bf16_f32 v113, v124, v125
	global_store_dwordx2 v[130:131], v[112:113], off offset:96
	v_lshl_add_u64 v[112:113], v[140:141], 2, s[8:9]
	s_and_saveexec_b64 s[86:87], s[4:5]
	s_cbranch_execz .LBB0_657
	s_waitcnt lgkmcnt(0)
	v_add_f32_e32 v116, v114, v115
	v_lshl_add_u64 v[114:115], v[112:113], 0, v[128:129]
	global_atomic_add_f32 v[114:115], v116, off
; template <int EPI, int NM, bool SWAP>
; DEVI void gemm_epilogue(const Params& p, f32x4 (&acc)[NM][4], const int R0, const int C0, const float* rsw, const EpiArgs& ea) {
;     ...
;     for (int m = 0; m < NM; ++m) {
;       u32x2 rn[4];
;       if (m + 1 < NM) {
; #pragma unroll
;         for (int n = 0; n < 4; ++n) rn[n] = *reinterpret_cast<const u32x2*>(abase + (size_t)ROFF(m + 1) * DM + n * 16);
;       }
;       __builtin_amdgcn_sched_barrier(0);
;       float s = 0.f;
; #pragma unroll
;       for (int n = 0; n < 4; ++n) {
;         f32x4 h = acc[m][n];
;         h[0] += __uint_as_float(rc[n][0] << 16); h[1] += __uint_as_float(rc[n][0] & 0xffff0000u);
;         h[2] += __uint_as_float(rc[n][1] << 16); h[3] += __uint_as_float(rc[n][1] & 0xffff0000u);
;         *reinterpret_cast<u32x2*>(abase + (size_t)ROFF(m) * DM + n * 16) = u32x2{cvtpk(h[0], h[1]), cvtpk(h[2], h[3])};
;         s += h[0] * h[0] + h[1] * h[1] + h[2] * h[2] + h[3] * h[3];
;       }
;       s += __shfl_xor(s, 16); s += __shfl_xor(s, 32);
;       if (fq == 0) atomicAdd(ea.ss_next + R0 + ROFF(m) + fr, s);
;       __builtin_amdgcn_sched_barrier(0);
;       if (m + 1 < NM) {
; #pragma unroll
;         for (int n = 0; n < 4; ++n) rc[n] = rn[n];
;       }
;     }
.LBB0_657:
	s_or_b64 exec, exec, s[86:87]
	s_mov_b64 s[86:87], 0x8000
	v_lshl_add_u64 v[124:125], v[130:131], 0, s[86:87]
	s_mov_b64 s[86:87], 0x8020
	v_lshl_add_u64 v[126:127], v[130:131], 0, s[86:87]
	s_mov_b64 s[86:87], 0x8040
	v_lshl_add_u64 v[140:141], v[130:131], 0, s[86:87]
	s_mov_b64 s[86:87], 0x8060
	v_lshl_add_u64 v[142:143], v[130:131], 0, s[86:87]
	v_add_co_u32_e32 v114, vcc, 0x10000, v130
	s_waitcnt lgkmcnt(0)
	s_nop 0
	v_addc_co_u32_e32 v115, vcc, 0, v131, vcc
	s_nop 0
	s_waitcnt vmcnt(28)
	v_lshlrev_b32_e32 v144, 16, v138
	v_add_f32_e32 v144, v108, v144
	v_and_b32_e32 v108, 0xffff0000, v138
	v_add_f32_e32 v138, v109, v108
	v_lshlrev_b32_e32 v108, 16, v139
	v_add_f32_e32 v110, v110, v108
	v_and_b32_e32 v108, 0xffff0000, v139
	v_add_f32_e32 v111, v111, v108
	v_cvt_pk_bf16_f32 v108, v144, v138
	v_cvt_pk_bf16_f32 v109, v110, v111
	global_store_dwordx2 v[124:125], v[108:109], off
	v_lshlrev_b32_e32 v109, 16, v136
	v_add_f32_e32 v109, v100, v109
	v_and_b32_e32 v100, 0xffff0000, v136
	v_add_f32_e32 v101, v101, v100
	v_lshlrev_b32_e32 v100, 16, v137
	v_add_f32_e32 v102, v102, v100
	v_and_b32_e32 v100, 0xffff0000, v137
	v_mul_f32_e32 v108, v138, v138
	v_add_f32_e32 v103, v103, v100
	v_cvt_pk_bf16_f32 v100, v109, v101
	v_mul_f32_e32 v101, v101, v101
	v_fmac_f32_e32 v108, v144, v144
	v_fmac_f32_e32 v101, v109, v109
	v_fmac_f32_e32 v108, v110, v110
	v_fmac_f32_e32 v101, v102, v102
	v_fmac_f32_e32 v108, v111, v111
	v_fmac_f32_e32 v101, v103, v103
	v_add_f32_e32 v101, v108, v101
	v_lshlrev_b32_e32 v108, 16, v134
	v_add_f32_e32 v104, v104, v108
	v_and_b32_e32 v108, 0xffff0000, v134
	v_add_f32_e32 v105, v105, v108
	v_lshlrev_b32_e32 v108, 16, v135
	v_add_f32_e32 v106, v106, v108
	v_and_b32_e32 v108, 0xffff0000, v135
	v_add_f32_e32 v107, v107, v108
	v_mul_f32_e32 v108, v105, v105
	v_fmac_f32_e32 v108, v104, v104
	v_fmac_f32_e32 v108, v106, v106
	v_fmac_f32_e32 v108, v107, v107
	v_add_f32_e32 v101, v101, v108
	v_lshlrev_b32_e32 v108, 16, v132
	v_add_f32_e32 v108, v96, v108
	v_and_b32_e32 v96, 0xffff0000, v132
	v_add_f32_e32 v109, v97, v96
	v_lshlrev_b32_e32 v96, 16, v133
	v_add_f32_e32 v110, v98, v96
	v_and_b32_e32 v96, 0xffff0000, v133
	v_add_f32_e32 v111, v99, v96
	v_mul_f32_e32 v96, v109, v109
	v_fmac_f32_e32 v96, v108, v108
	v_fmac_f32_e32 v96, v110, v110
	v_fmac_f32_e32 v96, v111, v111
	v_add_f32_e32 v96, v101, v96
	ds_bpermute_b32 v97, v122, v96
	v_cvt_pk_bf16_f32 v101, v102, v103
	global_store_dwordx2 v[126:127], v[100:101], off
	v_cvt_pk_bf16_f32 v98, v104, v105
	v_cvt_pk_bf16_f32 v99, v106, v107
	s_waitcnt lgkmcnt(0)
	v_add_f32_e32 v96, v96, v97
	ds_bpermute_b32 v97, v123, v96
	global_store_dwordx2 v[140:141], v[98:99], off
	v_cvt_pk_bf16_f32 v98, v108, v109
	v_cvt_pk_bf16_f32 v99, v110, v111
	global_store_dwordx2 v[142:143], v[98:99], off
	s_and_saveexec_b64 s[86:87], s[4:5]
	s_cbranch_execz .LBB0_659
	s_waitcnt lgkmcnt(0)
	v_add_f32_e32 v98, v96, v97
	v_lshl_add_u64 v[96:97], v[112:113], 0, v[128:129]
	global_atomic_add_f32 v[96:97], v98, off offset:64
.LBB0_659:
	s_or_b64 exec, exec, s[86:87]
	s_mov_b64 s[86:87], 0x10000
	v_lshl_add_u64 v[104:105], v[130:131], 0, s[86:87]
	s_mov_b64 s[86:87], 0x10020
	v_lshl_add_u64 v[106:107], v[130:131], 0, s[86:87]
	s_mov_b64 s[86:87], 0x10040
	v_lshl_add_u64 v[108:109], v[130:131], 0, s[86:87]
	s_mov_b64 s[86:87], 0x10060
	v_lshl_add_u64 v[110:111], v[130:131], 0, s[86:87]
	v_add_co_u32_e32 v96, vcc, 0x18000, v130
	s_waitcnt lgkmcnt(0)
	s_nop 0
	v_addc_co_u32_e32 v97, vcc, 0, v131, vcc
	s_nop 0
	s_waitcnt vmcnt(28)
	v_lshlrev_b32_e32 v124, 16, v176
	v_add_f32_e32 v124, v92, v124
	v_and_b32_e32 v92, 0xffff0000, v176
	v_add_f32_e32 v120, v93, v92
	v_lshlrev_b32_e32 v92, 16, v177
	v_add_f32_e32 v94, v94, v92
	v_and_b32_e32 v92, 0xffff0000, v177
	v_add_f32_e32 v95, v95, v92
	v_cvt_pk_bf16_f32 v92, v124, v120
	v_cvt_pk_bf16_f32 v93, v94, v95
	global_store_dwordx2 v[104:105], v[92:93], off
	v_lshlrev_b32_e32 v93, 16, v178
	v_add_f32_e32 v93, v84, v93
	v_and_b32_e32 v84, 0xffff0000, v178
	v_add_f32_e32 v85, v85, v84
	v_lshlrev_b32_e32 v84, 16, v179
	v_add_f32_e32 v86, v86, v84
	v_and_b32_e32 v84, 0xffff0000, v179
	v_mul_f32_e32 v92, v120, v120
	v_add_f32_e32 v87, v87, v84
	v_cvt_pk_bf16_f32 v84, v93, v85
	v_mul_f32_e32 v85, v85, v85
	v_fmac_f32_e32 v92, v124, v124
	v_fmac_f32_e32 v85, v93, v93
	v_fmac_f32_e32 v92, v94, v94
	v_fmac_f32_e32 v85, v86, v86
	v_fmac_f32_e32 v92, v95, v95
	v_fmac_f32_e32 v85, v87, v87
	v_add_f32_e32 v85, v92, v85
	v_lshlrev_b32_e32 v92, 16, v180
	v_add_f32_e32 v88, v88, v92
	v_and_b32_e32 v92, 0xffff0000, v180
	v_add_f32_e32 v89, v89, v92
	v_lshlrev_b32_e32 v92, 16, v181
	v_add_f32_e32 v90, v90, v92
	v_and_b32_e32 v92, 0xffff0000, v181
	v_add_f32_e32 v91, v91, v92
	v_mul_f32_e32 v92, v89, v89
	v_fmac_f32_e32 v92, v88, v88
	v_fmac_f32_e32 v92, v90, v90
	v_fmac_f32_e32 v92, v91, v91
	v_add_f32_e32 v85, v85, v92
	v_lshlrev_b32_e32 v92, 16, v182
	v_add_f32_e32 v92, v80, v92
	v_and_b32_e32 v80, 0xffff0000, v182
	v_add_f32_e32 v93, v81, v80
	v_lshlrev_b32_e32 v80, 16, v183
	v_add_f32_e32 v94, v82, v80
	v_and_b32_e32 v80, 0xffff0000, v183
	v_add_f32_e32 v95, v83, v80
	v_mul_f32_e32 v80, v93, v93
	v_fmac_f32_e32 v80, v92, v92
	v_fmac_f32_e32 v80, v94, v94
	v_fmac_f32_e32 v80, v95, v95
	v_add_f32_e32 v80, v85, v80
	ds_bpermute_b32 v81, v122, v80
	v_cvt_pk_bf16_f32 v85, v86, v87
	global_store_dwordx2 v[106:107], v[84:85], off
	v_cvt_pk_bf16_f32 v82, v88, v89
	v_cvt_pk_bf16_f32 v83, v90, v91
	s_waitcnt lgkmcnt(0)
	v_add_f32_e32 v80, v80, v81
	ds_bpermute_b32 v81, v123, v80
	global_store_dwordx2 v[108:109], v[82:83], off
	v_cvt_pk_bf16_f32 v82, v92, v93
	v_cvt_pk_bf16_f32 v83, v94, v95
	global_store_dwordx2 v[110:111], v[82:83], off
	s_and_saveexec_b64 s[86:87], s[4:5]
	s_cbranch_execz .LBB0_661
	s_waitcnt lgkmcnt(0)
	v_add_f32_e32 v82, v80, v81
	v_lshl_add_u64 v[80:81], v[112:113], 0, v[128:129]
	global_atomic_add_f32 v[80:81], v82, off offset:128
; template <int EPI, int NM, bool SWAP>
; DEVI void gemm_epilogue(const Params& p, f32x4 (&acc)[NM][4], const int R0, const int C0, const float* rsw, const EpiArgs& ea) {
;     ...
;     for (int m = 0; m < NM; ++m) {
;       u32x2 rn[4];
;       if (m + 1 < NM) {
; #pragma unroll
;         for (int n = 0; n < 4; ++n) rn[n] = *reinterpret_cast<const u32x2*>(abase + (size_t)ROFF(m + 1) * DM + n * 16);
;       }
;       __builtin_amdgcn_sched_barrier(0);
;       float s = 0.f;
; #pragma unroll
;       for (int n = 0; n < 4; ++n) {
;         f32x4 h = acc[m][n];
;         h[0] += __uint_as_float(rc[n][0] << 16); h[1] += __uint_as_float(rc[n][0] & 0xffff0000u);
;         h[2] += __uint_as_float(rc[n][1] << 16); h[3] += __uint_as_float(rc[n][1] & 0xffff0000u);
;         *reinterpret_cast<u32x2*>(abase + (size_t)ROFF(m) * DM + n * 16) = u32x2{cvtpk(h[0], h[1]), cvtpk(h[2], h[3])};
;         s += h[0] * h[0] + h[1] * h[1] + h[2] * h[2] + h[3] * h[3];
;       }
;       s += __shfl_xor(s, 16); s += __shfl_xor(s, 32);
;       if (fq == 0) atomicAdd(ea.ss_next + R0 + ROFF(m) + fr, s);
;       __builtin_amdgcn_sched_barrier(0);
;       if (m + 1 < NM) {
; #pragma unroll
;         for (int n = 0; n < 4; ++n) rc[n] = rn[n];
;       }
;     }
.LBB0_661:
	s_or_b64 exec, exec, s[86:87]
	s_mov_b64 s[86:87], 0x18000
	v_lshl_add_u64 v[88:89], v[130:131], 0, s[86:87]
	v_lshl_add_u64 v[90:91], v[130:131], 0, s[34:35]
	v_lshl_add_u64 v[92:93], v[130:131], 0, s[36:37]
	v_lshl_add_u64 v[94:95], v[130:131], 0, s[40:41]
	v_add_co_u32_e32 v80, vcc, 0x40000, v130
	s_waitcnt lgkmcnt(0)
	s_nop 0
	v_addc_co_u32_e32 v81, vcc, 0, v131, vcc
	s_nop 0
	s_waitcnt vmcnt(28)
	v_lshlrev_b32_e32 v104, 16, v184
	v_add_f32_e32 v104, v76, v104
	v_and_b32_e32 v76, 0xffff0000, v184
	v_add_f32_e32 v102, v77, v76
	v_lshlrev_b32_e32 v76, 16, v185
	v_add_f32_e32 v78, v78, v76
	v_and_b32_e32 v76, 0xffff0000, v185
	v_add_f32_e32 v79, v79, v76
	v_cvt_pk_bf16_f32 v76, v104, v102
	v_cvt_pk_bf16_f32 v77, v78, v79
	global_store_dwordx2 v[88:89], v[76:77], off
	v_lshlrev_b32_e32 v77, 16, v186
	v_add_f32_e32 v77, v68, v77
	v_and_b32_e32 v68, 0xffff0000, v186
	v_add_f32_e32 v69, v69, v68
	v_lshlrev_b32_e32 v68, 16, v187
	v_add_f32_e32 v70, v70, v68
	v_and_b32_e32 v68, 0xffff0000, v187
	v_mul_f32_e32 v76, v102, v102
	v_add_f32_e32 v71, v71, v68
	v_cvt_pk_bf16_f32 v68, v77, v69
	v_mul_f32_e32 v69, v69, v69
	v_fmac_f32_e32 v76, v104, v104
	v_fmac_f32_e32 v69, v77, v77
	v_fmac_f32_e32 v76, v78, v78
	v_fmac_f32_e32 v69, v70, v70
	v_fmac_f32_e32 v76, v79, v79
	v_fmac_f32_e32 v69, v71, v71
	v_add_f32_e32 v69, v76, v69
	v_lshlrev_b32_e32 v76, 16, v188
	v_add_f32_e32 v72, v72, v76
	v_and_b32_e32 v76, 0xffff0000, v188
	v_add_f32_e32 v73, v73, v76
	v_lshlrev_b32_e32 v76, 16, v189
	v_add_f32_e32 v74, v74, v76
	v_and_b32_e32 v76, 0xffff0000, v189
	v_add_f32_e32 v75, v75, v76
	v_mul_f32_e32 v76, v73, v73
	v_fmac_f32_e32 v76, v72, v72
	v_fmac_f32_e32 v76, v74, v74
	v_fmac_f32_e32 v76, v75, v75
	v_add_f32_e32 v69, v69, v76
	v_lshlrev_b32_e32 v76, 16, v190
	v_add_f32_e32 v76, v64, v76
	v_and_b32_e32 v64, 0xffff0000, v190
	v_add_f32_e32 v77, v65, v64
	v_lshlrev_b32_e32 v64, 16, v191
	v_add_f32_e32 v78, v66, v64
	v_and_b32_e32 v64, 0xffff0000, v191
	v_add_f32_e32 v79, v67, v64
	v_mul_f32_e32 v64, v77, v77
	v_fmac_f32_e32 v64, v76, v76
	v_fmac_f32_e32 v64, v78, v78
	v_fmac_f32_e32 v64, v79, v79
	v_add_f32_e32 v64, v69, v64
	ds_bpermute_b32 v65, v122, v64
	v_cvt_pk_bf16_f32 v69, v70, v71
	global_store_dwordx2 v[90:91], v[68:69], off
	v_cvt_pk_bf16_f32 v66, v72, v73
	v_cvt_pk_bf16_f32 v67, v74, v75
	s_waitcnt lgkmcnt(0)
	v_add_f32_e32 v64, v64, v65
	ds_bpermute_b32 v65, v123, v64
	global_store_dwordx2 v[92:93], v[66:67], off
	v_cvt_pk_bf16_f32 v66, v76, v77
	v_cvt_pk_bf16_f32 v67, v78, v79
	global_store_dwordx2 v[94:95], v[66:67], off
	s_and_saveexec_b64 s[86:87], s[4:5]
	s_cbranch_execz .LBB0_663
	s_waitcnt lgkmcnt(0)
	v_add_f32_e32 v66, v64, v65
	v_lshl_add_u64 v[64:65], v[112:113], 0, v[128:129]
	global_atomic_add_f32 v[64:65], v66, off offset:192
.LBB0_663:
	s_or_b64 exec, exec, s[86:87]
	v_lshl_add_u64 v[72:73], v[130:131], 0, s[42:43]
	v_lshl_add_u64 v[74:75], v[130:131], 0, s[50:51]
	v_lshl_add_u64 v[76:77], v[130:131], 0, s[52:53]
	v_lshl_add_u64 v[78:79], v[130:131], 0, s[54:55]
	v_add_co_u32_e32 v64, vcc, 0x48000, v130
	s_waitcnt lgkmcnt(0)
	s_nop 0
	v_addc_co_u32_e32 v65, vcc, 0, v131, vcc
	s_nop 0
	s_waitcnt vmcnt(28)
	v_lshlrev_b32_e32 v88, 16, v192
	v_add_f32_e32 v88, v60, v88
	v_and_b32_e32 v60, 0xffff0000, v192
	v_add_f32_e32 v86, v61, v60
	v_lshlrev_b32_e32 v60, 16, v193
	v_add_f32_e32 v62, v62, v60
	v_and_b32_e32 v60, 0xffff0000, v193
	v_add_f32_e32 v63, v63, v60
	v_cvt_pk_bf16_f32 v60, v88, v86
	v_cvt_pk_bf16_f32 v61, v62, v63
	global_store_dwordx2 v[72:73], v[60:61], off
	v_lshlrev_b32_e32 v61, 16, v194
	v_add_f32_e32 v61, v56, v61
	v_and_b32_e32 v56, 0xffff0000, v194
	v_add_f32_e32 v57, v57, v56
	v_lshlrev_b32_e32 v56, 16, v195
	v_add_f32_e32 v58, v58, v56
	v_and_b32_e32 v56, 0xffff0000, v195
	v_mul_f32_e32 v60, v86, v86
	v_add_f32_e32 v59, v59, v56
	v_cvt_pk_bf16_f32 v56, v61, v57
	v_mul_f32_e32 v57, v57, v57
	v_fmac_f32_e32 v60, v88, v88
	v_fmac_f32_e32 v57, v61, v61
	v_fmac_f32_e32 v60, v62, v62
	v_fmac_f32_e32 v57, v58, v58
	v_fmac_f32_e32 v60, v63, v63
	v_fmac_f32_e32 v57, v59, v59
	v_add_f32_e32 v57, v60, v57
	v_lshlrev_b32_e32 v60, 16, v196
	v_add_f32_e32 v52, v52, v60
	v_and_b32_e32 v60, 0xffff0000, v196
	v_add_f32_e32 v53, v53, v60
	v_lshlrev_b32_e32 v60, 16, v197
	v_add_f32_e32 v54, v54, v60
	v_and_b32_e32 v60, 0xffff0000, v197
	v_add_f32_e32 v55, v55, v60
	v_mul_f32_e32 v60, v53, v53
	v_fmac_f32_e32 v60, v52, v52
	v_fmac_f32_e32 v60, v54, v54
	v_fmac_f32_e32 v60, v55, v55
	v_add_f32_e32 v57, v57, v60
	v_lshlrev_b32_e32 v60, 16, v198
	v_add_f32_e32 v60, v48, v60
	v_and_b32_e32 v48, 0xffff0000, v198
	v_add_f32_e32 v61, v49, v48
	v_lshlrev_b32_e32 v48, 16, v199
	v_add_f32_e32 v62, v50, v48
	v_and_b32_e32 v48, 0xffff0000, v199
	v_add_f32_e32 v63, v51, v48
	v_mul_f32_e32 v48, v61, v61
	v_fmac_f32_e32 v48, v60, v60
	v_fmac_f32_e32 v48, v62, v62
	v_fmac_f32_e32 v48, v63, v63
	v_add_f32_e32 v48, v57, v48
	ds_bpermute_b32 v49, v122, v48
	v_cvt_pk_bf16_f32 v57, v58, v59
	global_store_dwordx2 v[74:75], v[56:57], off
	v_cvt_pk_bf16_f32 v50, v52, v53
	v_cvt_pk_bf16_f32 v51, v54, v55
	s_waitcnt lgkmcnt(0)
	v_add_f32_e32 v48, v48, v49
	ds_bpermute_b32 v49, v123, v48
	global_store_dwordx2 v[76:77], v[50:51], off
	v_cvt_pk_bf16_f32 v50, v60, v61
	v_cvt_pk_bf16_f32 v51, v62, v63
	global_store_dwordx2 v[78:79], v[50:51], off
	s_and_saveexec_b64 s[86:87], s[4:5]
	s_cbranch_execz .LBB0_665
	s_waitcnt lgkmcnt(0)
	v_add_f32_e32 v50, v48, v49
	v_lshl_add_u64 v[48:49], v[112:113], 0, v[128:129]
	global_atomic_add_f32 v[48:49], v50, off offset:512
; template <int EPI, int NM, bool SWAP>
; DEVI void gemm_epilogue(const Params& p, f32x4 (&acc)[NM][4], const int R0, const int C0, const float* rsw, const EpiArgs& ea) {
;     ...
;     for (int m = 0; m < NM; ++m) {
;       u32x2 rn[4];
;       if (m + 1 < NM) {
; #pragma unroll
;         for (int n = 0; n < 4; ++n) rn[n] = *reinterpret_cast<const u32x2*>(abase + (size_t)ROFF(m + 1) * DM + n * 16);
;       }
;       __builtin_amdgcn_sched_barrier(0);
;       float s = 0.f;
; #pragma unroll
;       for (int n = 0; n < 4; ++n) {
;         f32x4 h = acc[m][n];
;         h[0] += __uint_as_float(rc[n][0] << 16); h[1] += __uint_as_float(rc[n][0] & 0xffff0000u);
;         h[2] += __uint_as_float(rc[n][1] << 16); h[3] += __uint_as_float(rc[n][1] & 0xffff0000u);
;         *reinterpret_cast<u32x2*>(abase + (size_t)ROFF(m) * DM + n * 16) = u32x2{cvtpk(h[0], h[1]), cvtpk(h[2], h[3])};
;         s += h[0] * h[0] + h[1] * h[1] + h[2] * h[2] + h[3] * h[3];
;       }
;       s += __shfl_xor(s, 16); s += __shfl_xor(s, 32);
;       if (fq == 0) atomicAdd(ea.ss_next + R0 + ROFF(m) + fr, s);
;       __builtin_amdgcn_sched_barrier(0);
;       if (m + 1 < NM) {
; #pragma unroll
;         for (int n = 0; n < 4; ++n) rc[n] = rn[n];
;       }
;     }
.LBB0_665:
	s_or_b64 exec, exec, s[86:87]
	v_lshl_add_u64 v[56:57], v[130:131], 0, s[56:57]
	v_lshl_add_u64 v[58:59], v[130:131], 0, s[58:59]
	v_lshl_add_u64 v[60:61], v[130:131], 0, s[60:61]
	v_lshl_add_u64 v[62:63], v[130:131], 0, s[62:63]
	v_add_co_u32_e32 v48, vcc, 0x50000, v130
	s_waitcnt lgkmcnt(0)
	s_nop 0
	v_addc_co_u32_e32 v49, vcc, 0, v131, vcc
	s_nop 0
	s_waitcnt vmcnt(28)
	v_lshlrev_b32_e32 v72, 16, v200
	v_add_f32_e32 v72, v44, v72
	v_and_b32_e32 v44, 0xffff0000, v200
	v_add_f32_e32 v70, v45, v44
	v_lshlrev_b32_e32 v44, 16, v201
	v_add_f32_e32 v46, v46, v44
	v_and_b32_e32 v44, 0xffff0000, v201
	v_add_f32_e32 v47, v47, v44
	v_cvt_pk_bf16_f32 v44, v72, v70
	v_cvt_pk_bf16_f32 v45, v46, v47
	global_store_dwordx2 v[56:57], v[44:45], off
	v_lshlrev_b32_e32 v45, 16, v202
	v_add_f32_e32 v45, v40, v45
	v_and_b32_e32 v40, 0xffff0000, v202
	v_add_f32_e32 v41, v41, v40
	v_lshlrev_b32_e32 v40, 16, v203
	v_add_f32_e32 v42, v42, v40
	v_and_b32_e32 v40, 0xffff0000, v203
	v_mul_f32_e32 v44, v70, v70
	v_add_f32_e32 v43, v43, v40
	v_cvt_pk_bf16_f32 v40, v45, v41
	v_mul_f32_e32 v41, v41, v41
	v_fmac_f32_e32 v44, v72, v72
	v_fmac_f32_e32 v41, v45, v45
	v_fmac_f32_e32 v44, v46, v46
	v_fmac_f32_e32 v41, v42, v42
	v_fmac_f32_e32 v44, v47, v47
	v_fmac_f32_e32 v41, v43, v43
	v_add_f32_e32 v41, v44, v41
	v_lshlrev_b32_e32 v44, 16, v204
	v_add_f32_e32 v36, v36, v44
	v_and_b32_e32 v44, 0xffff0000, v204
	v_add_f32_e32 v37, v37, v44
	v_lshlrev_b32_e32 v44, 16, v205
	v_add_f32_e32 v38, v38, v44
	v_and_b32_e32 v44, 0xffff0000, v205
	v_add_f32_e32 v39, v39, v44
	v_mul_f32_e32 v44, v37, v37
	v_fmac_f32_e32 v44, v36, v36
	v_fmac_f32_e32 v44, v38, v38
	v_fmac_f32_e32 v44, v39, v39
	v_add_f32_e32 v41, v41, v44
	v_lshlrev_b32_e32 v44, 16, v206
	v_add_f32_e32 v44, v32, v44
	v_and_b32_e32 v32, 0xffff0000, v206
	v_add_f32_e32 v45, v33, v32
	v_lshlrev_b32_e32 v32, 16, v207
	v_add_f32_e32 v46, v34, v32
	v_and_b32_e32 v32, 0xffff0000, v207
	v_add_f32_e32 v47, v35, v32
	v_mul_f32_e32 v32, v45, v45
	v_fmac_f32_e32 v32, v44, v44
	v_fmac_f32_e32 v32, v46, v46
	v_fmac_f32_e32 v32, v47, v47
	v_add_f32_e32 v32, v41, v32
	ds_bpermute_b32 v33, v122, v32
	v_cvt_pk_bf16_f32 v41, v42, v43
	global_store_dwordx2 v[58:59], v[40:41], off
	v_cvt_pk_bf16_f32 v34, v36, v37
	v_cvt_pk_bf16_f32 v35, v38, v39
	s_waitcnt lgkmcnt(0)
	v_add_f32_e32 v32, v32, v33
	ds_bpermute_b32 v33, v123, v32
	global_store_dwordx2 v[60:61], v[34:35], off
	v_cvt_pk_bf16_f32 v34, v44, v45
	v_cvt_pk_bf16_f32 v35, v46, v47
	global_store_dwordx2 v[62:63], v[34:35], off
	s_and_saveexec_b64 s[86:87], s[4:5]
	s_cbranch_execz .LBB0_667
	s_waitcnt lgkmcnt(0)
	v_add_f32_e32 v34, v32, v33
	v_lshl_add_u64 v[32:33], v[112:113], 0, v[128:129]
	global_atomic_add_f32 v[32:33], v34, off offset:576
; template <int EPI, int NM, bool SWAP>
; DEVI void gemm_epilogue(const Params& p, f32x4 (&acc)[NM][4], const int R0, const int C0, const float* rsw, const EpiArgs& ea) {
;     ...
;     for (int m = 0; m < NM; ++m) {
;       u32x2 rn[4];
;       if (m + 1 < NM) {
; #pragma unroll
;         for (int n = 0; n < 4; ++n) rn[n] = *reinterpret_cast<const u32x2*>(abase + (size_t)ROFF(m + 1) * DM + n * 16);
;       }
;       __builtin_amdgcn_sched_barrier(0);
;       float s = 0.f;
; #pragma unroll
;       for (int n = 0; n < 4; ++n) {
;         f32x4 h = acc[m][n];
;         h[0] += __uint_as_float(rc[n][0] << 16); h[1] += __uint_as_float(rc[n][0] & 0xffff0000u);
;         h[2] += __uint_as_float(rc[n][1] << 16); h[3] += __uint_as_float(rc[n][1] & 0xffff0000u);
;         *reinterpret_cast<u32x2*>(abase + (size_t)ROFF(m) * DM + n * 16) = u32x2{cvtpk(h[0], h[1]), cvtpk(h[2], h[3])};
;         s += h[0] * h[0] + h[1] * h[1] + h[2] * h[2] + h[3] * h[3];
;       }
;       s += __shfl_xor(s, 16); s += __shfl_xor(s, 32);
;       if (fq == 0) atomicAdd(ea.ss_next + R0 + ROFF(m) + fr, s);
;       __builtin_amdgcn_sched_barrier(0);
;       if (m + 1 < NM) {
; #pragma unroll
;         for (int n = 0; n < 4; ++n) rc[n] = rn[n];
;       }
;     }
.LBB0_667:
	s_or_b64 exec, exec, s[86:87]
	v_lshl_add_u64 v[40:41], v[130:131], 0, s[64:65]
	v_lshl_add_u64 v[42:43], v[130:131], 0, s[66:67]
	v_lshl_add_u64 v[44:45], v[130:131], 0, s[68:69]
	v_lshl_add_u64 v[46:47], v[130:131], 0, s[70:71]
	v_add_co_u32_e32 v32, vcc, 0x58000, v130
	s_waitcnt lgkmcnt(0)
	s_nop 0
	v_addc_co_u32_e32 v33, vcc, 0, v131, vcc
	s_nop 0
	s_waitcnt vmcnt(28)
	v_lshlrev_b32_e32 v56, 16, v208
	v_add_f32_e32 v56, v28, v56
	v_and_b32_e32 v28, 0xffff0000, v208
	v_add_f32_e32 v54, v29, v28
	v_lshlrev_b32_e32 v28, 16, v209
	v_add_f32_e32 v30, v30, v28
	v_and_b32_e32 v28, 0xffff0000, v209
	v_add_f32_e32 v31, v31, v28
	v_cvt_pk_bf16_f32 v28, v56, v54
	v_cvt_pk_bf16_f32 v29, v30, v31
	global_store_dwordx2 v[40:41], v[28:29], off
	v_lshlrev_b32_e32 v29, 16, v210
	v_add_f32_e32 v29, v24, v29
	v_and_b32_e32 v24, 0xffff0000, v210
	v_add_f32_e32 v25, v25, v24
	v_lshlrev_b32_e32 v24, 16, v211
	v_add_f32_e32 v26, v26, v24
	v_and_b32_e32 v24, 0xffff0000, v211
	v_mul_f32_e32 v28, v54, v54
	v_add_f32_e32 v27, v27, v24
	v_cvt_pk_bf16_f32 v24, v29, v25
	v_mul_f32_e32 v25, v25, v25
	v_fmac_f32_e32 v28, v56, v56
	v_fmac_f32_e32 v25, v29, v29
	v_fmac_f32_e32 v28, v30, v30
	v_fmac_f32_e32 v25, v26, v26
	v_fmac_f32_e32 v28, v31, v31
	v_fmac_f32_e32 v25, v27, v27
	v_add_f32_e32 v25, v28, v25
	v_lshlrev_b32_e32 v28, 16, v212
	v_add_f32_e32 v20, v20, v28
	v_and_b32_e32 v28, 0xffff0000, v212
	v_add_f32_e32 v21, v21, v28
	v_lshlrev_b32_e32 v28, 16, v213
	v_add_f32_e32 v22, v22, v28
	v_and_b32_e32 v28, 0xffff0000, v213
	v_add_f32_e32 v23, v23, v28
	v_mul_f32_e32 v28, v21, v21
	v_fmac_f32_e32 v28, v20, v20
	v_fmac_f32_e32 v28, v22, v22
	v_fmac_f32_e32 v28, v23, v23
	v_add_f32_e32 v25, v25, v28
	v_lshlrev_b32_e32 v28, 16, v214
	v_add_f32_e32 v28, v16, v28
	v_and_b32_e32 v16, 0xffff0000, v214
	v_add_f32_e32 v29, v17, v16
	v_lshlrev_b32_e32 v16, 16, v215
	v_add_f32_e32 v30, v18, v16
	v_and_b32_e32 v16, 0xffff0000, v215
	v_add_f32_e32 v31, v19, v16
	v_mul_f32_e32 v16, v29, v29
	v_fmac_f32_e32 v16, v28, v28
	v_fmac_f32_e32 v16, v30, v30
	v_fmac_f32_e32 v16, v31, v31
	v_add_f32_e32 v16, v25, v16
	ds_bpermute_b32 v17, v122, v16
	v_cvt_pk_bf16_f32 v25, v26, v27
	global_store_dwordx2 v[42:43], v[24:25], off
	v_cvt_pk_bf16_f32 v18, v20, v21
	v_cvt_pk_bf16_f32 v19, v22, v23
	s_waitcnt lgkmcnt(0)
	v_add_f32_e32 v16, v16, v17
	ds_bpermute_b32 v17, v123, v16
	global_store_dwordx2 v[44:45], v[18:19], off
	v_cvt_pk_bf16_f32 v18, v28, v29
	v_cvt_pk_bf16_f32 v19, v30, v31
	global_store_dwordx2 v[46:47], v[18:19], off
	s_and_saveexec_b64 s[86:87], s[4:5]
	s_cbranch_execz .LBB0_669
	s_waitcnt lgkmcnt(0)
	v_add_f32_e32 v18, v16, v17
	v_lshl_add_u64 v[16:17], v[112:113], 0, v[128:129]
	global_atomic_add_f32 v[16:17], v18, off offset:640
.LBB0_669:
	s_or_b64 exec, exec, s[86:87]
	s_waitcnt lgkmcnt(0)
	v_lshl_add_u64 v[16:17], v[130:131], 0, s[78:79]
	v_lshl_add_u64 v[18:19], v[130:131], 0, s[80:81]
	v_lshl_add_u64 v[20:21], v[130:131], 0, s[82:83]
	v_lshl_add_u64 v[22:23], v[130:131], 0, s[84:85]
	s_waitcnt vmcnt(28)
	v_lshlrev_b32_e32 v24, 16, v216
	v_add_f32_e32 v24, v12, v24
	v_and_b32_e32 v12, 0xffff0000, v216
	v_add_f32_e32 v25, v13, v12
	v_lshlrev_b32_e32 v12, 16, v217
	v_add_f32_e32 v14, v14, v12
	v_and_b32_e32 v12, 0xffff0000, v217
	v_add_f32_e32 v15, v15, v12
	v_cvt_pk_bf16_f32 v12, v24, v25
	v_cvt_pk_bf16_f32 v13, v14, v15
	global_store_dwordx2 v[16:17], v[12:13], off
	v_lshlrev_b32_e32 v13, 16, v224
	v_add_f32_e32 v13, v8, v13
	v_and_b32_e32 v8, 0xffff0000, v224
	v_add_f32_e32 v9, v9, v8
	v_lshlrev_b32_e32 v8, 16, v225
	v_add_f32_e32 v10, v10, v8
	v_and_b32_e32 v8, 0xffff0000, v225
	v_mul_f32_e32 v12, v25, v25
	v_add_f32_e32 v11, v11, v8
	v_cvt_pk_bf16_f32 v8, v13, v9
	v_mul_f32_e32 v9, v9, v9
	v_fmac_f32_e32 v12, v24, v24
	v_fmac_f32_e32 v9, v13, v13
	v_fmac_f32_e32 v12, v14, v14
	v_fmac_f32_e32 v9, v10, v10
	v_fmac_f32_e32 v12, v15, v15
	v_fmac_f32_e32 v9, v11, v11
	v_add_f32_e32 v9, v12, v9
	v_lshlrev_b32_e32 v12, 16, v226
	v_add_f32_e32 v4, v4, v12
	v_and_b32_e32 v12, 0xffff0000, v226
	v_add_f32_e32 v5, v5, v12
	v_lshlrev_b32_e32 v12, 16, v227
	v_add_f32_e32 v6, v6, v12
	v_and_b32_e32 v12, 0xffff0000, v227
	v_add_f32_e32 v7, v7, v12
	v_mul_f32_e32 v12, v5, v5
	v_fmac_f32_e32 v12, v4, v4
	v_fmac_f32_e32 v12, v6, v6
	v_fmac_f32_e32 v12, v7, v7
	v_add_f32_e32 v9, v9, v12
	v_lshlrev_b32_e32 v12, 16, v228
	v_add_f32_e32 v12, v0, v12
	v_and_b32_e32 v0, 0xffff0000, v228
	v_add_f32_e32 v13, v1, v0
	v_lshlrev_b32_e32 v0, 16, v229
	v_add_f32_e32 v14, v2, v0
	v_and_b32_e32 v0, 0xffff0000, v229
	v_add_f32_e32 v15, v3, v0
	v_mul_f32_e32 v0, v13, v13
	v_fmac_f32_e32 v0, v12, v12
	v_fmac_f32_e32 v0, v14, v14
	v_fmac_f32_e32 v0, v15, v15
	v_add_f32_e32 v0, v9, v0
	ds_bpermute_b32 v1, v122, v0
	v_cvt_pk_bf16_f32 v9, v10, v11
	global_store_dwordx2 v[18:19], v[8:9], off
	v_cvt_pk_bf16_f32 v2, v4, v5
	v_cvt_pk_bf16_f32 v3, v6, v7
	s_waitcnt lgkmcnt(0)
	v_add_f32_e32 v0, v0, v1
	ds_bpermute_b32 v1, v123, v0
	global_store_dwordx2 v[20:21], v[2:3], off
	v_cvt_pk_bf16_f32 v2, v12, v13
	v_cvt_pk_bf16_f32 v3, v14, v15
	global_store_dwordx2 v[22:23], v[2:3], off
	s_and_saveexec_b64 s[86:87], s[4:5]
	s_cbranch_execz .LBB0_644
	s_waitcnt lgkmcnt(0)
	v_add_f32_e32 v2, v0, v1
	v_lshl_add_u64 v[0:1], v[112:113], 0, v[128:129]
	global_atomic_add_f32 v[0:1], v2, off offset:704
	s_branch .LBB0_644
